# speedup vs baseline: 1.0135x; 1.0079x over previous
; __device__ __forceinline__ u32 pack2(float a, float b) { return (u32)f2bf(a) | ((u32)f2bf(b) << 16); }
; __device__ __forceinline__ void gemm_tile(const GemmArgs& ga, int wgid, int next_wgid, bool prefetched, u16* shm, unsigned char* ws, int wv_) {
;     ...
;     _Pragma("unroll") for (int ai = 0; ai < 2; ++ai)
;       _Pragma("unroll") for (int m = 0; m < 4; ++m)
;         _Pragma("unroll") for (int j = 0; j < 4; ++j) {
;           int row = rbase + ai * HALF + m * 16 + j;
;           float s = (epi == EPI_Z) ? rsqrtf(sc[ai][m][j] * (1.f / D_) + 1e-6f) : 1.f;
;           *(uint2*)(e_outb + (size_t)row * ldo + bcol + lc4) =
;               make_uint2(pack2(acc[ai][0][m][0][j] * s, acc[ai][0][m][1][j] * s), pack2(acc[ai][1][m][0][j] * s, acc[ai][1][m][1][j] * s));
;         }
.LBB0_1091:
	v_cmp_gt_f32_e32 vcc, s93, v172
	v_mul_f32_e32 v0, 0x4b800000, v172
	s_ashr_i32 s13, s12, 31
	v_cndmask_b32_e32 v0, v172, v0, vcc
	s_lshl_b64 s[6:7], s[12:13], 1
	v_rsq_f32_e32 v0, v0
	s_add_u32 s6, s90, s6
	s_addc_u32 s7, s91, s7
	v_lshlrev_b32_e32 v166, 1, v134
	v_lshl_add_u64 v[128:129], s[6:7], 0, v[166:167]
	v_mad_u64_u32 v[2:3], s[6:7], s2, v168, 0
	v_mul_f32_e32 v1, 0x45800000, v0
	v_mov_b32_e32 v8, v3
	v_cndmask_b32_e32 v0, v0, v1, vcc
	v_mad_u64_u32 v[8:9], s[6:7], s2, v169, v[8:9]
	v_cndmask_b32_e64 v0, 1.0, v0, s[4:5]
	v_mov_b32_e32 v3, v8
	v_mov_b32_e32 v8, v116
	v_mov_b32_e32 v9, v124
	v_pk_mul_f32 v[8:9], v[8:9], v[0:1] op_sel_hi:[1,0]
	v_mov_b32_e32 v10, v112
	v_mov_b32_e32 v11, v120
	v_pk_mul_f32 v[0:1], v[10:11], v[0:1] op_sel_hi:[1,0]
	v_and_b32_sdwa v10, v9, v177 dst_sel:DWORD dst_unused:UNUSED_PAD src0_sel:WORD_1 src1_sel:DWORD
	v_and_b32_sdwa v11, v8, v177 dst_sel:DWORD dst_unused:UNUSED_PAD src0_sel:WORD_1 src1_sel:DWORD
	v_add3_u32 v8, v8, v11, s48
	v_add3_u32 v9, v9, v10, s48
	v_and_b32_sdwa v10, v1, v177 dst_sel:DWORD dst_unused:UNUSED_PAD src0_sel:WORD_1 src1_sel:DWORD
	v_and_b32_sdwa v11, v0, v177 dst_sel:DWORD dst_unused:UNUSED_PAD src0_sel:WORD_1 src1_sel:DWORD
	v_add3_u32 v1, v1, v10, s48
	v_add3_u32 v0, v0, v11, s48
	v_and_b32_e32 v1, 0xffff0000, v1
	v_and_b32_e32 v0, 0xffff0000, v0
	v_lshl_add_u64 v[2:3], v[2:3], 1, v[128:129]
	v_or_b32_sdwa v1, v1, v9 dst_sel:DWORD dst_unused:UNUSED_PAD src0_sel:DWORD src1_sel:WORD_1
	v_or_b32_sdwa v0, v0, v8 dst_sel:DWORD dst_unused:UNUSED_PAD src0_sel:DWORD src1_sel:WORD_1
	global_store_dwordx2 v[2:3], v[0:1], off
	v_or_b32_e32 v1, 1, v168
	v_rsq_f32_e32 v0, v159
	v_mov_b32_e32 v8, v117
	v_mov_b32_e32 v9, v125
	v_mov_b32_e32 v10, v113
	v_cndmask_b32_e64 v0, 1.0, v0, s[4:5]
	v_mad_u64_u32 v[2:3], s[6:7], s2, v1, 0
	v_ashrrev_i32_e32 v1, 31, v168
	v_pk_mul_f32 v[8:9], v[8:9], v[0:1] op_sel_hi:[1,0]
	v_mov_b32_e32 v11, v121
	v_mul_lo_u32 v159, s2, v1
	v_pk_mul_f32 v[0:1], v[10:11], v[0:1] op_sel_hi:[1,0]
	v_and_b32_sdwa v10, v9, v177 dst_sel:DWORD dst_unused:UNUSED_PAD src0_sel:WORD_1 src1_sel:DWORD
	v_and_b32_sdwa v11, v8, v177 dst_sel:DWORD dst_unused:UNUSED_PAD src0_sel:WORD_1 src1_sel:DWORD
	v_add3_u32 v8, v8, v11, s48
	v_add3_u32 v9, v9, v10, s48
	v_and_b32_sdwa v10, v1, v177 dst_sel:DWORD dst_unused:UNUSED_PAD src0_sel:WORD_1 src1_sel:DWORD
	v_and_b32_sdwa v11, v0, v177 dst_sel:DWORD dst_unused:UNUSED_PAD src0_sel:WORD_1 src1_sel:DWORD
	v_add3_u32 v1, v1, v10, s48
	v_add3_u32 v0, v0, v11, s48
	v_add_u32_e32 v3, v3, v159
	v_and_b32_e32 v1, 0xffff0000, v1
	v_and_b32_e32 v0, 0xffff0000, v0
	v_lshl_add_u64 v[2:3], v[2:3], 1, v[128:129]
	v_or_b32_sdwa v1, v1, v9 dst_sel:DWORD dst_unused:UNUSED_PAD src0_sel:DWORD src1_sel:WORD_1
	v_or_b32_sdwa v0, v0, v8 dst_sel:DWORD dst_unused:UNUSED_PAD src0_sel:DWORD src1_sel:WORD_1
	global_store_dwordx2 v[2:3], v[0:1], off
	v_or_b32_e32 v1, 2, v168
	v_rsq_f32_e32 v0, v170
	v_mov_b32_e32 v8, v118
	v_mov_b32_e32 v9, v126
	v_mov_b32_e32 v10, v114
	v_cndmask_b32_e64 v0, 1.0, v0, s[4:5]
	v_pk_mul_f32 v[8:9], v[8:9], v[0:1] op_sel_hi:[1,0]
	v_mov_b32_e32 v11, v122
	v_mad_u64_u32 v[2:3], s[6:7], s2, v1, 0
	v_pk_mul_f32 v[0:1], v[10:11], v[0:1] op_sel_hi:[1,0]
	v_and_b32_sdwa v10, v9, v177 dst_sel:DWORD dst_unused:UNUSED_PAD src0_sel:WORD_1 src1_sel:DWORD
	v_and_b32_sdwa v11, v8, v177 dst_sel:DWORD dst_unused:UNUSED_PAD src0_sel:WORD_1 src1_sel:DWORD
	v_add3_u32 v8, v8, v11, s48
	v_add3_u32 v9, v9, v10, s48
	v_and_b32_sdwa v10, v1, v177 dst_sel:DWORD dst_unused:UNUSED_PAD src0_sel:WORD_1 src1_sel:DWORD
	v_and_b32_sdwa v11, v0, v177 dst_sel:DWORD dst_unused:UNUSED_PAD src0_sel:WORD_1 src1_sel:DWORD
	v_add3_u32 v1, v1, v10, s48
	v_add3_u32 v0, v0, v11, s48
	v_add_u32_e32 v3, v3, v159
	v_and_b32_e32 v1, 0xffff0000, v1
	v_and_b32_e32 v0, 0xffff0000, v0
	v_lshl_add_u64 v[2:3], v[2:3], 1, v[128:129]
	v_or_b32_sdwa v1, v1, v9 dst_sel:DWORD dst_unused:UNUSED_PAD src0_sel:DWORD src1_sel:WORD_1
	v_or_b32_sdwa v0, v0, v8 dst_sel:DWORD dst_unused:UNUSED_PAD src0_sel:DWORD src1_sel:WORD_1
	global_store_dwordx2 v[2:3], v[0:1], off
	v_or_b32_e32 v1, 3, v168
	v_rsq_f32_e32 v0, v165
	v_mov_b32_e32 v8, v119
	v_mov_b32_e32 v9, v127
	v_mov_b32_e32 v10, v115
	v_cndmask_b32_e64 v0, 1.0, v0, s[4:5]
	v_pk_mul_f32 v[8:9], v[8:9], v[0:1] op_sel_hi:[1,0]
	v_mov_b32_e32 v11, v123
	v_mad_u64_u32 v[2:3], s[6:7], s2, v1, 0
	v_pk_mul_f32 v[0:1], v[10:11], v[0:1] op_sel_hi:[1,0]
	v_and_b32_sdwa v10, v9, v177 dst_sel:DWORD dst_unused:UNUSED_PAD src0_sel:WORD_1 src1_sel:DWORD
	v_and_b32_sdwa v11, v8, v177 dst_sel:DWORD dst_unused:UNUSED_PAD src0_sel:WORD_1 src1_sel:DWORD
	v_add3_u32 v8, v8, v11, s48
	v_add3_u32 v9, v9, v10, s48
	v_and_b32_sdwa v10, v1, v177 dst_sel:DWORD dst_unused:UNUSED_PAD src0_sel:WORD_1 src1_sel:DWORD
	v_and_b32_sdwa v11, v0, v177 dst_sel:DWORD dst_unused:UNUSED_PAD src0_sel:WORD_1 src1_sel:DWORD
	v_add3_u32 v1, v1, v10, s48
	v_add3_u32 v0, v0, v11, s48
	v_add_u32_e32 v3, v3, v159
	v_and_b32_e32 v1, 0xffff0000, v1
	v_and_b32_e32 v0, 0xffff0000, v0
	v_lshl_add_u64 v[2:3], v[2:3], 1, v[128:129]
	v_or_b32_sdwa v1, v1, v9 dst_sel:DWORD dst_unused:UNUSED_PAD src0_sel:DWORD src1_sel:WORD_1
	v_or_b32_sdwa v0, v0, v8 dst_sel:DWORD dst_unused:UNUSED_PAD src0_sel:DWORD src1_sel:WORD_1
	global_store_dwordx2 v[2:3], v[0:1], off
	v_mov_b32_e32 v8, v100
	v_rsq_f32_e32 v0, v164
	v_mov_b32_e32 v9, v108
	v_mov_b32_e32 v10, v96
	v_mov_b32_e32 v11, v104
	v_cndmask_b32_e64 v0, 1.0, v0, s[4:5]
	v_pk_mul_f32 v[8:9], v[8:9], v[0:1] op_sel_hi:[1,0]
	v_pk_mul_f32 v[0:1], v[10:11], v[0:1] op_sel_hi:[1,0]
	v_and_b32_sdwa v10, v9, v177 dst_sel:DWORD dst_unused:UNUSED_PAD src0_sel:WORD_1 src1_sel:DWORD
; __device__ __forceinline__ u32 pack2(float a, float b) { return (u32)f2bf(a) | ((u32)f2bf(b) << 16); }
; __device__ __forceinline__ void gemm_tile(const GemmArgs& ga, int wgid, int next_wgid, bool prefetched, u16* shm, unsigned char* ws, int wv_) {
;     ...
;     _Pragma("unroll") for (int ai = 0; ai < 2; ++ai)
;       _Pragma("unroll") for (int m = 0; m < 4; ++m)
;         _Pragma("unroll") for (int j = 0; j < 4; ++j) {
;           int row = rbase + ai * HALF + m * 16 + j;
;           float s = (epi == EPI_Z) ? rsqrtf(sc[ai][m][j] * (1.f / D_) + 1e-6f) : 1.f;
;           *(uint2*)(e_outb + (size_t)row * ldo + bcol + lc4) =
;               make_uint2(pack2(acc[ai][0][m][0][j] * s, acc[ai][0][m][1][j] * s), pack2(acc[ai][1][m][0][j] * s, acc[ai][1][m][1][j] * s));
;         }
	v_and_b32_sdwa v11, v8, v177 dst_sel:DWORD dst_unused:UNUSED_PAD src0_sel:WORD_1 src1_sel:DWORD
	v_or_b32_e32 v16, 16, v168
	v_add3_u32 v8, v8, v11, s48
	v_add3_u32 v9, v9, v10, s48
	v_and_b32_sdwa v10, v1, v177 dst_sel:DWORD dst_unused:UNUSED_PAD src0_sel:WORD_1 src1_sel:DWORD
	v_and_b32_sdwa v11, v0, v177 dst_sel:DWORD dst_unused:UNUSED_PAD src0_sel:WORD_1 src1_sel:DWORD
	v_mad_u64_u32 v[2:3], s[6:7], s2, v16, 0
	v_add3_u32 v1, v1, v10, s48
	v_add3_u32 v0, v0, v11, s48
	v_add_u32_e32 v3, v3, v159
	v_and_b32_e32 v1, 0xffff0000, v1
	v_and_b32_e32 v0, 0xffff0000, v0
	v_lshl_add_u64 v[2:3], v[2:3], 1, v[128:129]
	v_or_b32_sdwa v1, v1, v9 dst_sel:DWORD dst_unused:UNUSED_PAD src0_sel:DWORD src1_sel:WORD_1
	v_or_b32_sdwa v0, v0, v8 dst_sel:DWORD dst_unused:UNUSED_PAD src0_sel:DWORD src1_sel:WORD_1
	global_store_dwordx2 v[2:3], v[0:1], off
	v_or_b32_e32 v1, 17, v168
	v_rsq_f32_e32 v0, v163
	v_mov_b32_e32 v8, v101
	v_mov_b32_e32 v9, v109
	v_mov_b32_e32 v10, v97
	v_cndmask_b32_e64 v0, 1.0, v0, s[4:5]
	v_pk_mul_f32 v[8:9], v[8:9], v[0:1] op_sel_hi:[1,0]
	v_mov_b32_e32 v11, v105
	v_mad_u64_u32 v[2:3], s[6:7], s2, v1, 0
	v_pk_mul_f32 v[0:1], v[10:11], v[0:1] op_sel_hi:[1,0]
	v_and_b32_sdwa v10, v9, v177 dst_sel:DWORD dst_unused:UNUSED_PAD src0_sel:WORD_1 src1_sel:DWORD
	v_and_b32_sdwa v11, v8, v177 dst_sel:DWORD dst_unused:UNUSED_PAD src0_sel:WORD_1 src1_sel:DWORD
	v_add3_u32 v8, v8, v11, s48
	v_add3_u32 v9, v9, v10, s48
	v_and_b32_sdwa v10, v1, v177 dst_sel:DWORD dst_unused:UNUSED_PAD src0_sel:WORD_1 src1_sel:DWORD
	v_and_b32_sdwa v11, v0, v177 dst_sel:DWORD dst_unused:UNUSED_PAD src0_sel:WORD_1 src1_sel:DWORD
	v_add3_u32 v1, v1, v10, s48
	v_add3_u32 v0, v0, v11, s48
	v_add_u32_e32 v3, v3, v159
	v_and_b32_e32 v1, 0xffff0000, v1
	v_and_b32_e32 v0, 0xffff0000, v0
	v_lshl_add_u64 v[2:3], v[2:3], 1, v[128:129]
	v_or_b32_sdwa v1, v1, v9 dst_sel:DWORD dst_unused:UNUSED_PAD src0_sel:DWORD src1_sel:WORD_1
	v_or_b32_sdwa v0, v0, v8 dst_sel:DWORD dst_unused:UNUSED_PAD src0_sel:DWORD src1_sel:WORD_1
	global_store_dwordx2 v[2:3], v[0:1], off
	v_or_b32_e32 v1, 18, v168
	v_rsq_f32_e32 v0, v162
	v_mov_b32_e32 v8, v102
	v_mov_b32_e32 v9, v110
	v_mov_b32_e32 v10, v98
	v_cndmask_b32_e64 v0, 1.0, v0, s[4:5]
	v_pk_mul_f32 v[8:9], v[8:9], v[0:1] op_sel_hi:[1,0]
	v_mov_b32_e32 v11, v106
	v_mad_u64_u32 v[2:3], s[6:7], s2, v1, 0
	v_pk_mul_f32 v[0:1], v[10:11], v[0:1] op_sel_hi:[1,0]
	v_and_b32_sdwa v10, v9, v177 dst_sel:DWORD dst_unused:UNUSED_PAD src0_sel:WORD_1 src1_sel:DWORD
	v_and_b32_sdwa v11, v8, v177 dst_sel:DWORD dst_unused:UNUSED_PAD src0_sel:WORD_1 src1_sel:DWORD
	v_add3_u32 v8, v8, v11, s48
	v_add3_u32 v9, v9, v10, s48
	v_and_b32_sdwa v10, v1, v177 dst_sel:DWORD dst_unused:UNUSED_PAD src0_sel:WORD_1 src1_sel:DWORD
	v_and_b32_sdwa v11, v0, v177 dst_sel:DWORD dst_unused:UNUSED_PAD src0_sel:WORD_1 src1_sel:DWORD
	v_add3_u32 v1, v1, v10, s48
	v_add3_u32 v0, v0, v11, s48
	v_add_u32_e32 v3, v3, v159
	v_and_b32_e32 v1, 0xffff0000, v1
	v_and_b32_e32 v0, 0xffff0000, v0
	v_lshl_add_u64 v[2:3], v[2:3], 1, v[128:129]
	v_or_b32_sdwa v1, v1, v9 dst_sel:DWORD dst_unused:UNUSED_PAD src0_sel:DWORD src1_sel:WORD_1
	v_or_b32_sdwa v0, v0, v8 dst_sel:DWORD dst_unused:UNUSED_PAD src0_sel:DWORD src1_sel:WORD_1
	global_store_dwordx2 v[2:3], v[0:1], off
	v_or_b32_e32 v1, 19, v168
	v_rsq_f32_e32 v0, v160
	v_mov_b32_e32 v8, v103
	v_mov_b32_e32 v9, v111
	v_mov_b32_e32 v10, v99
	v_cndmask_b32_e64 v0, 1.0, v0, s[4:5]
	v_pk_mul_f32 v[8:9], v[8:9], v[0:1] op_sel_hi:[1,0]
	v_mov_b32_e32 v11, v107
	v_mad_u64_u32 v[2:3], s[6:7], s2, v1, 0
	v_pk_mul_f32 v[0:1], v[10:11], v[0:1] op_sel_hi:[1,0]
	v_and_b32_sdwa v10, v9, v177 dst_sel:DWORD dst_unused:UNUSED_PAD src0_sel:WORD_1 src1_sel:DWORD
	v_and_b32_sdwa v11, v8, v177 dst_sel:DWORD dst_unused:UNUSED_PAD src0_sel:WORD_1 src1_sel:DWORD
	v_add3_u32 v8, v8, v11, s48
	v_add3_u32 v9, v9, v10, s48
	v_and_b32_sdwa v10, v1, v177 dst_sel:DWORD dst_unused:UNUSED_PAD src0_sel:WORD_1 src1_sel:DWORD
	v_and_b32_sdwa v11, v0, v177 dst_sel:DWORD dst_unused:UNUSED_PAD src0_sel:WORD_1 src1_sel:DWORD
	v_add3_u32 v1, v1, v10, s48
	v_add3_u32 v0, v0, v11, s48
	v_add_u32_e32 v3, v3, v159
	v_and_b32_e32 v1, 0xffff0000, v1
	v_and_b32_e32 v0, 0xffff0000, v0
	v_lshl_add_u64 v[2:3], v[2:3], 1, v[128:129]
	v_or_b32_sdwa v1, v1, v9 dst_sel:DWORD dst_unused:UNUSED_PAD src0_sel:DWORD src1_sel:WORD_1
	v_or_b32_sdwa v0, v0, v8 dst_sel:DWORD dst_unused:UNUSED_PAD src0_sel:DWORD src1_sel:WORD_1
	global_store_dwordx2 v[2:3], v[0:1], off
	v_mov_b32_e32 v8, v84
	v_rsq_f32_e32 v0, v158
	v_mov_b32_e32 v9, v92
	v_mov_b32_e32 v10, v80
	v_mov_b32_e32 v11, v88
	v_cndmask_b32_e64 v0, 1.0, v0, s[4:5]
	v_pk_mul_f32 v[8:9], v[8:9], v[0:1] op_sel_hi:[1,0]
	v_pk_mul_f32 v[0:1], v[10:11], v[0:1] op_sel_hi:[1,0]
	v_and_b32_sdwa v10, v9, v177 dst_sel:DWORD dst_unused:UNUSED_PAD src0_sel:WORD_1 src1_sel:DWORD
	v_and_b32_sdwa v11, v8, v177 dst_sel:DWORD dst_unused:UNUSED_PAD src0_sel:WORD_1 src1_sel:DWORD
	v_or_b32_e32 v171, 32, v168
	v_add3_u32 v8, v8, v11, s48
	v_add3_u32 v9, v9, v10, s48
	v_and_b32_sdwa v10, v1, v177 dst_sel:DWORD dst_unused:UNUSED_PAD src0_sel:WORD_1 src1_sel:DWORD
	v_and_b32_sdwa v11, v0, v177 dst_sel:DWORD dst_unused:UNUSED_PAD src0_sel:WORD_1 src1_sel:DWORD
	v_mad_u64_u32 v[2:3], s[6:7], s2, v171, 0
	v_add3_u32 v1, v1, v10, s48
	v_add3_u32 v0, v0, v11, s48
	v_add_u32_e32 v3, v3, v159
	v_and_b32_e32 v1, 0xffff0000, v1
	v_and_b32_e32 v0, 0xffff0000, v0
	v_lshl_add_u64 v[2:3], v[2:3], 1, v[128:129]
	v_or_b32_sdwa v1, v1, v9 dst_sel:DWORD dst_unused:UNUSED_PAD src0_sel:DWORD src1_sel:WORD_1
	v_or_b32_sdwa v0, v0, v8 dst_sel:DWORD dst_unused:UNUSED_PAD src0_sel:DWORD src1_sel:WORD_1
; __device__ __forceinline__ u32 pack2(float a, float b) { return (u32)f2bf(a) | ((u32)f2bf(b) << 16); }
; __device__ __forceinline__ void gemm_tile(const GemmArgs& ga, int wgid, int next_wgid, bool prefetched, u16* shm, unsigned char* ws, int wv_) {
;     ...
;     _Pragma("unroll") for (int ai = 0; ai < 2; ++ai)
;       _Pragma("unroll") for (int m = 0; m < 4; ++m)
;         _Pragma("unroll") for (int j = 0; j < 4; ++j) {
;           int row = rbase + ai * HALF + m * 16 + j;
;           float s = (epi == EPI_Z) ? rsqrtf(sc[ai][m][j] * (1.f / D_) + 1e-6f) : 1.f;
;           *(uint2*)(e_outb + (size_t)row * ldo + bcol + lc4) =
;               make_uint2(pack2(acc[ai][0][m][0][j] * s, acc[ai][0][m][1][j] * s), pack2(acc[ai][1][m][0][j] * s, acc[ai][1][m][1][j] * s));
;         }
	global_store_dwordx2 v[2:3], v[0:1], off
	v_or_b32_e32 v1, 33, v168
	v_rsq_f32_e32 v0, v157
	v_mov_b32_e32 v8, v85
	v_mov_b32_e32 v9, v93
	v_mov_b32_e32 v10, v81
	v_cndmask_b32_e64 v0, 1.0, v0, s[4:5]
	v_pk_mul_f32 v[8:9], v[8:9], v[0:1] op_sel_hi:[1,0]
	v_mov_b32_e32 v11, v89
	v_mad_u64_u32 v[2:3], s[6:7], s2, v1, 0
	v_pk_mul_f32 v[0:1], v[10:11], v[0:1] op_sel_hi:[1,0]
	v_and_b32_sdwa v10, v9, v177 dst_sel:DWORD dst_unused:UNUSED_PAD src0_sel:WORD_1 src1_sel:DWORD
	v_and_b32_sdwa v11, v8, v177 dst_sel:DWORD dst_unused:UNUSED_PAD src0_sel:WORD_1 src1_sel:DWORD
	v_add3_u32 v8, v8, v11, s48
	v_add3_u32 v9, v9, v10, s48
	v_and_b32_sdwa v10, v1, v177 dst_sel:DWORD dst_unused:UNUSED_PAD src0_sel:WORD_1 src1_sel:DWORD
	v_and_b32_sdwa v11, v0, v177 dst_sel:DWORD dst_unused:UNUSED_PAD src0_sel:WORD_1 src1_sel:DWORD
	v_add3_u32 v1, v1, v10, s48
	v_add3_u32 v0, v0, v11, s48
	v_add_u32_e32 v3, v3, v159
	v_and_b32_e32 v1, 0xffff0000, v1
	v_and_b32_e32 v0, 0xffff0000, v0
	v_lshl_add_u64 v[2:3], v[2:3], 1, v[128:129]
	v_or_b32_sdwa v1, v1, v9 dst_sel:DWORD dst_unused:UNUSED_PAD src0_sel:DWORD src1_sel:WORD_1
	v_or_b32_sdwa v0, v0, v8 dst_sel:DWORD dst_unused:UNUSED_PAD src0_sel:DWORD src1_sel:WORD_1
	global_store_dwordx2 v[2:3], v[0:1], off
	v_or_b32_e32 v1, 34, v168
	v_rsq_f32_e32 v0, v156
	v_mov_b32_e32 v8, v86
	v_mov_b32_e32 v9, v94
	v_mov_b32_e32 v10, v82
	v_cndmask_b32_e64 v0, 1.0, v0, s[4:5]
	v_pk_mul_f32 v[8:9], v[8:9], v[0:1] op_sel_hi:[1,0]
	v_mov_b32_e32 v11, v90
	v_mad_u64_u32 v[2:3], s[6:7], s2, v1, 0
	v_pk_mul_f32 v[0:1], v[10:11], v[0:1] op_sel_hi:[1,0]
	v_and_b32_sdwa v10, v9, v177 dst_sel:DWORD dst_unused:UNUSED_PAD src0_sel:WORD_1 src1_sel:DWORD
	v_and_b32_sdwa v11, v8, v177 dst_sel:DWORD dst_unused:UNUSED_PAD src0_sel:WORD_1 src1_sel:DWORD
	v_add3_u32 v8, v8, v11, s48
	v_add3_u32 v9, v9, v10, s48
	v_and_b32_sdwa v10, v1, v177 dst_sel:DWORD dst_unused:UNUSED_PAD src0_sel:WORD_1 src1_sel:DWORD
	v_and_b32_sdwa v11, v0, v177 dst_sel:DWORD dst_unused:UNUSED_PAD src0_sel:WORD_1 src1_sel:DWORD
	v_add3_u32 v1, v1, v10, s48
	v_add3_u32 v0, v0, v11, s48
	v_add_u32_e32 v3, v3, v159
	v_and_b32_e32 v1, 0xffff0000, v1
	v_and_b32_e32 v0, 0xffff0000, v0
	v_lshl_add_u64 v[2:3], v[2:3], 1, v[128:129]
	v_or_b32_sdwa v1, v1, v9 dst_sel:DWORD dst_unused:UNUSED_PAD src0_sel:DWORD src1_sel:WORD_1
	v_or_b32_sdwa v0, v0, v8 dst_sel:DWORD dst_unused:UNUSED_PAD src0_sel:DWORD src1_sel:WORD_1
	global_store_dwordx2 v[2:3], v[0:1], off
	v_or_b32_e32 v1, 35, v168
	v_rsq_f32_e32 v0, v155
	v_mov_b32_e32 v8, v87
	v_mov_b32_e32 v9, v95
	v_mov_b32_e32 v10, v83
	v_cndmask_b32_e64 v0, 1.0, v0, s[4:5]
	v_pk_mul_f32 v[8:9], v[8:9], v[0:1] op_sel_hi:[1,0]
	v_mov_b32_e32 v11, v91
	v_mad_u64_u32 v[2:3], s[6:7], s2, v1, 0
	v_pk_mul_f32 v[0:1], v[10:11], v[0:1] op_sel_hi:[1,0]
	v_and_b32_sdwa v10, v9, v177 dst_sel:DWORD dst_unused:UNUSED_PAD src0_sel:WORD_1 src1_sel:DWORD
	v_and_b32_sdwa v11, v8, v177 dst_sel:DWORD dst_unused:UNUSED_PAD src0_sel:WORD_1 src1_sel:DWORD
	v_add3_u32 v8, v8, v11, s48
	v_add3_u32 v9, v9, v10, s48
	v_and_b32_sdwa v10, v1, v177 dst_sel:DWORD dst_unused:UNUSED_PAD src0_sel:WORD_1 src1_sel:DWORD
	v_and_b32_sdwa v11, v0, v177 dst_sel:DWORD dst_unused:UNUSED_PAD src0_sel:WORD_1 src1_sel:DWORD
	v_add3_u32 v1, v1, v10, s48
	v_add3_u32 v0, v0, v11, s48
	v_add_u32_e32 v3, v3, v159
	v_and_b32_e32 v1, 0xffff0000, v1
	v_and_b32_e32 v0, 0xffff0000, v0
	v_lshl_add_u64 v[2:3], v[2:3], 1, v[128:129]
	v_or_b32_sdwa v1, v1, v9 dst_sel:DWORD dst_unused:UNUSED_PAD src0_sel:DWORD src1_sel:WORD_1
	v_or_b32_sdwa v0, v0, v8 dst_sel:DWORD dst_unused:UNUSED_PAD src0_sel:DWORD src1_sel:WORD_1
	global_store_dwordx2 v[2:3], v[0:1], off
	v_mov_b32_e32 v8, v68
	v_rsq_f32_e32 v0, v153
	v_mov_b32_e32 v9, v76
	v_mov_b32_e32 v10, v64
	v_mov_b32_e32 v11, v72
	v_cndmask_b32_e64 v0, 1.0, v0, s[4:5]
	v_pk_mul_f32 v[8:9], v[8:9], v[0:1] op_sel_hi:[1,0]
	v_pk_mul_f32 v[0:1], v[10:11], v[0:1] op_sel_hi:[1,0]
	v_and_b32_sdwa v10, v9, v177 dst_sel:DWORD dst_unused:UNUSED_PAD src0_sel:WORD_1 src1_sel:DWORD
	v_and_b32_sdwa v11, v8, v177 dst_sel:DWORD dst_unused:UNUSED_PAD src0_sel:WORD_1 src1_sel:DWORD
	v_or_b32_e32 v161, 48, v168
	v_add3_u32 v8, v8, v11, s48
	v_add3_u32 v9, v9, v10, s48
	v_and_b32_sdwa v10, v1, v177 dst_sel:DWORD dst_unused:UNUSED_PAD src0_sel:WORD_1 src1_sel:DWORD
	v_and_b32_sdwa v11, v0, v177 dst_sel:DWORD dst_unused:UNUSED_PAD src0_sel:WORD_1 src1_sel:DWORD
	v_mad_u64_u32 v[2:3], s[6:7], s2, v161, 0
	v_add3_u32 v1, v1, v10, s48
	v_add3_u32 v0, v0, v11, s48
	v_add_u32_e32 v3, v3, v159
	v_and_b32_e32 v1, 0xffff0000, v1
	v_and_b32_e32 v0, 0xffff0000, v0
	v_lshl_add_u64 v[2:3], v[2:3], 1, v[128:129]
	v_or_b32_sdwa v1, v1, v9 dst_sel:DWORD dst_unused:UNUSED_PAD src0_sel:DWORD src1_sel:WORD_1
	v_or_b32_sdwa v0, v0, v8 dst_sel:DWORD dst_unused:UNUSED_PAD src0_sel:DWORD src1_sel:WORD_1
	global_store_dwordx2 v[2:3], v[0:1], off
	v_or_b32_e32 v1, 49, v168
	v_rsq_f32_e32 v0, v152
	v_mov_b32_e32 v8, v69
	v_mov_b32_e32 v9, v77
	v_mov_b32_e32 v10, v65
	v_cndmask_b32_e64 v0, 1.0, v0, s[4:5]
	v_pk_mul_f32 v[8:9], v[8:9], v[0:1] op_sel_hi:[1,0]
	v_mov_b32_e32 v11, v73
	v_mad_u64_u32 v[2:3], s[6:7], s2, v1, 0
	v_pk_mul_f32 v[0:1], v[10:11], v[0:1] op_sel_hi:[1,0]
	v_and_b32_sdwa v10, v9, v177 dst_sel:DWORD dst_unused:UNUSED_PAD src0_sel:WORD_1 src1_sel:DWORD
	v_and_b32_sdwa v11, v8, v177 dst_sel:DWORD dst_unused:UNUSED_PAD src0_sel:WORD_1 src1_sel:DWORD
	v_add3_u32 v8, v8, v11, s48
	v_add3_u32 v9, v9, v10, s48
	v_and_b32_sdwa v10, v1, v177 dst_sel:DWORD dst_unused:UNUSED_PAD src0_sel:WORD_1 src1_sel:DWORD
	v_and_b32_sdwa v11, v0, v177 dst_sel:DWORD dst_unused:UNUSED_PAD src0_sel:WORD_1 src1_sel:DWORD
; __device__ __forceinline__ u32 pack2(float a, float b) { return (u32)f2bf(a) | ((u32)f2bf(b) << 16); }
; __device__ __forceinline__ void gemm_tile(const GemmArgs& ga, int wgid, int next_wgid, bool prefetched, u16* shm, unsigned char* ws, int wv_) {
;     ...
;     _Pragma("unroll") for (int ai = 0; ai < 2; ++ai)
;       _Pragma("unroll") for (int m = 0; m < 4; ++m)
;         _Pragma("unroll") for (int j = 0; j < 4; ++j) {
;           int row = rbase + ai * HALF + m * 16 + j;
;           float s = (epi == EPI_Z) ? rsqrtf(sc[ai][m][j] * (1.f / D_) + 1e-6f) : 1.f;
;           *(uint2*)(e_outb + (size_t)row * ldo + bcol + lc4) =
;               make_uint2(pack2(acc[ai][0][m][0][j] * s, acc[ai][0][m][1][j] * s), pack2(acc[ai][1][m][0][j] * s, acc[ai][1][m][1][j] * s));
;         }
	v_add3_u32 v1, v1, v10, s48
	v_add3_u32 v0, v0, v11, s48
	v_add_u32_e32 v3, v3, v159
	v_and_b32_e32 v1, 0xffff0000, v1
	v_and_b32_e32 v0, 0xffff0000, v0
	v_lshl_add_u64 v[2:3], v[2:3], 1, v[128:129]
	v_or_b32_sdwa v1, v1, v9 dst_sel:DWORD dst_unused:UNUSED_PAD src0_sel:DWORD src1_sel:WORD_1
	v_or_b32_sdwa v0, v0, v8 dst_sel:DWORD dst_unused:UNUSED_PAD src0_sel:DWORD src1_sel:WORD_1
	global_store_dwordx2 v[2:3], v[0:1], off
	v_or_b32_e32 v1, 50, v168
	v_rsq_f32_e32 v0, v151
	v_mov_b32_e32 v8, v70
	v_mov_b32_e32 v9, v78
	v_mov_b32_e32 v10, v66
	v_cndmask_b32_e64 v0, 1.0, v0, s[4:5]
	v_pk_mul_f32 v[8:9], v[8:9], v[0:1] op_sel_hi:[1,0]
	v_mov_b32_e32 v11, v74
	v_mad_u64_u32 v[2:3], s[6:7], s2, v1, 0
	v_pk_mul_f32 v[0:1], v[10:11], v[0:1] op_sel_hi:[1,0]
	v_and_b32_sdwa v10, v9, v177 dst_sel:DWORD dst_unused:UNUSED_PAD src0_sel:WORD_1 src1_sel:DWORD
	v_and_b32_sdwa v11, v8, v177 dst_sel:DWORD dst_unused:UNUSED_PAD src0_sel:WORD_1 src1_sel:DWORD
	v_add3_u32 v8, v8, v11, s48
	v_add3_u32 v9, v9, v10, s48
	v_and_b32_sdwa v10, v1, v177 dst_sel:DWORD dst_unused:UNUSED_PAD src0_sel:WORD_1 src1_sel:DWORD
	v_and_b32_sdwa v11, v0, v177 dst_sel:DWORD dst_unused:UNUSED_PAD src0_sel:WORD_1 src1_sel:DWORD
	v_add3_u32 v1, v1, v10, s48
	v_add3_u32 v0, v0, v11, s48
	v_add_u32_e32 v3, v3, v159
	v_and_b32_e32 v1, 0xffff0000, v1
	v_and_b32_e32 v0, 0xffff0000, v0
	v_lshl_add_u64 v[2:3], v[2:3], 1, v[128:129]
	v_or_b32_sdwa v1, v1, v9 dst_sel:DWORD dst_unused:UNUSED_PAD src0_sel:DWORD src1_sel:WORD_1
	v_or_b32_sdwa v0, v0, v8 dst_sel:DWORD dst_unused:UNUSED_PAD src0_sel:DWORD src1_sel:WORD_1
	global_store_dwordx2 v[2:3], v[0:1], off
	v_or_b32_e32 v1, 51, v168
	v_rsq_f32_e32 v0, v150
	v_mov_b32_e32 v8, v71
	v_mov_b32_e32 v9, v79
	v_mov_b32_e32 v10, v67
	v_cndmask_b32_e64 v0, 1.0, v0, s[4:5]
	v_pk_mul_f32 v[8:9], v[8:9], v[0:1] op_sel_hi:[1,0]
	v_mov_b32_e32 v11, v75
	v_mad_u64_u32 v[2:3], s[6:7], s2, v1, 0
	v_pk_mul_f32 v[0:1], v[10:11], v[0:1] op_sel_hi:[1,0]
	v_and_b32_sdwa v10, v9, v177 dst_sel:DWORD dst_unused:UNUSED_PAD src0_sel:WORD_1 src1_sel:DWORD
	v_and_b32_sdwa v11, v8, v177 dst_sel:DWORD dst_unused:UNUSED_PAD src0_sel:WORD_1 src1_sel:DWORD
	v_add3_u32 v8, v8, v11, s48
	v_add3_u32 v9, v9, v10, s48
	v_and_b32_sdwa v10, v1, v177 dst_sel:DWORD dst_unused:UNUSED_PAD src0_sel:WORD_1 src1_sel:DWORD
	v_and_b32_sdwa v11, v0, v177 dst_sel:DWORD dst_unused:UNUSED_PAD src0_sel:WORD_1 src1_sel:DWORD
	v_add3_u32 v1, v1, v10, s48
	v_add3_u32 v0, v0, v11, s48
	v_add_u32_e32 v3, v3, v159
	v_and_b32_e32 v1, 0xffff0000, v1
	v_and_b32_e32 v0, 0xffff0000, v0
	v_lshl_add_u64 v[2:3], v[2:3], 1, v[128:129]
	v_or_b32_sdwa v1, v1, v9 dst_sel:DWORD dst_unused:UNUSED_PAD src0_sel:DWORD src1_sel:WORD_1
	v_or_b32_sdwa v0, v0, v8 dst_sel:DWORD dst_unused:UNUSED_PAD src0_sel:DWORD src1_sel:WORD_1
	global_store_dwordx2 v[2:3], v[0:1], off
	v_add_u32_e32 v154, 0x80, v168
	v_rsq_f32_e32 v0, v149
	v_mad_u64_u32 v[2:3], s[6:7], s2, v154, 0
	v_mov_b32_e32 v8, v3
	v_ashrrev_i32_e32 v1, 31, v154
	v_mad_u64_u32 v[8:9], s[6:7], s2, v1, v[8:9]
	v_cndmask_b32_e64 v0, 1.0, v0, s[4:5]
	v_mov_b32_e32 v3, v8
	v_mov_b32_e32 v8, v52
	v_mov_b32_e32 v9, v60
	v_pk_mul_f32 v[8:9], v[8:9], v[0:1] op_sel_hi:[1,0]
	v_mov_b32_e32 v10, v48
	v_mov_b32_e32 v11, v56
	v_pk_mul_f32 v[0:1], v[10:11], v[0:1] op_sel_hi:[1,0]
	v_and_b32_sdwa v10, v9, v177 dst_sel:DWORD dst_unused:UNUSED_PAD src0_sel:WORD_1 src1_sel:DWORD
	v_and_b32_sdwa v11, v8, v177 dst_sel:DWORD dst_unused:UNUSED_PAD src0_sel:WORD_1 src1_sel:DWORD
	v_add3_u32 v8, v8, v11, s48
	v_add3_u32 v9, v9, v10, s48
	v_and_b32_sdwa v10, v1, v177 dst_sel:DWORD dst_unused:UNUSED_PAD src0_sel:WORD_1 src1_sel:DWORD
	v_and_b32_sdwa v11, v0, v177 dst_sel:DWORD dst_unused:UNUSED_PAD src0_sel:WORD_1 src1_sel:DWORD
	v_add3_u32 v1, v1, v10, s48
	v_add3_u32 v0, v0, v11, s48
	v_and_b32_e32 v1, 0xffff0000, v1
	v_and_b32_e32 v0, 0xffff0000, v0
	v_lshl_add_u64 v[2:3], v[2:3], 1, v[128:129]
	v_or_b32_sdwa v1, v1, v9 dst_sel:DWORD dst_unused:UNUSED_PAD src0_sel:DWORD src1_sel:WORD_1
	v_or_b32_sdwa v0, v0, v8 dst_sel:DWORD dst_unused:UNUSED_PAD src0_sel:DWORD src1_sel:WORD_1
	global_store_dwordx2 v[2:3], v[0:1], off
	v_add_u32_e32 v1, 0x81, v168
	v_rsq_f32_e32 v0, v147
	v_ashrrev_i32_e32 v9, 31, v1
	v_mov_b32_e32 v10, v49
	v_mov_b32_e32 v11, v57
	v_mad_u64_u32 v[2:3], s[6:7], s2, v1, 0
	v_mov_b32_e32 v8, v3
	v_mad_u64_u32 v[8:9], s[6:7], s2, v9, v[8:9]
	v_cndmask_b32_e64 v0, 1.0, v0, s[4:5]
	v_mov_b32_e32 v3, v8
	v_mov_b32_e32 v8, v53
	v_mov_b32_e32 v9, v61
	v_pk_mul_f32 v[8:9], v[8:9], v[0:1] op_sel_hi:[1,0]
	v_pk_mul_f32 v[0:1], v[10:11], v[0:1] op_sel_hi:[1,0]
	v_and_b32_sdwa v10, v9, v177 dst_sel:DWORD dst_unused:UNUSED_PAD src0_sel:WORD_1 src1_sel:DWORD
	v_and_b32_sdwa v11, v8, v177 dst_sel:DWORD dst_unused:UNUSED_PAD src0_sel:WORD_1 src1_sel:DWORD
	v_add3_u32 v8, v8, v11, s48
	v_add3_u32 v9, v9, v10, s48
	v_and_b32_sdwa v10, v1, v177 dst_sel:DWORD dst_unused:UNUSED_PAD src0_sel:WORD_1 src1_sel:DWORD
	v_and_b32_sdwa v11, v0, v177 dst_sel:DWORD dst_unused:UNUSED_PAD src0_sel:WORD_1 src1_sel:DWORD
	v_add3_u32 v1, v1, v10, s48
	v_add3_u32 v0, v0, v11, s48
	v_and_b32_e32 v1, 0xffff0000, v1
	v_and_b32_e32 v0, 0xffff0000, v0
	v_lshl_add_u64 v[2:3], v[2:3], 1, v[128:129]
	v_or_b32_sdwa v1, v1, v9 dst_sel:DWORD dst_unused:UNUSED_PAD src0_sel:DWORD src1_sel:WORD_1
	v_or_b32_sdwa v0, v0, v8 dst_sel:DWORD dst_unused:UNUSED_PAD src0_sel:DWORD src1_sel:WORD_1
	global_store_dwordx2 v[2:3], v[0:1], off
	v_add_u32_e32 v1, 0x82, v168
	v_rsq_f32_e32 v0, v146
	v_ashrrev_i32_e32 v9, 31, v1
	v_mov_b32_e32 v10, v50
	v_mov_b32_e32 v11, v58
	v_mad_u64_u32 v[2:3], s[6:7], s2, v1, 0
	v_mov_b32_e32 v8, v3
; __device__ __forceinline__ u32 pack2(float a, float b) { return (u32)f2bf(a) | ((u32)f2bf(b) << 16); }
; __device__ __forceinline__ void gemm_tile(const GemmArgs& ga, int wgid, int next_wgid, bool prefetched, u16* shm, unsigned char* ws, int wv_) {
;     ...
;     _Pragma("unroll") for (int ai = 0; ai < 2; ++ai)
;       _Pragma("unroll") for (int m = 0; m < 4; ++m)
;         _Pragma("unroll") for (int j = 0; j < 4; ++j) {
;           int row = rbase + ai * HALF + m * 16 + j;
;           float s = (epi == EPI_Z) ? rsqrtf(sc[ai][m][j] * (1.f / D_) + 1e-6f) : 1.f;
;           *(uint2*)(e_outb + (size_t)row * ldo + bcol + lc4) =
;               make_uint2(pack2(acc[ai][0][m][0][j] * s, acc[ai][0][m][1][j] * s), pack2(acc[ai][1][m][0][j] * s, acc[ai][1][m][1][j] * s));
;         }
	v_mad_u64_u32 v[8:9], s[6:7], s2, v9, v[8:9]
	v_cndmask_b32_e64 v0, 1.0, v0, s[4:5]
	v_mov_b32_e32 v3, v8
	v_mov_b32_e32 v8, v54
	v_mov_b32_e32 v9, v62
	v_pk_mul_f32 v[8:9], v[8:9], v[0:1] op_sel_hi:[1,0]
	v_pk_mul_f32 v[0:1], v[10:11], v[0:1] op_sel_hi:[1,0]
	v_and_b32_sdwa v10, v9, v177 dst_sel:DWORD dst_unused:UNUSED_PAD src0_sel:WORD_1 src1_sel:DWORD
	v_and_b32_sdwa v11, v8, v177 dst_sel:DWORD dst_unused:UNUSED_PAD src0_sel:WORD_1 src1_sel:DWORD
	v_add3_u32 v8, v8, v11, s48
	v_add3_u32 v9, v9, v10, s48
	v_and_b32_sdwa v10, v1, v177 dst_sel:DWORD dst_unused:UNUSED_PAD src0_sel:WORD_1 src1_sel:DWORD
	v_and_b32_sdwa v11, v0, v177 dst_sel:DWORD dst_unused:UNUSED_PAD src0_sel:WORD_1 src1_sel:DWORD
	v_add3_u32 v1, v1, v10, s48
	v_add3_u32 v0, v0, v11, s48
	v_and_b32_e32 v1, 0xffff0000, v1
	v_and_b32_e32 v0, 0xffff0000, v0
	v_lshl_add_u64 v[2:3], v[2:3], 1, v[128:129]
	v_or_b32_sdwa v1, v1, v9 dst_sel:DWORD dst_unused:UNUSED_PAD src0_sel:DWORD src1_sel:WORD_1
	v_or_b32_sdwa v0, v0, v8 dst_sel:DWORD dst_unused:UNUSED_PAD src0_sel:DWORD src1_sel:WORD_1
	global_store_dwordx2 v[2:3], v[0:1], off
	v_add_u32_e32 v1, 0x83, v168
	v_rsq_f32_e32 v0, v145
	v_ashrrev_i32_e32 v9, 31, v1
	v_mov_b32_e32 v10, v51
	v_mov_b32_e32 v11, v59
	v_mad_u64_u32 v[2:3], s[6:7], s2, v1, 0
	v_mov_b32_e32 v8, v3
	v_mad_u64_u32 v[8:9], s[6:7], s2, v9, v[8:9]
	v_cndmask_b32_e64 v0, 1.0, v0, s[4:5]
	v_mov_b32_e32 v3, v8
	v_mov_b32_e32 v8, v55
	v_mov_b32_e32 v9, v63
	v_pk_mul_f32 v[8:9], v[8:9], v[0:1] op_sel_hi:[1,0]
	v_pk_mul_f32 v[0:1], v[10:11], v[0:1] op_sel_hi:[1,0]
	v_and_b32_sdwa v10, v9, v177 dst_sel:DWORD dst_unused:UNUSED_PAD src0_sel:WORD_1 src1_sel:DWORD
	v_and_b32_sdwa v11, v8, v177 dst_sel:DWORD dst_unused:UNUSED_PAD src0_sel:WORD_1 src1_sel:DWORD
	v_add3_u32 v8, v8, v11, s48
	v_add3_u32 v9, v9, v10, s48
	v_and_b32_sdwa v10, v1, v177 dst_sel:DWORD dst_unused:UNUSED_PAD src0_sel:WORD_1 src1_sel:DWORD
	v_and_b32_sdwa v11, v0, v177 dst_sel:DWORD dst_unused:UNUSED_PAD src0_sel:WORD_1 src1_sel:DWORD
	v_add3_u32 v1, v1, v10, s48
	v_add3_u32 v0, v0, v11, s48
	v_and_b32_e32 v1, 0xffff0000, v1
	v_and_b32_e32 v0, 0xffff0000, v0
	v_lshl_add_u64 v[2:3], v[2:3], 1, v[128:129]
	v_or_b32_sdwa v1, v1, v9 dst_sel:DWORD dst_unused:UNUSED_PAD src0_sel:DWORD src1_sel:WORD_1
	v_or_b32_sdwa v0, v0, v8 dst_sel:DWORD dst_unused:UNUSED_PAD src0_sel:DWORD src1_sel:WORD_1
	global_store_dwordx2 v[2:3], v[0:1], off
	v_add_u32_e32 v148, 0x90, v168
	v_rsq_f32_e32 v0, v144
	v_mad_u64_u32 v[2:3], s[6:7], s2, v148, 0
	v_mov_b32_e32 v8, v3
	v_ashrrev_i32_e32 v1, 31, v148
	v_mad_u64_u32 v[8:9], s[6:7], s2, v1, v[8:9]
	v_cndmask_b32_e64 v0, 1.0, v0, s[4:5]
	v_mov_b32_e32 v3, v8
	v_mov_b32_e32 v8, v36
	v_mov_b32_e32 v9, v44
	v_pk_mul_f32 v[8:9], v[8:9], v[0:1] op_sel_hi:[1,0]
	v_mov_b32_e32 v10, v32
	v_mov_b32_e32 v11, v40
	v_pk_mul_f32 v[0:1], v[10:11], v[0:1] op_sel_hi:[1,0]
	v_and_b32_sdwa v10, v9, v177 dst_sel:DWORD dst_unused:UNUSED_PAD src0_sel:WORD_1 src1_sel:DWORD
	v_and_b32_sdwa v11, v8, v177 dst_sel:DWORD dst_unused:UNUSED_PAD src0_sel:WORD_1 src1_sel:DWORD
	v_add3_u32 v8, v8, v11, s48
	v_add3_u32 v9, v9, v10, s48
	v_and_b32_sdwa v10, v1, v177 dst_sel:DWORD dst_unused:UNUSED_PAD src0_sel:WORD_1 src1_sel:DWORD
	v_and_b32_sdwa v11, v0, v177 dst_sel:DWORD dst_unused:UNUSED_PAD src0_sel:WORD_1 src1_sel:DWORD
	v_add3_u32 v1, v1, v10, s48
	v_add3_u32 v0, v0, v11, s48
	v_and_b32_e32 v1, 0xffff0000, v1
	v_and_b32_e32 v0, 0xffff0000, v0
	v_lshl_add_u64 v[2:3], v[2:3], 1, v[128:129]
	v_or_b32_sdwa v1, v1, v9 dst_sel:DWORD dst_unused:UNUSED_PAD src0_sel:DWORD src1_sel:WORD_1
	v_or_b32_sdwa v0, v0, v8 dst_sel:DWORD dst_unused:UNUSED_PAD src0_sel:DWORD src1_sel:WORD_1
	global_store_dwordx2 v[2:3], v[0:1], off
	v_add_u32_e32 v1, 0x91, v168
	v_rsq_f32_e32 v0, v143
	v_ashrrev_i32_e32 v9, 31, v1
	v_mov_b32_e32 v10, v33
	v_mov_b32_e32 v11, v41
	v_mad_u64_u32 v[2:3], s[6:7], s2, v1, 0
	v_mov_b32_e32 v8, v3
	v_mad_u64_u32 v[8:9], s[6:7], s2, v9, v[8:9]
	v_cndmask_b32_e64 v0, 1.0, v0, s[4:5]
	v_mov_b32_e32 v3, v8
	v_mov_b32_e32 v8, v37
	v_mov_b32_e32 v9, v45
	v_pk_mul_f32 v[8:9], v[8:9], v[0:1] op_sel_hi:[1,0]
	v_pk_mul_f32 v[0:1], v[10:11], v[0:1] op_sel_hi:[1,0]
	v_and_b32_sdwa v10, v9, v177 dst_sel:DWORD dst_unused:UNUSED_PAD src0_sel:WORD_1 src1_sel:DWORD
	v_and_b32_sdwa v11, v8, v177 dst_sel:DWORD dst_unused:UNUSED_PAD src0_sel:WORD_1 src1_sel:DWORD
	v_add3_u32 v8, v8, v11, s48
	v_add3_u32 v9, v9, v10, s48
	v_and_b32_sdwa v10, v1, v177 dst_sel:DWORD dst_unused:UNUSED_PAD src0_sel:WORD_1 src1_sel:DWORD
	v_and_b32_sdwa v11, v0, v177 dst_sel:DWORD dst_unused:UNUSED_PAD src0_sel:WORD_1 src1_sel:DWORD
	v_add3_u32 v1, v1, v10, s48
	v_add3_u32 v0, v0, v11, s48
	v_and_b32_e32 v1, 0xffff0000, v1
	v_and_b32_e32 v0, 0xffff0000, v0
	v_lshl_add_u64 v[2:3], v[2:3], 1, v[128:129]
	v_or_b32_sdwa v1, v1, v9 dst_sel:DWORD dst_unused:UNUSED_PAD src0_sel:DWORD src1_sel:WORD_1
	v_or_b32_sdwa v0, v0, v8 dst_sel:DWORD dst_unused:UNUSED_PAD src0_sel:DWORD src1_sel:WORD_1
	global_store_dwordx2 v[2:3], v[0:1], off
	v_add_u32_e32 v1, 0x92, v168
	v_rsq_f32_e32 v0, v141
	v_ashrrev_i32_e32 v9, 31, v1
	v_mov_b32_e32 v10, v34
	v_mov_b32_e32 v11, v42
	v_mad_u64_u32 v[2:3], s[6:7], s2, v1, 0
	v_mov_b32_e32 v8, v3
	v_mad_u64_u32 v[8:9], s[6:7], s2, v9, v[8:9]
	v_cndmask_b32_e64 v0, 1.0, v0, s[4:5]
	v_mov_b32_e32 v3, v8
	v_mov_b32_e32 v8, v38
	v_mov_b32_e32 v9, v46
	v_pk_mul_f32 v[8:9], v[8:9], v[0:1] op_sel_hi:[1,0]
	v_pk_mul_f32 v[0:1], v[10:11], v[0:1] op_sel_hi:[1,0]
	v_and_b32_sdwa v10, v9, v177 dst_sel:DWORD dst_unused:UNUSED_PAD src0_sel:WORD_1 src1_sel:DWORD
	v_and_b32_sdwa v11, v8, v177 dst_sel:DWORD dst_unused:UNUSED_PAD src0_sel:WORD_1 src1_sel:DWORD
; __device__ __forceinline__ u32 pack2(float a, float b) { return (u32)f2bf(a) | ((u32)f2bf(b) << 16); }
; __device__ __forceinline__ void gemm_tile(const GemmArgs& ga, int wgid, int next_wgid, bool prefetched, u16* shm, unsigned char* ws, int wv_) {
;     ...
;     _Pragma("unroll") for (int ai = 0; ai < 2; ++ai)
;       _Pragma("unroll") for (int m = 0; m < 4; ++m)
;         _Pragma("unroll") for (int j = 0; j < 4; ++j) {
;           int row = rbase + ai * HALF + m * 16 + j;
;           float s = (epi == EPI_Z) ? rsqrtf(sc[ai][m][j] * (1.f / D_) + 1e-6f) : 1.f;
;           *(uint2*)(e_outb + (size_t)row * ldo + bcol + lc4) =
;               make_uint2(pack2(acc[ai][0][m][0][j] * s, acc[ai][0][m][1][j] * s), pack2(acc[ai][1][m][0][j] * s, acc[ai][1][m][1][j] * s));
;         }
	v_add3_u32 v8, v8, v11, s48
	v_add3_u32 v9, v9, v10, s48
	v_and_b32_sdwa v10, v1, v177 dst_sel:DWORD dst_unused:UNUSED_PAD src0_sel:WORD_1 src1_sel:DWORD
	v_and_b32_sdwa v11, v0, v177 dst_sel:DWORD dst_unused:UNUSED_PAD src0_sel:WORD_1 src1_sel:DWORD
	v_add3_u32 v1, v1, v10, s48
	v_add3_u32 v0, v0, v11, s48
	v_and_b32_e32 v1, 0xffff0000, v1
	v_and_b32_e32 v0, 0xffff0000, v0
	v_lshl_add_u64 v[2:3], v[2:3], 1, v[128:129]
	v_or_b32_sdwa v1, v1, v9 dst_sel:DWORD dst_unused:UNUSED_PAD src0_sel:DWORD src1_sel:WORD_1
	v_or_b32_sdwa v0, v0, v8 dst_sel:DWORD dst_unused:UNUSED_PAD src0_sel:DWORD src1_sel:WORD_1
	global_store_dwordx2 v[2:3], v[0:1], off
	v_add_u32_e32 v1, 0x93, v168
	v_rsq_f32_e32 v0, v140
	v_ashrrev_i32_e32 v9, 31, v1
	v_mov_b32_e32 v10, v35
	v_mov_b32_e32 v11, v43
	v_mad_u64_u32 v[2:3], s[6:7], s2, v1, 0
	v_mov_b32_e32 v8, v3
	v_mad_u64_u32 v[8:9], s[6:7], s2, v9, v[8:9]
	v_cndmask_b32_e64 v0, 1.0, v0, s[4:5]
	v_mov_b32_e32 v3, v8
	v_mov_b32_e32 v8, v39
	v_mov_b32_e32 v9, v47
	v_pk_mul_f32 v[8:9], v[8:9], v[0:1] op_sel_hi:[1,0]
	v_pk_mul_f32 v[0:1], v[10:11], v[0:1] op_sel_hi:[1,0]
	v_and_b32_sdwa v10, v9, v177 dst_sel:DWORD dst_unused:UNUSED_PAD src0_sel:WORD_1 src1_sel:DWORD
	v_and_b32_sdwa v11, v8, v177 dst_sel:DWORD dst_unused:UNUSED_PAD src0_sel:WORD_1 src1_sel:DWORD
	v_add3_u32 v8, v8, v11, s48
	v_add3_u32 v9, v9, v10, s48
	v_and_b32_sdwa v10, v1, v177 dst_sel:DWORD dst_unused:UNUSED_PAD src0_sel:WORD_1 src1_sel:DWORD
	v_and_b32_sdwa v11, v0, v177 dst_sel:DWORD dst_unused:UNUSED_PAD src0_sel:WORD_1 src1_sel:DWORD
	v_add3_u32 v1, v1, v10, s48
	v_add3_u32 v0, v0, v11, s48
	v_and_b32_e32 v1, 0xffff0000, v1
	v_and_b32_e32 v0, 0xffff0000, v0
	v_lshl_add_u64 v[2:3], v[2:3], 1, v[128:129]
	v_or_b32_sdwa v1, v1, v9 dst_sel:DWORD dst_unused:UNUSED_PAD src0_sel:DWORD src1_sel:WORD_1
	v_or_b32_sdwa v0, v0, v8 dst_sel:DWORD dst_unused:UNUSED_PAD src0_sel:DWORD src1_sel:WORD_1
	global_store_dwordx2 v[2:3], v[0:1], off
	v_add_u32_e32 v142, 0xa0, v168
	v_rsq_f32_e32 v0, v139
	v_mad_u64_u32 v[2:3], s[6:7], s2, v142, 0
	v_mov_b32_e32 v8, v3
	v_ashrrev_i32_e32 v1, 31, v142
	v_mad_u64_u32 v[8:9], s[6:7], s2, v1, v[8:9]
	v_cndmask_b32_e64 v0, 1.0, v0, s[4:5]
	v_mov_b32_e32 v3, v8
	v_mov_b32_e32 v8, v20
	v_mov_b32_e32 v9, v244
	v_pk_mul_f32 v[8:9], v[8:9], v[0:1] op_sel_hi:[1,0]
	v_mov_b32_e32 v10, v240
	v_mov_b32_e32 v11, v24
	v_pk_mul_f32 v[0:1], v[10:11], v[0:1] op_sel_hi:[1,0]
	v_and_b32_sdwa v10, v9, v177 dst_sel:DWORD dst_unused:UNUSED_PAD src0_sel:WORD_1 src1_sel:DWORD
	v_and_b32_sdwa v11, v8, v177 dst_sel:DWORD dst_unused:UNUSED_PAD src0_sel:WORD_1 src1_sel:DWORD
	v_add3_u32 v8, v8, v11, s48
	v_add3_u32 v9, v9, v10, s48
	v_and_b32_sdwa v10, v1, v177 dst_sel:DWORD dst_unused:UNUSED_PAD src0_sel:WORD_1 src1_sel:DWORD
	v_and_b32_sdwa v11, v0, v177 dst_sel:DWORD dst_unused:UNUSED_PAD src0_sel:WORD_1 src1_sel:DWORD
	v_add3_u32 v1, v1, v10, s48
	v_add3_u32 v0, v0, v11, s48
	v_and_b32_e32 v1, 0xffff0000, v1
	v_and_b32_e32 v0, 0xffff0000, v0
	v_lshl_add_u64 v[2:3], v[2:3], 1, v[128:129]
	v_or_b32_sdwa v1, v1, v9 dst_sel:DWORD dst_unused:UNUSED_PAD src0_sel:DWORD src1_sel:WORD_1
	v_or_b32_sdwa v0, v0, v8 dst_sel:DWORD dst_unused:UNUSED_PAD src0_sel:DWORD src1_sel:WORD_1
	global_store_dwordx2 v[2:3], v[0:1], off
	v_add_u32_e32 v1, 0xa1, v168
	v_rsq_f32_e32 v0, v138
	v_ashrrev_i32_e32 v9, 31, v1
	v_mov_b32_e32 v10, v241
	v_mov_b32_e32 v11, v25
	v_mad_u64_u32 v[2:3], s[6:7], s2, v1, 0
	v_mov_b32_e32 v8, v3
	v_mad_u64_u32 v[8:9], s[6:7], s2, v9, v[8:9]
	v_cndmask_b32_e64 v0, 1.0, v0, s[4:5]
	v_mov_b32_e32 v3, v8
	v_mov_b32_e32 v8, v21
	v_mov_b32_e32 v9, v245
	v_pk_mul_f32 v[8:9], v[8:9], v[0:1] op_sel_hi:[1,0]
	v_pk_mul_f32 v[0:1], v[10:11], v[0:1] op_sel_hi:[1,0]
	v_and_b32_sdwa v10, v9, v177 dst_sel:DWORD dst_unused:UNUSED_PAD src0_sel:WORD_1 src1_sel:DWORD
	v_and_b32_sdwa v11, v8, v177 dst_sel:DWORD dst_unused:UNUSED_PAD src0_sel:WORD_1 src1_sel:DWORD
	v_add3_u32 v8, v8, v11, s48
	v_add3_u32 v9, v9, v10, s48
	v_and_b32_sdwa v10, v1, v177 dst_sel:DWORD dst_unused:UNUSED_PAD src0_sel:WORD_1 src1_sel:DWORD
	v_and_b32_sdwa v11, v0, v177 dst_sel:DWORD dst_unused:UNUSED_PAD src0_sel:WORD_1 src1_sel:DWORD
	v_add3_u32 v1, v1, v10, s48
	v_add3_u32 v0, v0, v11, s48
	v_and_b32_e32 v1, 0xffff0000, v1
	v_and_b32_e32 v0, 0xffff0000, v0
	v_lshl_add_u64 v[2:3], v[2:3], 1, v[128:129]
	v_or_b32_sdwa v1, v1, v9 dst_sel:DWORD dst_unused:UNUSED_PAD src0_sel:DWORD src1_sel:WORD_1
	v_or_b32_sdwa v0, v0, v8 dst_sel:DWORD dst_unused:UNUSED_PAD src0_sel:DWORD src1_sel:WORD_1
	global_store_dwordx2 v[2:3], v[0:1], off
	v_add_u32_e32 v1, 0xa2, v168
	v_rsq_f32_e32 v0, v137
	v_ashrrev_i32_e32 v9, 31, v1
	v_mov_b32_e32 v10, v242
	v_mov_b32_e32 v11, v26
	v_mad_u64_u32 v[2:3], s[6:7], s2, v1, 0
	v_mov_b32_e32 v8, v3
	v_mad_u64_u32 v[8:9], s[6:7], s2, v9, v[8:9]
	v_cndmask_b32_e64 v0, 1.0, v0, s[4:5]
	v_mov_b32_e32 v3, v8
	v_mov_b32_e32 v8, v22
	v_mov_b32_e32 v9, v246
	v_pk_mul_f32 v[8:9], v[8:9], v[0:1] op_sel_hi:[1,0]
	v_pk_mul_f32 v[0:1], v[10:11], v[0:1] op_sel_hi:[1,0]
	v_and_b32_sdwa v10, v9, v177 dst_sel:DWORD dst_unused:UNUSED_PAD src0_sel:WORD_1 src1_sel:DWORD
	v_and_b32_sdwa v11, v8, v177 dst_sel:DWORD dst_unused:UNUSED_PAD src0_sel:WORD_1 src1_sel:DWORD
	v_add3_u32 v8, v8, v11, s48
	v_add3_u32 v9, v9, v10, s48
	v_and_b32_sdwa v10, v1, v177 dst_sel:DWORD dst_unused:UNUSED_PAD src0_sel:WORD_1 src1_sel:DWORD
	v_and_b32_sdwa v11, v0, v177 dst_sel:DWORD dst_unused:UNUSED_PAD src0_sel:WORD_1 src1_sel:DWORD
	v_add3_u32 v1, v1, v10, s48
	v_add3_u32 v0, v0, v11, s48
	v_and_b32_e32 v1, 0xffff0000, v1
	v_and_b32_e32 v0, 0xffff0000, v0
	v_lshl_add_u64 v[2:3], v[2:3], 1, v[128:129]
; __device__ __forceinline__ u32 pack2(float a, float b) { return (u32)f2bf(a) | ((u32)f2bf(b) << 16); }
; __device__ __forceinline__ void gemm_tile(const GemmArgs& ga, int wgid, int next_wgid, bool prefetched, u16* shm, unsigned char* ws, int wv_) {
;     ...
;     _Pragma("unroll") for (int ai = 0; ai < 2; ++ai)
;       _Pragma("unroll") for (int m = 0; m < 4; ++m)
;         _Pragma("unroll") for (int j = 0; j < 4; ++j) {
;           int row = rbase + ai * HALF + m * 16 + j;
;           float s = (epi == EPI_Z) ? rsqrtf(sc[ai][m][j] * (1.f / D_) + 1e-6f) : 1.f;
;           *(uint2*)(e_outb + (size_t)row * ldo + bcol + lc4) =
;               make_uint2(pack2(acc[ai][0][m][0][j] * s, acc[ai][0][m][1][j] * s), pack2(acc[ai][1][m][0][j] * s, acc[ai][1][m][1][j] * s));
;         }
	v_or_b32_sdwa v1, v1, v9 dst_sel:DWORD dst_unused:UNUSED_PAD src0_sel:DWORD src1_sel:WORD_1
	v_or_b32_sdwa v0, v0, v8 dst_sel:DWORD dst_unused:UNUSED_PAD src0_sel:DWORD src1_sel:WORD_1
	global_store_dwordx2 v[2:3], v[0:1], off
	v_add_u32_e32 v1, 0xa3, v168
	v_rsq_f32_e32 v0, v135
	v_ashrrev_i32_e32 v9, 31, v1
	v_mov_b32_e32 v10, v243
	v_mov_b32_e32 v11, v27
	v_mad_u64_u32 v[2:3], s[6:7], s2, v1, 0
	v_mov_b32_e32 v8, v3
	v_mad_u64_u32 v[8:9], s[6:7], s2, v9, v[8:9]
	v_cndmask_b32_e64 v0, 1.0, v0, s[4:5]
	v_mov_b32_e32 v3, v8
	v_mov_b32_e32 v8, v23
	v_mov_b32_e32 v9, v247
	v_pk_mul_f32 v[8:9], v[8:9], v[0:1] op_sel_hi:[1,0]
	v_pk_mul_f32 v[0:1], v[10:11], v[0:1] op_sel_hi:[1,0]
	v_and_b32_sdwa v10, v9, v177 dst_sel:DWORD dst_unused:UNUSED_PAD src0_sel:WORD_1 src1_sel:DWORD
	v_and_b32_sdwa v11, v8, v177 dst_sel:DWORD dst_unused:UNUSED_PAD src0_sel:WORD_1 src1_sel:DWORD
	v_add3_u32 v8, v8, v11, s48
	v_add3_u32 v9, v9, v10, s48
	v_and_b32_sdwa v10, v1, v177 dst_sel:DWORD dst_unused:UNUSED_PAD src0_sel:WORD_1 src1_sel:DWORD
	v_and_b32_sdwa v11, v0, v177 dst_sel:DWORD dst_unused:UNUSED_PAD src0_sel:WORD_1 src1_sel:DWORD
	v_add3_u32 v1, v1, v10, s48
	v_add3_u32 v0, v0, v11, s48
	v_and_b32_e32 v1, 0xffff0000, v1
	v_and_b32_e32 v0, 0xffff0000, v0
	v_lshl_add_u64 v[2:3], v[2:3], 1, v[128:129]
	v_or_b32_sdwa v1, v1, v9 dst_sel:DWORD dst_unused:UNUSED_PAD src0_sel:DWORD src1_sel:WORD_1
	v_or_b32_sdwa v0, v0, v8 dst_sel:DWORD dst_unused:UNUSED_PAD src0_sel:DWORD src1_sel:WORD_1
	global_store_dwordx2 v[2:3], v[0:1], off
	v_add_u32_e32 v136, 0xb0, v168
	v_rsq_f32_e32 v0, v133
	v_mad_u64_u32 v[2:3], s[6:7], s2, v136, 0
	v_mov_b32_e32 v8, v3
	v_ashrrev_i32_e32 v1, 31, v136
	v_mad_u64_u32 v[8:9], s[6:7], s2, v1, v[8:9]
	v_cndmask_b32_e64 v0, 1.0, v0, s[4:5]
	v_mov_b32_e32 v3, v8
	v_mov_b32_e32 v8, v204
	v_mov_b32_e32 v9, v12
	v_pk_mul_f32 v[8:9], v[8:9], v[0:1] op_sel_hi:[1,0]
	v_mov_b32_e32 v10, v182
	v_mov_b32_e32 v11, v4
	v_pk_mul_f32 v[0:1], v[10:11], v[0:1] op_sel_hi:[1,0]
	v_and_b32_sdwa v10, v9, v177 dst_sel:DWORD dst_unused:UNUSED_PAD src0_sel:WORD_1 src1_sel:DWORD
	v_and_b32_sdwa v11, v8, v177 dst_sel:DWORD dst_unused:UNUSED_PAD src0_sel:WORD_1 src1_sel:DWORD
	v_add3_u32 v8, v8, v11, s48
	v_add3_u32 v9, v9, v10, s48
	v_and_b32_sdwa v10, v1, v177 dst_sel:DWORD dst_unused:UNUSED_PAD src0_sel:WORD_1 src1_sel:DWORD
	v_and_b32_sdwa v11, v0, v177 dst_sel:DWORD dst_unused:UNUSED_PAD src0_sel:WORD_1 src1_sel:DWORD
	v_add3_u32 v1, v1, v10, s48
	v_add3_u32 v0, v0, v11, s48
	v_and_b32_e32 v1, 0xffff0000, v1
	v_and_b32_e32 v0, 0xffff0000, v0
	v_lshl_add_u64 v[2:3], v[2:3], 1, v[128:129]
	v_or_b32_sdwa v1, v1, v9 dst_sel:DWORD dst_unused:UNUSED_PAD src0_sel:DWORD src1_sel:WORD_1
	v_or_b32_sdwa v0, v0, v8 dst_sel:DWORD dst_unused:UNUSED_PAD src0_sel:DWORD src1_sel:WORD_1
	global_store_dwordx2 v[2:3], v[0:1], off
	v_add_u32_e32 v1, 0xb1, v168
	v_rsq_f32_e32 v0, v132
	v_ashrrev_i32_e32 v9, 31, v1
	v_mov_b32_e32 v10, v183
	v_mov_b32_e32 v11, v5
	v_mad_u64_u32 v[2:3], s[6:7], s2, v1, 0
	v_mov_b32_e32 v8, v3
	v_mad_u64_u32 v[8:9], s[6:7], s2, v9, v[8:9]
	v_cndmask_b32_e64 v0, 1.0, v0, s[4:5]
	v_mov_b32_e32 v3, v8
	v_mov_b32_e32 v8, v205
	v_mov_b32_e32 v9, v13
	v_pk_mul_f32 v[8:9], v[8:9], v[0:1] op_sel_hi:[1,0]
	v_pk_mul_f32 v[0:1], v[10:11], v[0:1] op_sel_hi:[1,0]
	v_and_b32_sdwa v10, v9, v177 dst_sel:DWORD dst_unused:UNUSED_PAD src0_sel:WORD_1 src1_sel:DWORD
	v_and_b32_sdwa v11, v8, v177 dst_sel:DWORD dst_unused:UNUSED_PAD src0_sel:WORD_1 src1_sel:DWORD
	v_add3_u32 v8, v8, v11, s48
	v_add3_u32 v9, v9, v10, s48
	v_and_b32_sdwa v10, v1, v177 dst_sel:DWORD dst_unused:UNUSED_PAD src0_sel:WORD_1 src1_sel:DWORD
	v_and_b32_sdwa v11, v0, v177 dst_sel:DWORD dst_unused:UNUSED_PAD src0_sel:WORD_1 src1_sel:DWORD
	v_add3_u32 v1, v1, v10, s48
	v_add3_u32 v0, v0, v11, s48
	v_and_b32_e32 v1, 0xffff0000, v1
	v_and_b32_e32 v0, 0xffff0000, v0
	v_lshl_add_u64 v[2:3], v[2:3], 1, v[128:129]
	v_or_b32_sdwa v1, v1, v9 dst_sel:DWORD dst_unused:UNUSED_PAD src0_sel:DWORD src1_sel:WORD_1
	v_or_b32_sdwa v0, v0, v8 dst_sel:DWORD dst_unused:UNUSED_PAD src0_sel:DWORD src1_sel:WORD_1
	global_store_dwordx2 v[2:3], v[0:1], off
	v_add_u32_e32 v1, 0xb2, v168
	v_rsq_f32_e32 v0, v131
	v_ashrrev_i32_e32 v9, 31, v1
	v_mov_b32_e32 v10, v184
	v_mov_b32_e32 v11, v6
	v_mad_u64_u32 v[2:3], s[6:7], s2, v1, 0
	v_mov_b32_e32 v8, v3
	v_mad_u64_u32 v[8:9], s[6:7], s2, v9, v[8:9]
	v_cndmask_b32_e64 v0, 1.0, v0, s[4:5]
	v_mov_b32_e32 v3, v8
	v_mov_b32_e32 v8, v206
	v_mov_b32_e32 v9, v14
	v_pk_mul_f32 v[8:9], v[8:9], v[0:1] op_sel_hi:[1,0]
	v_pk_mul_f32 v[0:1], v[10:11], v[0:1] op_sel_hi:[1,0]
	v_and_b32_sdwa v10, v9, v177 dst_sel:DWORD dst_unused:UNUSED_PAD src0_sel:WORD_1 src1_sel:DWORD
	v_and_b32_sdwa v11, v8, v177 dst_sel:DWORD dst_unused:UNUSED_PAD src0_sel:WORD_1 src1_sel:DWORD
	v_add3_u32 v8, v8, v11, s48
	v_add3_u32 v9, v9, v10, s48
	v_and_b32_sdwa v10, v1, v177 dst_sel:DWORD dst_unused:UNUSED_PAD src0_sel:WORD_1 src1_sel:DWORD
	v_and_b32_sdwa v11, v0, v177 dst_sel:DWORD dst_unused:UNUSED_PAD src0_sel:WORD_1 src1_sel:DWORD
	v_add3_u32 v1, v1, v10, s48
	v_add3_u32 v0, v0, v11, s48
	v_and_b32_e32 v1, 0xffff0000, v1
	v_and_b32_e32 v0, 0xffff0000, v0
	v_lshl_add_u64 v[2:3], v[2:3], 1, v[128:129]
	v_or_b32_sdwa v1, v1, v9 dst_sel:DWORD dst_unused:UNUSED_PAD src0_sel:DWORD src1_sel:WORD_1
	v_or_b32_sdwa v0, v0, v8 dst_sel:DWORD dst_unused:UNUSED_PAD src0_sel:DWORD src1_sel:WORD_1
	global_store_dwordx2 v[2:3], v[0:1], off
	v_add_u32_e32 v1, 0xb3, v168
	v_rsq_f32_e32 v0, v130
	v_ashrrev_i32_e32 v9, 31, v1
	v_mov_b32_e32 v10, v185
	v_mov_b32_e32 v11, v7
	v_mad_u64_u32 v[2:3], s[6:7], s2, v1, 0
	v_mov_b32_e32 v8, v3
	v_mad_u64_u32 v[8:9], s[2:3], s2, v9, v[8:9]
	v_cndmask_b32_e64 v0, 1.0, v0, s[4:5]
	v_mov_b32_e32 v3, v8
	v_mov_b32_e32 v8, v207
	v_mov_b32_e32 v9, v15
	v_pk_mul_f32 v[8:9], v[8:9], v[0:1] op_sel_hi:[1,0]
	v_pk_mul_f32 v[0:1], v[10:11], v[0:1] op_sel_hi:[1,0]
	v_and_b32_sdwa v10, v9, v177 dst_sel:DWORD dst_unused:UNUSED_PAD src0_sel:WORD_1 src1_sel:DWORD
	v_and_b32_sdwa v11, v8, v177 dst_sel:DWORD dst_unused:UNUSED_PAD src0_sel:WORD_1 src1_sel:DWORD
	v_add3_u32 v8, v8, v11, s48
	v_add3_u32 v9, v9, v10, s48
	v_and_b32_sdwa v10, v1, v177 dst_sel:DWORD dst_unused:UNUSED_PAD src0_sel:WORD_1 src1_sel:DWORD
	v_and_b32_sdwa v11, v0, v177 dst_sel:DWORD dst_unused:UNUSED_PAD src0_sel:WORD_1 src1_sel:DWORD
	v_add3_u32 v1, v1, v10, s48
	v_add3_u32 v0, v0, v11, s48
	v_and_b32_e32 v1, 0xffff0000, v1
	v_and_b32_e32 v0, 0xffff0000, v0
	v_lshl_add_u64 v[2:3], v[2:3], 1, v[128:129]
	v_or_b32_sdwa v1, v1, v9 dst_sel:DWORD dst_unused:UNUSED_PAD src0_sel:DWORD src1_sel:WORD_1
	v_or_b32_sdwa v0, v0, v8 dst_sel:DWORD dst_unused:UNUSED_PAD src0_sel:DWORD src1_sel:WORD_1
	global_store_dwordx2 v[2:3], v[0:1], off
	s_branch .LBB0_1052

; __device__ __forceinline__ float bflo(u32 w) { return __uint_as_float(w << 16); }
; __device__ __forceinline__ float bfhi(u32 w) { return __uint_as_float(w & 0xffff0000u); }
; __device__ __forceinline__ u32 pack2(float a, float b) { return (u32)f2bf(a) | ((u32)f2bf(b) << 16); }
; __device__ __forceinline__ float sigmoidf_(float x) { return __builtin_amdgcn_rcpf(1.f + __expf(-x)); }
; __device__ __forceinline__ void gemm_tile(const GemmArgs& ga, int wgid, int next_wgid, bool prefetched, u16* shm, unsigned char* ws, int wv_) {
;     ...
;       if (!GATE) { EPI_LOADS(0, 0) }
;       _Pragma("unroll") for (int bb = 0; bb < 8; ++bb) {
;         const int ai = bb >> 2, m = bb & 3;
;         const int cur = GATE ? 0 : (bb & 1);
;         if (GATE) { EPI_LOADS(bb, 0) }
;         else if (bb < 7) { EPI_LOADS(bb + 1, (bb + 1) & 1) }
;         _Pragma("unroll") for (int j = 0; j < 4; ++j) {
;           int row = rbase + ai * HALF + m * 16 + j;
;           unsigned eo = (unsigned)row * (unsigned)D_ + (unsigned)col0;
;           float s = 1.f;
;           if (GATE) s = rsqrtf(sc[j] * (1.f / D_) + 1e-6f);
;           const float a0 = acc[ai][0][m][0][j], a1 = acc[ai][0][m][1][j], a2 = acc[ai][1][m][0][j], a3 = acc[ai][1][m][1][j];
;           float4 xv = xin[cur][j];
;           if (GATE) {
;             xv.x += ga.live * (bflo(pin[j].x) * sigmoidf_(a0 * s));
;             xv.y += ga.live * (bfhi(pin[j].x) * sigmoidf_(a1 * s));
;             xv.z += ga.live * (bflo(pin[j].y) * sigmoidf_(a2 * s));
;             xv.w += ga.live * (bfhi(pin[j].y) * sigmoidf_(a3 * s));
;           } else {
;             const float al = ga.live * ga.alpha;
;             xv.x += al * a0; xv.y += al * a1; xv.z += al * a2; xv.w += al * a3;
;           }
;           *(float4*)(const_cast<char*>(xb) + (size_t)(eo * 4u)) = xv;
;           if (e_gn) *(uint2*)(ob + (size_t)(eo * 2u)) = make_uint2(pack2(xv.x * gn4.x, xv.y * gn4.y), pack2(xv.z * gn4.z, xv.w * gn4.w));
.LBB0_1130:
	v_readlane_b32 s8, v254, 61
	v_readlane_b32 s9, v254, 62
	s_add_u32 s8, s22, s8
	s_addc_u32 s9, s23, s9
	v_readlane_b32 s12, v254, 43
	v_writelane_b32 v255, s8, 6
	v_readlane_b32 s13, v254, 44
	v_lshlrev_b32_e32 v190, 11, v168
	v_cndmask_b32_e64 v0, 0, 1, s[6:7]
	v_writelane_b32 v255, s9, 7
	s_mov_b64 s[8:9], -1
	s_and_b64 vcc, exec, s[12:13]
	v_add_u32_e32 v173, v190, v172
	v_cmp_ne_u32_e64 s[6:7], 1, v0
	s_cbranch_vccz .LBB0_1196
	v_ashrrev_i32_e32 v169, 31, v168
	v_lshlrev_b32_e32 v28, 2, v173
	v_lshl_add_u64 v[146:147], v[168:169], 2, s[68:69]
	s_waitcnt lgkmcnt(0)
	global_load_dwordx4 v[0:3], v28, s[78:79]
	global_load_dwordx4 v[134:137], v[146:147], off
	s_add_u32 s8, s14, 0x29140000
	v_add_u32_e32 v10, 0x800, v173
	v_lshlrev_b32_e32 v166, 1, v173
	s_addc_u32 s9, s15, 0
	v_add_u32_e32 v11, 0x1000, v173
	v_add_u32_e32 v16, 0x1800, v173
	v_lshlrev_b32_e32 v17, 2, v10
	global_load_dwordx2 v[8:9], v166, s[8:9]
	v_lshlrev_b32_e32 v10, 1, v10
	v_lshlrev_b32_e32 v18, 2, v11
	v_lshlrev_b32_e32 v11, 1, v11
	v_lshlrev_b32_e32 v19, 2, v16
	v_lshlrev_b32_e32 v16, 1, v16
	global_load_dwordx4 v[142:145], v17, s[78:79]
	global_load_dwordx2 v[152:153], v10, s[8:9]
	global_load_dwordx4 v[138:141], v18, s[78:79]
	global_load_dwordx2 v[150:151], v11, s[8:9]
	global_load_dwordx4 v[130:133], v19, s[78:79]
	global_load_dwordx2 v[148:149], v16, s[8:9]
	s_waitcnt vmcnt(0)
	v_mov_b32_e32 v10, v0
	v_fmamk_f32 v0, v134, 0x3a000000, v175
	v_mov_b32_e32 v11, v2
	s_nop 1
	v_rsq_f32_e32 v16, v0
	v_mov_b32_e32 v2, v1
	v_lshlrev_b32_e32 v1, 16, v9
	v_lshlrev_b32_e32 v0, 16, v8
	v_mul_f32_e32 v17, v116, v16
	v_mul_f32_e32 v18, v112, v16
	v_mul_f32_e32 v19, v124, v16
	v_mul_f32_e32 v16, v120, v16
	v_mul_f32_e32 v17, 0xbfb8aa3b, v17
	v_mul_f32_e32 v18, 0xbfb8aa3b, v18
	v_mul_f32_e32 v19, 0xbfb8aa3b, v19
	v_mul_f32_e32 v16, 0xbfb8aa3b, v16
	v_exp_f32_e32 v17, v17
	v_exp_f32_e32 v18, v18
	v_exp_f32_e32 v19, v19
	v_exp_f32_e32 v16, v16
	v_add_f32_e32 v17, 1.0, v17
	v_add_f32_e32 v18, 1.0, v18
	v_add_f32_e32 v19, 1.0, v19
	v_add_f32_e32 v29, 1.0, v16
	v_rcp_f32_e32 v16, v17
	v_rcp_f32_e32 v18, v18
	v_rcp_f32_e32 v17, v19
	v_rcp_f32_e32 v19, v29
	v_and_b32_e32 v9, 0xffff0000, v9
	v_and_b32_e32 v8, 0xffff0000, v8
	v_pk_fma_f32 v[154:155], v[16:17], v[0:1], v[10:11]
	v_pk_fma_f32 v[156:157], v[18:19], v[8:9], v[2:3]
	v_mov_b32_e32 v0, v154
	v_mov_b32_e32 v1, v156
	v_mov_b32_e32 v2, v155
	v_mov_b32_e32 v3, v157
	s_and_b64 vcc, exec, s[6:7]
	global_store_dwordx4 v28, v[0:3], s[2:3]
	s_cbranch_vccnz .LBB0_1133
	s_nop 0
	v_pk_mul_f32 v[0:1], v[128:129], v[154:155]
	v_pk_mul_f32 v[2:3], v[170:171], v[156:157]
	v_and_b32_sdwa v10, v1, v177 dst_sel:DWORD dst_unused:UNUSED_PAD src0_sel:WORD_1 src1_sel:DWORD
	v_and_b32_sdwa v11, v0, v177 dst_sel:DWORD dst_unused:UNUSED_PAD src0_sel:WORD_1 src1_sel:DWORD
	v_add3_u32 v0, v0, v11, s48
	v_add3_u32 v1, v1, v10, s48
	v_and_b32_sdwa v10, v3, v177 dst_sel:DWORD dst_unused:UNUSED_PAD src0_sel:WORD_1 src1_sel:DWORD
	v_and_b32_sdwa v11, v2, v177 dst_sel:DWORD dst_unused:UNUSED_PAD src0_sel:WORD_1 src1_sel:DWORD
	v_add3_u32 v3, v3, v10, s48
	v_add3_u32 v2, v2, v11, s48
	v_and_b32_e32 v3, 0xffff0000, v3
	v_and_b32_e32 v2, 0xffff0000, v2
	v_lshl_add_u64 v[8:9], s[90:91], 0, v[166:167]
	v_or_b32_sdwa v1, v3, v1 dst_sel:DWORD dst_unused:UNUSED_PAD src0_sel:DWORD src1_sel:WORD_1
	v_or_b32_sdwa v0, v2, v0 dst_sel:DWORD dst_unused:UNUSED_PAD src0_sel:DWORD src1_sel:WORD_1
	global_store_dwordx2 v[8:9], v[0:1], off

; __device__ __forceinline__ float bflo(u32 w) { return __uint_as_float(w << 16); }
; __device__ __forceinline__ float bfhi(u32 w) { return __uint_as_float(w & 0xffff0000u); }
; __device__ __forceinline__ u32 pack2(float a, float b) { return (u32)f2bf(a) | ((u32)f2bf(b) << 16); }
; __device__ __forceinline__ float sigmoidf_(float x) { return __builtin_amdgcn_rcpf(1.f + __expf(-x)); }
; __device__ __forceinline__ void gemm_tile(const GemmArgs& ga, int wgid, int next_wgid, bool prefetched, u16* shm, unsigned char* ws, int wv_) {
;     ...
;       if (!GATE) { EPI_LOADS(0, 0) }
;       _Pragma("unroll") for (int bb = 0; bb < 8; ++bb) {
;         const int ai = bb >> 2, m = bb & 3;
;         const int cur = GATE ? 0 : (bb & 1);
;         if (GATE) { EPI_LOADS(bb, 0) }
;         else if (bb < 7) { EPI_LOADS(bb + 1, (bb + 1) & 1) }
;         _Pragma("unroll") for (int j = 0; j < 4; ++j) {
;           int row = rbase + ai * HALF + m * 16 + j;
;           unsigned eo = (unsigned)row * (unsigned)D_ + (unsigned)col0;
;           float s = 1.f;
;           if (GATE) s = rsqrtf(sc[j] * (1.f / D_) + 1e-6f);
;           const float a0 = acc[ai][0][m][0][j], a1 = acc[ai][0][m][1][j], a2 = acc[ai][1][m][0][j], a3 = acc[ai][1][m][1][j];
;           float4 xv = xin[cur][j];
;           if (GATE) {
;             xv.x += ga.live * (bflo(pin[j].x) * sigmoidf_(a0 * s));
;             xv.y += ga.live * (bfhi(pin[j].x) * sigmoidf_(a1 * s));
;             xv.z += ga.live * (bflo(pin[j].y) * sigmoidf_(a2 * s));
;             xv.w += ga.live * (bfhi(pin[j].y) * sigmoidf_(a3 * s));
;           } else {
;             const float al = ga.live * ga.alpha;
;             xv.x += al * a0; xv.y += al * a1; xv.z += al * a2; xv.w += al * a3;
;           }
;           *(float4*)(const_cast<char*>(xb) + (size_t)(eo * 4u)) = xv;
;           if (e_gn) *(uint2*)(ob + (size_t)(eo * 2u)) = make_uint2(pack2(xv.x * gn4.x, xv.y * gn4.y), pack2(xv.z * gn4.z, xv.w * gn4.w));
;           float sq = xv.x * xv.x + xv.y * xv.y + xv.z * xv.z + xv.w * xv.w;
;           sq = red16(sq);
;           const int ridx = bb * 4 + j;
;           if (ridx < 16) sqA = (fr == ridx) ? sq : sqA;
;           else sqB = (fr == ridx - 16) ? sq : sqB;
;         }
.LBB0_1139:
	s_nop 0
	v_pk_mul_f32 v[0:1], v[134:135], v[134:135]
	v_pk_mul_f32 v[2:3], v[130:131], v[130:131]
	s_nop 0
	v_add_f32_e32 v0, v0, v2
	v_add_f32_e32 v0, v1, v0
	v_add_f32_e32 v0, v3, v0
	s_nop 1
	v_add_f32_dpp v0, v0, v0 quad_perm:[1,0,3,2] row_mask:0xf bank_mask:0xf bound_ctrl:1
	s_nop 1
	v_add_f32_dpp v0, v0, v0 quad_perm:[2,3,0,1] row_mask:0xf bank_mask:0xf bound_ctrl:1
	s_nop 1
	v_add_f32_dpp v164, v0, v0 row_half_mirror row_mask:0xf bank_mask:0xf bound_ctrl:1
	s_nop 1
	v_mov_b32_dpp v165, v164 row_mirror row_mask:0xf bank_mask:0xf bound_ctrl:1
	global_load_dwordx4 v[130:133], v[146:147], off offset:64
	v_lshl_add_u32 v198, v168, 11, v172
	v_add_u32_e32 v0, 0x8000, v198
	v_lshlrev_b32_e32 v30, 2, v0
	v_lshlrev_b32_e32 v166, 1, v0
	global_load_dwordx4 v[0:3], v30, s[78:79]
	v_add_u32_e32 v10, 0x8800, v198
	v_add_u32_e32 v11, 0x9000, v198
	v_add_u32_e32 v16, 0x9800, v198
	v_lshlrev_b32_e32 v17, 2, v10
	global_load_dwordx2 v[8:9], v166, s[8:9]
	v_lshlrev_b32_e32 v10, 1, v10
	v_lshlrev_b32_e32 v18, 2, v11
	v_lshlrev_b32_e32 v11, 1, v11
	v_lshlrev_b32_e32 v19, 2, v16
	v_lshlrev_b32_e32 v16, 1, v16
	global_load_dwordx4 v[142:145], v17, s[78:79]
	global_load_dwordx2 v[152:153], v10, s[8:9]
	global_load_dwordx4 v[138:141], v18, s[78:79]
	global_load_dwordx2 v[150:151], v11, s[8:9]
	global_load_dwordx4 v[134:137], v19, s[78:79]
	global_load_dwordx2 v[148:149], v16, s[8:9]
	s_waitcnt vmcnt(8)
	v_fmamk_f32 v10, v130, 0x3a000000, v175
	s_waitcnt vmcnt(7)
	v_mov_b32_e32 v16, v0
	v_rsq_f32_e32 v18, v10
	v_mov_b32_e32 v17, v2
	s_waitcnt vmcnt(6)
	v_lshlrev_b32_e32 v11, 16, v9
	v_mov_b32_e32 v0, v18
	v_mul_f32_e32 v2, v100, v0
	v_mul_f32_e32 v18, v96, v0
	v_mul_f32_e32 v19, v108, v0
	v_mul_f32_e32 v0, v104, v0
	v_mul_f32_e32 v2, 0xbfb8aa3b, v2
	v_mul_f32_e32 v18, 0xbfb8aa3b, v18
	v_mul_f32_e32 v19, 0xbfb8aa3b, v19
	v_mul_f32_e32 v0, 0xbfb8aa3b, v0
	v_exp_f32_e32 v2, v2
	v_exp_f32_e32 v18, v18
	v_exp_f32_e32 v19, v19
	v_exp_f32_e32 v0, v0
	v_add_f32_e32 v2, 1.0, v2
	v_add_f32_e32 v28, 1.0, v18
	v_add_f32_e32 v19, 1.0, v19
	v_add_f32_e32 v0, 1.0, v0
	v_rcp_f32_e32 v18, v2
	v_rcp_f32_e32 v28, v28
	v_rcp_f32_e32 v19, v19
	v_rcp_f32_e32 v29, v0
	v_lshlrev_b32_e32 v10, 16, v8
	v_and_b32_e32 v9, 0xffff0000, v9
	v_and_b32_e32 v8, 0xffff0000, v8
	v_mov_b32_e32 v2, v1
	v_pk_fma_f32 v[154:155], v[18:19], v[10:11], v[16:17]
	v_pk_fma_f32 v[156:157], v[28:29], v[8:9], v[2:3]
	v_mov_b32_e32 v0, v154
	v_mov_b32_e32 v1, v156
	v_mov_b32_e32 v2, v155
	v_mov_b32_e32 v3, v157
	s_and_b64 vcc, exec, s[6:7]
	global_store_dwordx4 v30, v[0:3], s[2:3]
	s_cbranch_vccnz .LBB0_1141
	s_nop 0
	v_pk_mul_f32 v[0:1], v[128:129], v[154:155]
	v_pk_mul_f32 v[2:3], v[170:171], v[156:157]
	v_and_b32_sdwa v10, v1, v177 dst_sel:DWORD dst_unused:UNUSED_PAD src0_sel:WORD_1 src1_sel:DWORD
	v_and_b32_sdwa v11, v0, v177 dst_sel:DWORD dst_unused:UNUSED_PAD src0_sel:WORD_1 src1_sel:DWORD
	v_add3_u32 v0, v0, v11, s48
	v_add3_u32 v1, v1, v10, s48
	v_and_b32_sdwa v10, v3, v177 dst_sel:DWORD dst_unused:UNUSED_PAD src0_sel:WORD_1 src1_sel:DWORD
	v_and_b32_sdwa v11, v2, v177 dst_sel:DWORD dst_unused:UNUSED_PAD src0_sel:WORD_1 src1_sel:DWORD
	v_add3_u32 v3, v3, v10, s48
	v_add3_u32 v2, v2, v11, s48
	v_and_b32_e32 v3, 0xffff0000, v3
	v_and_b32_e32 v2, 0xffff0000, v2
	v_lshl_add_u64 v[8:9], s[90:91], 0, v[166:167]
	v_or_b32_sdwa v1, v3, v1 dst_sel:DWORD dst_unused:UNUSED_PAD src0_sel:DWORD src1_sel:WORD_1
	v_or_b32_sdwa v0, v2, v0 dst_sel:DWORD dst_unused:UNUSED_PAD src0_sel:DWORD src1_sel:WORD_1
	global_store_dwordx2 v[8:9], v[0:1], off

; __device__ __forceinline__ float bflo(u32 w) { return __uint_as_float(w << 16); }
; __device__ __forceinline__ float bfhi(u32 w) { return __uint_as_float(w & 0xffff0000u); }
; __device__ __forceinline__ u32 pack2(float a, float b) { return (u32)f2bf(a) | ((u32)f2bf(b) << 16); }
; __device__ __forceinline__ float sigmoidf_(float x) { return __builtin_amdgcn_rcpf(1.f + __expf(-x)); }
; __device__ __forceinline__ void gemm_tile(const GemmArgs& ga, int wgid, int next_wgid, bool prefetched, u16* shm, unsigned char* ws, int wv_) {
;     ...
;       if (!GATE) { EPI_LOADS(0, 0) }
;       _Pragma("unroll") for (int bb = 0; bb < 8; ++bb) {
;         const int ai = bb >> 2, m = bb & 3;
;         const int cur = GATE ? 0 : (bb & 1);
;         if (GATE) { EPI_LOADS(bb, 0) }
;         else if (bb < 7) { EPI_LOADS(bb + 1, (bb + 1) & 1) }
;         _Pragma("unroll") for (int j = 0; j < 4; ++j) {
;           int row = rbase + ai * HALF + m * 16 + j;
;           unsigned eo = (unsigned)row * (unsigned)D_ + (unsigned)col0;
;           float s = 1.f;
;           if (GATE) s = rsqrtf(sc[j] * (1.f / D_) + 1e-6f);
;           const float a0 = acc[ai][0][m][0][j], a1 = acc[ai][0][m][1][j], a2 = acc[ai][1][m][0][j], a3 = acc[ai][1][m][1][j];
;           float4 xv = xin[cur][j];
;           if (GATE) {
;             xv.x += ga.live * (bflo(pin[j].x) * sigmoidf_(a0 * s));
;             xv.y += ga.live * (bfhi(pin[j].x) * sigmoidf_(a1 * s));
;             xv.z += ga.live * (bflo(pin[j].y) * sigmoidf_(a2 * s));
;             xv.w += ga.live * (bfhi(pin[j].y) * sigmoidf_(a3 * s));
;           } else {
;             const float al = ga.live * ga.alpha;
;             xv.x += al * a0; xv.y += al * a1; xv.z += al * a2; xv.w += al * a3;
;           }
;           *(float4*)(const_cast<char*>(xb) + (size_t)(eo * 4u)) = xv;
;           if (e_gn) *(uint2*)(ob + (size_t)(eo * 2u)) = make_uint2(pack2(xv.x * gn4.x, xv.y * gn4.y), pack2(xv.z * gn4.z, xv.w * gn4.w));
;           float sq = xv.x * xv.x + xv.y * xv.y + xv.z * xv.z + xv.w * xv.w;
;           sq = red16(sq);
;           const int ridx = bb * 4 + j;
;           if (ridx < 16) sqA = (fr == ridx) ? sq : sqA;
;           else sqB = (fr == ridx - 16) ? sq : sqB;
;         }
.LBB0_1147:
	s_nop 0
	v_pk_mul_f32 v[0:1], v[130:131], v[130:131]
	v_pk_mul_f32 v[2:3], v[132:133], v[132:133]
	s_nop 0
	v_add_f32_e32 v0, v0, v2
	v_add_f32_e32 v0, v1, v0
	v_add_f32_e32 v0, v3, v0
	s_nop 1
	v_add_f32_dpp v0, v0, v0 quad_perm:[1,0,3,2] row_mask:0xf bank_mask:0xf bound_ctrl:1
	s_nop 1
	v_add_f32_dpp v0, v0, v0 quad_perm:[2,3,0,1] row_mask:0xf bank_mask:0xf bound_ctrl:1
	s_nop 1
	v_add_f32_dpp v196, v0, v0 row_half_mirror row_mask:0xf bank_mask:0xf bound_ctrl:1
	s_nop 1
	v_mov_b32_dpp v197, v196 row_mirror row_mask:0xf bank_mask:0xf bound_ctrl:1
	global_load_dwordx4 v[130:133], v[146:147], off offset:128
	v_add_u32_e32 v0, 0x10000, v198
	v_lshlrev_b32_e32 v30, 2, v0
	v_lshlrev_b32_e32 v166, 1, v0
	global_load_dwordx4 v[0:3], v30, s[78:79]
	v_add_u32_e32 v10, 0x10800, v198
	v_add_u32_e32 v11, 0x11000, v198
	v_add_u32_e32 v16, 0x11800, v198
	v_lshlrev_b32_e32 v17, 2, v10
	global_load_dwordx2 v[8:9], v166, s[8:9]
	v_lshlrev_b32_e32 v10, 1, v10
	v_lshlrev_b32_e32 v18, 2, v11
	v_lshlrev_b32_e32 v11, 1, v11
	v_lshlrev_b32_e32 v19, 2, v16
	v_lshlrev_b32_e32 v16, 1, v16
	global_load_dwordx4 v[142:145], v17, s[78:79]
	global_load_dwordx2 v[152:153], v10, s[8:9]
	global_load_dwordx4 v[138:141], v18, s[78:79]
	global_load_dwordx2 v[150:151], v11, s[8:9]
	global_load_dwordx4 v[134:137], v19, s[78:79]
	global_load_dwordx2 v[148:149], v16, s[8:9]
	s_waitcnt vmcnt(8)
	v_fmamk_f32 v10, v130, 0x3a000000, v175
	s_waitcnt vmcnt(7)
	v_mov_b32_e32 v17, v2
	v_rsq_f32_e32 v18, v10
	v_mov_b32_e32 v16, v0
	s_waitcnt vmcnt(6)
	v_lshlrev_b32_e32 v11, 16, v9
	v_mov_b32_e32 v0, v18
	v_mul_f32_e32 v2, v84, v0
	v_mul_f32_e32 v18, v80, v0
	v_mul_f32_e32 v19, v92, v0
	v_mul_f32_e32 v0, v88, v0
	v_mul_f32_e32 v2, 0xbfb8aa3b, v2
	v_mul_f32_e32 v18, 0xbfb8aa3b, v18
	v_mul_f32_e32 v19, 0xbfb8aa3b, v19
	v_mul_f32_e32 v0, 0xbfb8aa3b, v0
	v_exp_f32_e32 v2, v2
	v_exp_f32_e32 v18, v18
	v_exp_f32_e32 v19, v19
	v_exp_f32_e32 v0, v0
	v_add_f32_e32 v2, 1.0, v2
	v_add_f32_e32 v28, 1.0, v18
	v_add_f32_e32 v19, 1.0, v19
	v_add_f32_e32 v0, 1.0, v0
	v_rcp_f32_e32 v18, v2
	v_rcp_f32_e32 v28, v28
	v_rcp_f32_e32 v19, v19
	v_rcp_f32_e32 v29, v0
	v_lshlrev_b32_e32 v10, 16, v8
	v_and_b32_e32 v9, 0xffff0000, v9
	v_and_b32_e32 v8, 0xffff0000, v8
	v_mov_b32_e32 v2, v1
	v_pk_fma_f32 v[154:155], v[18:19], v[10:11], v[16:17]
	v_pk_fma_f32 v[156:157], v[28:29], v[8:9], v[2:3]
	v_mov_b32_e32 v0, v154
	v_mov_b32_e32 v1, v156
	v_mov_b32_e32 v2, v155
	v_mov_b32_e32 v3, v157
	s_and_b64 vcc, exec, s[6:7]
	global_store_dwordx4 v30, v[0:3], s[2:3]
	s_cbranch_vccnz .LBB0_1149
	s_nop 0
	v_pk_mul_f32 v[0:1], v[128:129], v[154:155]
	v_pk_mul_f32 v[2:3], v[170:171], v[156:157]
	v_and_b32_sdwa v10, v1, v177 dst_sel:DWORD dst_unused:UNUSED_PAD src0_sel:WORD_1 src1_sel:DWORD
	v_and_b32_sdwa v11, v0, v177 dst_sel:DWORD dst_unused:UNUSED_PAD src0_sel:WORD_1 src1_sel:DWORD
	v_add3_u32 v0, v0, v11, s48
	v_add3_u32 v1, v1, v10, s48
	v_and_b32_sdwa v10, v3, v177 dst_sel:DWORD dst_unused:UNUSED_PAD src0_sel:WORD_1 src1_sel:DWORD
	v_and_b32_sdwa v11, v2, v177 dst_sel:DWORD dst_unused:UNUSED_PAD src0_sel:WORD_1 src1_sel:DWORD
	v_add3_u32 v3, v3, v10, s48
	v_add3_u32 v2, v2, v11, s48
	v_and_b32_e32 v3, 0xffff0000, v3
	v_and_b32_e32 v2, 0xffff0000, v2
	v_lshl_add_u64 v[8:9], s[90:91], 0, v[166:167]
	v_or_b32_sdwa v1, v3, v1 dst_sel:DWORD dst_unused:UNUSED_PAD src0_sel:DWORD src1_sel:WORD_1
	v_or_b32_sdwa v0, v2, v0 dst_sel:DWORD dst_unused:UNUSED_PAD src0_sel:DWORD src1_sel:WORD_1
	global_store_dwordx2 v[8:9], v[0:1], off

; __device__ __forceinline__ float bflo(u32 w) { return __uint_as_float(w << 16); }
; __device__ __forceinline__ float bfhi(u32 w) { return __uint_as_float(w & 0xffff0000u); }
; __device__ __forceinline__ u32 pack2(float a, float b) { return (u32)f2bf(a) | ((u32)f2bf(b) << 16); }
; __device__ __forceinline__ float sigmoidf_(float x) { return __builtin_amdgcn_rcpf(1.f + __expf(-x)); }
; __device__ __forceinline__ void gemm_tile(const GemmArgs& ga, int wgid, int next_wgid, bool prefetched, u16* shm, unsigned char* ws, int wv_) {
;     ...
;       if (!GATE) { EPI_LOADS(0, 0) }
;       _Pragma("unroll") for (int bb = 0; bb < 8; ++bb) {
;         const int ai = bb >> 2, m = bb & 3;
;         const int cur = GATE ? 0 : (bb & 1);
;         if (GATE) { EPI_LOADS(bb, 0) }
;         else if (bb < 7) { EPI_LOADS(bb + 1, (bb + 1) & 1) }
;         _Pragma("unroll") for (int j = 0; j < 4; ++j) {
;           int row = rbase + ai * HALF + m * 16 + j;
;           unsigned eo = (unsigned)row * (unsigned)D_ + (unsigned)col0;
;           float s = 1.f;
;           if (GATE) s = rsqrtf(sc[j] * (1.f / D_) + 1e-6f);
;           const float a0 = acc[ai][0][m][0][j], a1 = acc[ai][0][m][1][j], a2 = acc[ai][1][m][0][j], a3 = acc[ai][1][m][1][j];
;           float4 xv = xin[cur][j];
;           if (GATE) {
;             xv.x += ga.live * (bflo(pin[j].x) * sigmoidf_(a0 * s));
;             xv.y += ga.live * (bfhi(pin[j].x) * sigmoidf_(a1 * s));
;             xv.z += ga.live * (bflo(pin[j].y) * sigmoidf_(a2 * s));
;             xv.w += ga.live * (bfhi(pin[j].y) * sigmoidf_(a3 * s));
;           } else {
;             const float al = ga.live * ga.alpha;
;             xv.x += al * a0; xv.y += al * a1; xv.z += al * a2; xv.w += al * a3;
;           }
;           *(float4*)(const_cast<char*>(xb) + (size_t)(eo * 4u)) = xv;
;           if (e_gn) *(uint2*)(ob + (size_t)(eo * 2u)) = make_uint2(pack2(xv.x * gn4.x, xv.y * gn4.y), pack2(xv.z * gn4.z, xv.w * gn4.w));
;           float sq = xv.x * xv.x + xv.y * xv.y + xv.z * xv.z + xv.w * xv.w;
;           sq = red16(sq);
.LBB0_1155:
	s_nop 0
	v_pk_mul_f32 v[0:1], v[130:131], v[130:131]
	v_pk_mul_f32 v[2:3], v[132:133], v[132:133]
	s_nop 0
	v_add_f32_e32 v0, v0, v2
	v_add_f32_e32 v0, v1, v0
	v_add_f32_e32 v0, v3, v0
	s_nop 1
	v_add_f32_dpp v0, v0, v0 quad_perm:[1,0,3,2] row_mask:0xf bank_mask:0xf bound_ctrl:1
	s_nop 1
	v_add_f32_dpp v0, v0, v0 quad_perm:[2,3,0,1] row_mask:0xf bank_mask:0xf bound_ctrl:1
	s_nop 1
	v_add_f32_dpp v186, v0, v0 row_half_mirror row_mask:0xf bank_mask:0xf bound_ctrl:1
	s_nop 1
	v_mov_b32_dpp v237, v186 row_mirror row_mask:0xf bank_mask:0xf bound_ctrl:1
	global_load_dwordx4 v[130:133], v[146:147], off offset:192
	v_add_u32_e32 v0, 0x18000, v198
	v_lshlrev_b32_e32 v30, 2, v0
	v_lshlrev_b32_e32 v166, 1, v0
	global_load_dwordx4 v[0:3], v30, s[78:79]
	v_add_u32_e32 v10, 0x18800, v198
	v_add_u32_e32 v11, 0x19000, v198
	v_add_u32_e32 v16, 0x19800, v198
	v_lshlrev_b32_e32 v17, 2, v10
	global_load_dwordx2 v[8:9], v166, s[8:9]
	v_lshlrev_b32_e32 v10, 1, v10
	v_lshlrev_b32_e32 v18, 2, v11
	v_lshlrev_b32_e32 v11, 1, v11
	v_lshlrev_b32_e32 v19, 2, v16
	v_lshlrev_b32_e32 v16, 1, v16
	global_load_dwordx4 v[142:145], v17, s[78:79]
	global_load_dwordx2 v[152:153], v10, s[8:9]
	global_load_dwordx4 v[138:141], v18, s[78:79]
	global_load_dwordx2 v[150:151], v11, s[8:9]
	global_load_dwordx4 v[134:137], v19, s[78:79]
	global_load_dwordx2 v[148:149], v16, s[8:9]
	s_waitcnt vmcnt(8)
	v_fmamk_f32 v10, v130, 0x3a000000, v175
	s_waitcnt vmcnt(7)
	v_mov_b32_e32 v17, v2
	v_rsq_f32_e32 v18, v10
	v_mov_b32_e32 v16, v0
	s_waitcnt vmcnt(6)
	v_lshlrev_b32_e32 v11, 16, v9
	v_mov_b32_e32 v0, v18
	v_mul_f32_e32 v2, v68, v0
	v_mul_f32_e32 v18, v64, v0
	v_mul_f32_e32 v19, v76, v0
	v_mul_f32_e32 v0, v72, v0
	v_mul_f32_e32 v2, 0xbfb8aa3b, v2
	v_mul_f32_e32 v18, 0xbfb8aa3b, v18
	v_mul_f32_e32 v19, 0xbfb8aa3b, v19
	v_mul_f32_e32 v0, 0xbfb8aa3b, v0
	v_exp_f32_e32 v2, v2
	v_exp_f32_e32 v18, v18
	v_exp_f32_e32 v19, v19
	v_exp_f32_e32 v0, v0
	v_add_f32_e32 v2, 1.0, v2
	v_add_f32_e32 v28, 1.0, v18
	v_add_f32_e32 v19, 1.0, v19
	v_add_f32_e32 v0, 1.0, v0
	v_rcp_f32_e32 v18, v2
	v_rcp_f32_e32 v28, v28
	v_rcp_f32_e32 v19, v19
	v_rcp_f32_e32 v29, v0
	v_lshlrev_b32_e32 v10, 16, v8
	v_and_b32_e32 v9, 0xffff0000, v9
	v_and_b32_e32 v8, 0xffff0000, v8
	v_mov_b32_e32 v2, v1
	v_pk_fma_f32 v[154:155], v[18:19], v[10:11], v[16:17]
	v_pk_fma_f32 v[156:157], v[28:29], v[8:9], v[2:3]
	v_mov_b32_e32 v0, v154
	v_mov_b32_e32 v1, v156
	v_mov_b32_e32 v2, v155
	v_mov_b32_e32 v3, v157
	s_and_b64 vcc, exec, s[6:7]
	global_store_dwordx4 v30, v[0:3], s[2:3]
	s_cbranch_vccnz .LBB0_1157
	s_nop 0
	v_pk_mul_f32 v[0:1], v[128:129], v[154:155]
	v_pk_mul_f32 v[2:3], v[170:171], v[156:157]
	v_and_b32_sdwa v10, v1, v177 dst_sel:DWORD dst_unused:UNUSED_PAD src0_sel:WORD_1 src1_sel:DWORD
	v_and_b32_sdwa v11, v0, v177 dst_sel:DWORD dst_unused:UNUSED_PAD src0_sel:WORD_1 src1_sel:DWORD
	v_add3_u32 v0, v0, v11, s48
	v_add3_u32 v1, v1, v10, s48
	v_and_b32_sdwa v10, v3, v177 dst_sel:DWORD dst_unused:UNUSED_PAD src0_sel:WORD_1 src1_sel:DWORD
	v_and_b32_sdwa v11, v2, v177 dst_sel:DWORD dst_unused:UNUSED_PAD src0_sel:WORD_1 src1_sel:DWORD
	v_add3_u32 v3, v3, v10, s48
	v_add3_u32 v2, v2, v11, s48
	v_and_b32_e32 v3, 0xffff0000, v3
	v_and_b32_e32 v2, 0xffff0000, v2
	v_lshl_add_u64 v[8:9], s[90:91], 0, v[166:167]
	v_or_b32_sdwa v1, v3, v1 dst_sel:DWORD dst_unused:UNUSED_PAD src0_sel:DWORD src1_sel:WORD_1
	v_or_b32_sdwa v0, v2, v0 dst_sel:DWORD dst_unused:UNUSED_PAD src0_sel:DWORD src1_sel:WORD_1
	global_store_dwordx2 v[8:9], v[0:1], off

; __device__ __forceinline__ float bflo(u32 w) { return __uint_as_float(w << 16); }
; __device__ __forceinline__ float bfhi(u32 w) { return __uint_as_float(w & 0xffff0000u); }
; __device__ __forceinline__ u32 pack2(float a, float b) { return (u32)f2bf(a) | ((u32)f2bf(b) << 16); }
; __device__ __forceinline__ float sigmoidf_(float x) { return __builtin_amdgcn_rcpf(1.f + __expf(-x)); }
; __device__ __forceinline__ void gemm_tile(const GemmArgs& ga, int wgid, int next_wgid, bool prefetched, u16* shm, unsigned char* ws, int wv_) {
;     ...
;       if (!GATE) { EPI_LOADS(0, 0) }
;       _Pragma("unroll") for (int bb = 0; bb < 8; ++bb) {
;         const int ai = bb >> 2, m = bb & 3;
;         const int cur = GATE ? 0 : (bb & 1);
;         if (GATE) { EPI_LOADS(bb, 0) }
;         else if (bb < 7) { EPI_LOADS(bb + 1, (bb + 1) & 1) }
;         _Pragma("unroll") for (int j = 0; j < 4; ++j) {
;           int row = rbase + ai * HALF + m * 16 + j;
;           unsigned eo = (unsigned)row * (unsigned)D_ + (unsigned)col0;
;           float s = 1.f;
;           if (GATE) s = rsqrtf(sc[j] * (1.f / D_) + 1e-6f);
;           const float a0 = acc[ai][0][m][0][j], a1 = acc[ai][0][m][1][j], a2 = acc[ai][1][m][0][j], a3 = acc[ai][1][m][1][j];
;           float4 xv = xin[cur][j];
;           if (GATE) {
;             xv.x += ga.live * (bflo(pin[j].x) * sigmoidf_(a0 * s));
;             xv.y += ga.live * (bfhi(pin[j].x) * sigmoidf_(a1 * s));
;             xv.z += ga.live * (bflo(pin[j].y) * sigmoidf_(a2 * s));
;             xv.w += ga.live * (bfhi(pin[j].y) * sigmoidf_(a3 * s));
;           } else {
;             const float al = ga.live * ga.alpha;
;             xv.x += al * a0; xv.y += al * a1; xv.z += al * a2; xv.w += al * a3;
;           }
;           *(float4*)(const_cast<char*>(xb) + (size_t)(eo * 4u)) = xv;
;           if (e_gn) *(uint2*)(ob + (size_t)(eo * 2u)) = make_uint2(pack2(xv.x * gn4.x, xv.y * gn4.y), pack2(xv.z * gn4.z, xv.w * gn4.w));
;           float sq = xv.x * xv.x + xv.y * xv.y + xv.z * xv.z + xv.w * xv.w;
;           sq = red16(sq);
.LBB0_1163:
	s_nop 0
	v_pk_mul_f32 v[0:1], v[130:131], v[130:131]
	v_pk_mul_f32 v[2:3], v[132:133], v[132:133]
	s_nop 0
	v_add_f32_e32 v0, v0, v2
	v_add_f32_e32 v0, v1, v0
	v_add_f32_e32 v0, v3, v0
	s_nop 1
	v_add_f32_dpp v0, v0, v0 quad_perm:[1,0,3,2] row_mask:0xf bank_mask:0xf bound_ctrl:1
	s_nop 1
	v_add_f32_dpp v0, v0, v0 quad_perm:[2,3,0,1] row_mask:0xf bank_mask:0xf bound_ctrl:1
	s_nop 1
	v_add_f32_dpp v213, v0, v0 row_half_mirror row_mask:0xf bank_mask:0xf bound_ctrl:1
	s_nop 1
	v_mov_b32_dpp v214, v213 row_mirror row_mask:0xf bank_mask:0xf bound_ctrl:1
	global_load_dwordx4 v[130:133], v[146:147], off offset:512
	v_add_u32_e32 v0, 0x40000, v198
	v_lshlrev_b32_e32 v30, 2, v0
	v_lshlrev_b32_e32 v166, 1, v0
	global_load_dwordx4 v[0:3], v30, s[78:79]
	v_add_u32_e32 v10, 0x40800, v198
	v_add_u32_e32 v11, 0x41000, v198
	v_add_u32_e32 v16, 0x41800, v198
	v_lshlrev_b32_e32 v17, 2, v10
	global_load_dwordx2 v[8:9], v166, s[8:9]
	v_lshlrev_b32_e32 v10, 1, v10
	v_lshlrev_b32_e32 v18, 2, v11
	v_lshlrev_b32_e32 v11, 1, v11
	v_lshlrev_b32_e32 v19, 2, v16
	v_lshlrev_b32_e32 v16, 1, v16
	global_load_dwordx4 v[142:145], v17, s[78:79]
	global_load_dwordx2 v[152:153], v10, s[8:9]
	global_load_dwordx4 v[138:141], v18, s[78:79]
	global_load_dwordx2 v[150:151], v11, s[8:9]
	global_load_dwordx4 v[134:137], v19, s[78:79]
	global_load_dwordx2 v[148:149], v16, s[8:9]
	s_waitcnt vmcnt(8)
	v_fmamk_f32 v10, v130, 0x3a000000, v175
	s_waitcnt vmcnt(7)
	v_mov_b32_e32 v17, v2
	v_rsq_f32_e32 v18, v10
	v_mov_b32_e32 v16, v0
	s_waitcnt vmcnt(6)
	v_lshlrev_b32_e32 v11, 16, v9
	v_mov_b32_e32 v0, v18
	v_mul_f32_e32 v2, v52, v0
	v_mul_f32_e32 v18, v48, v0
	v_mul_f32_e32 v19, v60, v0
	v_mul_f32_e32 v0, v56, v0
	v_mul_f32_e32 v2, 0xbfb8aa3b, v2
	v_mul_f32_e32 v18, 0xbfb8aa3b, v18
	v_mul_f32_e32 v19, 0xbfb8aa3b, v19
	v_mul_f32_e32 v0, 0xbfb8aa3b, v0
	v_exp_f32_e32 v2, v2
	v_exp_f32_e32 v18, v18
	v_exp_f32_e32 v19, v19
	v_exp_f32_e32 v0, v0
	v_add_f32_e32 v2, 1.0, v2
	v_add_f32_e32 v28, 1.0, v18
	v_add_f32_e32 v19, 1.0, v19
	v_add_f32_e32 v0, 1.0, v0
	v_rcp_f32_e32 v18, v2
	v_rcp_f32_e32 v28, v28
	v_rcp_f32_e32 v19, v19
	v_rcp_f32_e32 v29, v0
	v_lshlrev_b32_e32 v10, 16, v8
	v_and_b32_e32 v9, 0xffff0000, v9
	v_and_b32_e32 v8, 0xffff0000, v8
	v_mov_b32_e32 v2, v1
	v_pk_fma_f32 v[154:155], v[18:19], v[10:11], v[16:17]
	v_pk_fma_f32 v[156:157], v[28:29], v[8:9], v[2:3]
	v_mov_b32_e32 v0, v154
	v_mov_b32_e32 v1, v156
	v_mov_b32_e32 v2, v155
	v_mov_b32_e32 v3, v157
	s_and_b64 vcc, exec, s[6:7]
	global_store_dwordx4 v30, v[0:3], s[2:3]
	s_cbranch_vccnz .LBB0_1165
	s_nop 0
	v_pk_mul_f32 v[0:1], v[128:129], v[154:155]
	v_pk_mul_f32 v[2:3], v[170:171], v[156:157]
	v_and_b32_sdwa v10, v1, v177 dst_sel:DWORD dst_unused:UNUSED_PAD src0_sel:WORD_1 src1_sel:DWORD
	v_and_b32_sdwa v11, v0, v177 dst_sel:DWORD dst_unused:UNUSED_PAD src0_sel:WORD_1 src1_sel:DWORD
	v_add3_u32 v0, v0, v11, s48
	v_add3_u32 v1, v1, v10, s48
	v_and_b32_sdwa v10, v3, v177 dst_sel:DWORD dst_unused:UNUSED_PAD src0_sel:WORD_1 src1_sel:DWORD
	v_and_b32_sdwa v11, v2, v177 dst_sel:DWORD dst_unused:UNUSED_PAD src0_sel:WORD_1 src1_sel:DWORD
	v_add3_u32 v3, v3, v10, s48
	v_add3_u32 v2, v2, v11, s48
	v_and_b32_e32 v3, 0xffff0000, v3
	v_and_b32_e32 v2, 0xffff0000, v2
	v_lshl_add_u64 v[8:9], s[90:91], 0, v[166:167]
	v_or_b32_sdwa v1, v3, v1 dst_sel:DWORD dst_unused:UNUSED_PAD src0_sel:DWORD src1_sel:WORD_1
	v_or_b32_sdwa v0, v2, v0 dst_sel:DWORD dst_unused:UNUSED_PAD src0_sel:DWORD src1_sel:WORD_1
	global_store_dwordx2 v[8:9], v[0:1], off

; __device__ __forceinline__ float bflo(u32 w) { return __uint_as_float(w << 16); }
; __device__ __forceinline__ float bfhi(u32 w) { return __uint_as_float(w & 0xffff0000u); }
; __device__ __forceinline__ u32 pack2(float a, float b) { return (u32)f2bf(a) | ((u32)f2bf(b) << 16); }
; __device__ __forceinline__ float sigmoidf_(float x) { return __builtin_amdgcn_rcpf(1.f + __expf(-x)); }
; __device__ __forceinline__ void gemm_tile(const GemmArgs& ga, int wgid, int next_wgid, bool prefetched, u16* shm, unsigned char* ws, int wv_) {
;     ...
;       if (!GATE) { EPI_LOADS(0, 0) }
;       _Pragma("unroll") for (int bb = 0; bb < 8; ++bb) {
;         const int ai = bb >> 2, m = bb & 3;
;         const int cur = GATE ? 0 : (bb & 1);
;         if (GATE) { EPI_LOADS(bb, 0) }
;         else if (bb < 7) { EPI_LOADS(bb + 1, (bb + 1) & 1) }
;         _Pragma("unroll") for (int j = 0; j < 4; ++j) {
;           int row = rbase + ai * HALF + m * 16 + j;
;           unsigned eo = (unsigned)row * (unsigned)D_ + (unsigned)col0;
;           float s = 1.f;
;           if (GATE) s = rsqrtf(sc[j] * (1.f / D_) + 1e-6f);
;           const float a0 = acc[ai][0][m][0][j], a1 = acc[ai][0][m][1][j], a2 = acc[ai][1][m][0][j], a3 = acc[ai][1][m][1][j];
;           float4 xv = xin[cur][j];
;           if (GATE) {
;             xv.x += ga.live * (bflo(pin[j].x) * sigmoidf_(a0 * s));
;             xv.y += ga.live * (bfhi(pin[j].x) * sigmoidf_(a1 * s));
;             xv.z += ga.live * (bflo(pin[j].y) * sigmoidf_(a2 * s));
;             xv.w += ga.live * (bfhi(pin[j].y) * sigmoidf_(a3 * s));
;           } else {
;             const float al = ga.live * ga.alpha;
;             xv.x += al * a0; xv.y += al * a1; xv.z += al * a2; xv.w += al * a3;
;           }
;           *(float4*)(const_cast<char*>(xb) + (size_t)(eo * 4u)) = xv;
;           if (e_gn) *(uint2*)(ob + (size_t)(eo * 2u)) = make_uint2(pack2(xv.x * gn4.x, xv.y * gn4.y), pack2(xv.z * gn4.z, xv.w * gn4.w));
;           float sq = xv.x * xv.x + xv.y * xv.y + xv.z * xv.z + xv.w * xv.w;
;           sq = red16(sq);
.LBB0_1171:
	s_nop 0
	v_pk_mul_f32 v[0:1], v[130:131], v[130:131]
	v_pk_mul_f32 v[2:3], v[132:133], v[132:133]
	s_nop 0
	v_add_f32_e32 v0, v0, v2
	v_add_f32_e32 v0, v1, v0
	v_add_f32_e32 v0, v3, v0
	s_nop 1
	v_add_f32_dpp v0, v0, v0 quad_perm:[1,0,3,2] row_mask:0xf bank_mask:0xf bound_ctrl:1
	s_nop 1
	v_add_f32_dpp v0, v0, v0 quad_perm:[2,3,0,1] row_mask:0xf bank_mask:0xf bound_ctrl:1
	s_nop 1
	v_add_f32_dpp v221, v0, v0 row_half_mirror row_mask:0xf bank_mask:0xf bound_ctrl:1
	s_nop 1
	v_mov_b32_dpp v222, v221 row_mirror row_mask:0xf bank_mask:0xf bound_ctrl:1
	global_load_dwordx4 v[130:133], v[146:147], off offset:576
	v_add_u32_e32 v0, 0x48000, v198
	v_lshlrev_b32_e32 v30, 2, v0
	v_lshlrev_b32_e32 v166, 1, v0
	global_load_dwordx4 v[0:3], v30, s[78:79]
	v_add_u32_e32 v10, 0x48800, v198
	v_add_u32_e32 v11, 0x49000, v198
	v_add_u32_e32 v16, 0x49800, v198
	v_lshlrev_b32_e32 v17, 2, v10
	global_load_dwordx2 v[8:9], v166, s[8:9]
	v_lshlrev_b32_e32 v10, 1, v10
	v_lshlrev_b32_e32 v18, 2, v11
	v_lshlrev_b32_e32 v11, 1, v11
	v_lshlrev_b32_e32 v19, 2, v16
	v_lshlrev_b32_e32 v16, 1, v16
	global_load_dwordx4 v[142:145], v17, s[78:79]
	global_load_dwordx2 v[152:153], v10, s[8:9]
	global_load_dwordx4 v[138:141], v18, s[78:79]
	global_load_dwordx2 v[150:151], v11, s[8:9]
	global_load_dwordx4 v[134:137], v19, s[78:79]
	global_load_dwordx2 v[148:149], v16, s[8:9]
	s_waitcnt vmcnt(8)
	v_fmamk_f32 v10, v130, 0x3a000000, v175
	s_waitcnt vmcnt(7)
	v_mov_b32_e32 v17, v2
	v_rsq_f32_e32 v18, v10
	v_mov_b32_e32 v16, v0
	s_waitcnt vmcnt(6)
	v_lshlrev_b32_e32 v11, 16, v9
	v_mov_b32_e32 v0, v18
	v_mul_f32_e32 v2, v36, v0
	v_mul_f32_e32 v18, v32, v0
	v_mul_f32_e32 v19, v44, v0
	v_mul_f32_e32 v0, v40, v0
	v_mul_f32_e32 v2, 0xbfb8aa3b, v2
	v_mul_f32_e32 v18, 0xbfb8aa3b, v18
	v_mul_f32_e32 v19, 0xbfb8aa3b, v19
	v_mul_f32_e32 v0, 0xbfb8aa3b, v0
	v_exp_f32_e32 v2, v2
	v_exp_f32_e32 v18, v18
	v_exp_f32_e32 v19, v19
	v_exp_f32_e32 v0, v0
	v_add_f32_e32 v2, 1.0, v2
	v_add_f32_e32 v28, 1.0, v18
	v_add_f32_e32 v19, 1.0, v19
	v_add_f32_e32 v0, 1.0, v0
	v_rcp_f32_e32 v18, v2
	v_rcp_f32_e32 v28, v28
	v_rcp_f32_e32 v19, v19
	v_rcp_f32_e32 v29, v0
	v_lshlrev_b32_e32 v10, 16, v8
	v_and_b32_e32 v9, 0xffff0000, v9
	v_and_b32_e32 v8, 0xffff0000, v8
	v_mov_b32_e32 v2, v1
	v_pk_fma_f32 v[154:155], v[18:19], v[10:11], v[16:17]
	v_pk_fma_f32 v[156:157], v[28:29], v[8:9], v[2:3]
	v_mov_b32_e32 v0, v154
	v_mov_b32_e32 v1, v156
	v_mov_b32_e32 v2, v155
	v_mov_b32_e32 v3, v157
	s_and_b64 vcc, exec, s[6:7]
	global_store_dwordx4 v30, v[0:3], s[2:3]
	s_cbranch_vccnz .LBB0_1173
	s_nop 0
	v_pk_mul_f32 v[0:1], v[128:129], v[154:155]
	v_pk_mul_f32 v[2:3], v[170:171], v[156:157]
	v_and_b32_sdwa v10, v1, v177 dst_sel:DWORD dst_unused:UNUSED_PAD src0_sel:WORD_1 src1_sel:DWORD
	v_and_b32_sdwa v11, v0, v177 dst_sel:DWORD dst_unused:UNUSED_PAD src0_sel:WORD_1 src1_sel:DWORD
	v_add3_u32 v0, v0, v11, s48
	v_add3_u32 v1, v1, v10, s48
	v_and_b32_sdwa v10, v3, v177 dst_sel:DWORD dst_unused:UNUSED_PAD src0_sel:WORD_1 src1_sel:DWORD
	v_and_b32_sdwa v11, v2, v177 dst_sel:DWORD dst_unused:UNUSED_PAD src0_sel:WORD_1 src1_sel:DWORD
	v_add3_u32 v3, v3, v10, s48
	v_add3_u32 v2, v2, v11, s48
	v_and_b32_e32 v3, 0xffff0000, v3
	v_and_b32_e32 v2, 0xffff0000, v2
	v_lshl_add_u64 v[8:9], s[90:91], 0, v[166:167]
	v_or_b32_sdwa v1, v3, v1 dst_sel:DWORD dst_unused:UNUSED_PAD src0_sel:DWORD src1_sel:WORD_1
	v_or_b32_sdwa v0, v2, v0 dst_sel:DWORD dst_unused:UNUSED_PAD src0_sel:DWORD src1_sel:WORD_1
	global_store_dwordx2 v[8:9], v[0:1], off

; __device__ __forceinline__ float bflo(u32 w) { return __uint_as_float(w << 16); }
; __device__ __forceinline__ float bfhi(u32 w) { return __uint_as_float(w & 0xffff0000u); }
; __device__ __forceinline__ u32 pack2(float a, float b) { return (u32)f2bf(a) | ((u32)f2bf(b) << 16); }
; __device__ __forceinline__ float sigmoidf_(float x) { return __builtin_amdgcn_rcpf(1.f + __expf(-x)); }
; __device__ __forceinline__ void gemm_tile(const GemmArgs& ga, int wgid, int next_wgid, bool prefetched, u16* shm, unsigned char* ws, int wv_) {
;     ...
;       if (!GATE) { EPI_LOADS(0, 0) }
;       _Pragma("unroll") for (int bb = 0; bb < 8; ++bb) {
;         const int ai = bb >> 2, m = bb & 3;
;         const int cur = GATE ? 0 : (bb & 1);
;         if (GATE) { EPI_LOADS(bb, 0) }
;         else if (bb < 7) { EPI_LOADS(bb + 1, (bb + 1) & 1) }
;         _Pragma("unroll") for (int j = 0; j < 4; ++j) {
;           int row = rbase + ai * HALF + m * 16 + j;
;           unsigned eo = (unsigned)row * (unsigned)D_ + (unsigned)col0;
;           float s = 1.f;
;           if (GATE) s = rsqrtf(sc[j] * (1.f / D_) + 1e-6f);
;           const float a0 = acc[ai][0][m][0][j], a1 = acc[ai][0][m][1][j], a2 = acc[ai][1][m][0][j], a3 = acc[ai][1][m][1][j];
;           float4 xv = xin[cur][j];
;           if (GATE) {
;             xv.x += ga.live * (bflo(pin[j].x) * sigmoidf_(a0 * s));
;             xv.y += ga.live * (bfhi(pin[j].x) * sigmoidf_(a1 * s));
;             xv.z += ga.live * (bflo(pin[j].y) * sigmoidf_(a2 * s));
;             xv.w += ga.live * (bfhi(pin[j].y) * sigmoidf_(a3 * s));
;           } else {
;             const float al = ga.live * ga.alpha;
;             xv.x += al * a0; xv.y += al * a1; xv.z += al * a2; xv.w += al * a3;
;           }
;           *(float4*)(const_cast<char*>(xb) + (size_t)(eo * 4u)) = xv;
;           if (e_gn) *(uint2*)(ob + (size_t)(eo * 2u)) = make_uint2(pack2(xv.x * gn4.x, xv.y * gn4.y), pack2(xv.z * gn4.z, xv.w * gn4.w));
;           float sq = xv.x * xv.x + xv.y * xv.y + xv.z * xv.z + xv.w * xv.w;
;           sq = red16(sq);
.LBB0_1179:
	s_nop 0
	v_pk_mul_f32 v[0:1], v[130:131], v[130:131]
	v_pk_mul_f32 v[2:3], v[132:133], v[132:133]
	s_nop 0
	v_add_f32_e32 v0, v0, v2
	v_add_f32_e32 v0, v1, v0
	v_add_f32_e32 v0, v3, v0
	s_nop 1
	v_add_f32_dpp v0, v0, v0 quad_perm:[1,0,3,2] row_mask:0xf bank_mask:0xf bound_ctrl:1
	s_nop 1
	v_add_f32_dpp v0, v0, v0 quad_perm:[2,3,0,1] row_mask:0xf bank_mask:0xf bound_ctrl:1
	s_nop 1
	v_add_f32_dpp v229, v0, v0 row_half_mirror row_mask:0xf bank_mask:0xf bound_ctrl:1
	s_nop 1
	v_mov_b32_dpp v230, v229 row_mirror row_mask:0xf bank_mask:0xf bound_ctrl:1
	global_load_dwordx4 v[130:133], v[146:147], off offset:640
	v_add_u32_e32 v0, 0x50000, v198
	v_lshlrev_b32_e32 v30, 2, v0
	v_lshlrev_b32_e32 v166, 1, v0
	global_load_dwordx4 v[0:3], v30, s[78:79]
	v_add_u32_e32 v10, 0x50800, v198
	v_add_u32_e32 v11, 0x51000, v198
	v_add_u32_e32 v16, 0x51800, v198
	v_lshlrev_b32_e32 v17, 2, v10
	global_load_dwordx2 v[8:9], v166, s[8:9]
	v_lshlrev_b32_e32 v10, 1, v10
	v_lshlrev_b32_e32 v18, 2, v11
	v_lshlrev_b32_e32 v11, 1, v11
	v_lshlrev_b32_e32 v19, 2, v16
	v_lshlrev_b32_e32 v16, 1, v16
	global_load_dwordx4 v[142:145], v17, s[78:79]
	global_load_dwordx2 v[152:153], v10, s[8:9]
	global_load_dwordx4 v[138:141], v18, s[78:79]
	global_load_dwordx2 v[150:151], v11, s[8:9]
	global_load_dwordx4 v[134:137], v19, s[78:79]
	global_load_dwordx2 v[148:149], v16, s[8:9]
	s_waitcnt vmcnt(8)
	v_fmamk_f32 v10, v130, 0x3a000000, v175
	s_waitcnt vmcnt(7)
	v_mov_b32_e32 v17, v2
	v_rsq_f32_e32 v18, v10
	v_mov_b32_e32 v16, v0
	s_waitcnt vmcnt(6)
	v_lshlrev_b32_e32 v11, 16, v9
	v_mov_b32_e32 v0, v18
	v_mul_f32_e32 v2, v20, v0
	v_mul_f32_e32 v18, v240, v0
	v_mul_f32_e32 v19, v244, v0
	v_mul_f32_e32 v0, v24, v0
	v_mul_f32_e32 v2, 0xbfb8aa3b, v2
	v_mul_f32_e32 v18, 0xbfb8aa3b, v18
	v_mul_f32_e32 v19, 0xbfb8aa3b, v19
	v_mul_f32_e32 v0, 0xbfb8aa3b, v0
	v_exp_f32_e32 v2, v2
	v_exp_f32_e32 v18, v18
	v_exp_f32_e32 v19, v19
	v_exp_f32_e32 v0, v0
	v_add_f32_e32 v2, 1.0, v2
	v_add_f32_e32 v28, 1.0, v18
	v_add_f32_e32 v19, 1.0, v19
	v_add_f32_e32 v0, 1.0, v0
	v_rcp_f32_e32 v18, v2
	v_rcp_f32_e32 v28, v28
	v_rcp_f32_e32 v19, v19
	v_rcp_f32_e32 v29, v0
	v_lshlrev_b32_e32 v10, 16, v8
	v_and_b32_e32 v9, 0xffff0000, v9
	v_and_b32_e32 v8, 0xffff0000, v8
	v_mov_b32_e32 v2, v1
	v_pk_fma_f32 v[154:155], v[18:19], v[10:11], v[16:17]
	v_pk_fma_f32 v[156:157], v[28:29], v[8:9], v[2:3]
	v_mov_b32_e32 v0, v154
	v_mov_b32_e32 v1, v156
	v_mov_b32_e32 v2, v155
	v_mov_b32_e32 v3, v157
	s_and_b64 vcc, exec, s[6:7]
	global_store_dwordx4 v30, v[0:3], s[2:3]
	s_cbranch_vccnz .LBB0_1181
	s_nop 0
	v_pk_mul_f32 v[0:1], v[128:129], v[154:155]
	v_pk_mul_f32 v[2:3], v[170:171], v[156:157]
	v_and_b32_sdwa v10, v1, v177 dst_sel:DWORD dst_unused:UNUSED_PAD src0_sel:WORD_1 src1_sel:DWORD
	v_and_b32_sdwa v11, v0, v177 dst_sel:DWORD dst_unused:UNUSED_PAD src0_sel:WORD_1 src1_sel:DWORD
	v_add3_u32 v0, v0, v11, s48
	v_add3_u32 v1, v1, v10, s48
	v_and_b32_sdwa v10, v3, v177 dst_sel:DWORD dst_unused:UNUSED_PAD src0_sel:WORD_1 src1_sel:DWORD
	v_and_b32_sdwa v11, v2, v177 dst_sel:DWORD dst_unused:UNUSED_PAD src0_sel:WORD_1 src1_sel:DWORD
	v_add3_u32 v3, v3, v10, s48
	v_add3_u32 v2, v2, v11, s48
	v_and_b32_e32 v3, 0xffff0000, v3
	v_and_b32_e32 v2, 0xffff0000, v2
	v_lshl_add_u64 v[8:9], s[90:91], 0, v[166:167]
	v_or_b32_sdwa v1, v3, v1 dst_sel:DWORD dst_unused:UNUSED_PAD src0_sel:DWORD src1_sel:WORD_1
	v_or_b32_sdwa v0, v2, v0 dst_sel:DWORD dst_unused:UNUSED_PAD src0_sel:DWORD src1_sel:WORD_1
	global_store_dwordx2 v[8:9], v[0:1], off

; __device__ __forceinline__ float bflo(u32 w) { return __uint_as_float(w << 16); }
; __device__ __forceinline__ float bfhi(u32 w) { return __uint_as_float(w & 0xffff0000u); }
; __device__ __forceinline__ u32 pack2(float a, float b) { return (u32)f2bf(a) | ((u32)f2bf(b) << 16); }
; __device__ __forceinline__ float sigmoidf_(float x) { return __builtin_amdgcn_rcpf(1.f + __expf(-x)); }
; __device__ __forceinline__ void gemm_tile(const GemmArgs& ga, int wgid, int next_wgid, bool prefetched, u16* shm, unsigned char* ws, int wv_) {
;     ...
;       if (!GATE) { EPI_LOADS(0, 0) }
;       _Pragma("unroll") for (int bb = 0; bb < 8; ++bb) {
;         const int ai = bb >> 2, m = bb & 3;
;         const int cur = GATE ? 0 : (bb & 1);
;         if (GATE) { EPI_LOADS(bb, 0) }
;         else if (bb < 7) { EPI_LOADS(bb + 1, (bb + 1) & 1) }
;         _Pragma("unroll") for (int j = 0; j < 4; ++j) {
;           int row = rbase + ai * HALF + m * 16 + j;
;           unsigned eo = (unsigned)row * (unsigned)D_ + (unsigned)col0;
;           float s = 1.f;
;           if (GATE) s = rsqrtf(sc[j] * (1.f / D_) + 1e-6f);
;           const float a0 = acc[ai][0][m][0][j], a1 = acc[ai][0][m][1][j], a2 = acc[ai][1][m][0][j], a3 = acc[ai][1][m][1][j];
;           float4 xv = xin[cur][j];
;           if (GATE) {
;             xv.x += ga.live * (bflo(pin[j].x) * sigmoidf_(a0 * s));
;             xv.y += ga.live * (bfhi(pin[j].x) * sigmoidf_(a1 * s));
;             xv.z += ga.live * (bflo(pin[j].y) * sigmoidf_(a2 * s));
;             xv.w += ga.live * (bfhi(pin[j].y) * sigmoidf_(a3 * s));
;           } else {
;             const float al = ga.live * ga.alpha;
;             xv.x += al * a0; xv.y += al * a1; xv.z += al * a2; xv.w += al * a3;
;           }
;           *(float4*)(const_cast<char*>(xb) + (size_t)(eo * 4u)) = xv;
;           if (e_gn) *(uint2*)(ob + (size_t)(eo * 2u)) = make_uint2(pack2(xv.x * gn4.x, xv.y * gn4.y), pack2(xv.z * gn4.z, xv.w * gn4.w));
;           float sq = xv.x * xv.x + xv.y * xv.y + xv.z * xv.z + xv.w * xv.w;
;           sq = red16(sq);
.LBB0_1187:
	s_nop 0
	v_pk_mul_f32 v[0:1], v[130:131], v[130:131]
	v_pk_mul_f32 v[2:3], v[132:133], v[132:133]
	s_mov_b64 s[60:61], s[88:89]
	v_add_f32_e32 v0, v0, v2
	v_add_f32_e32 v0, v1, v0
	v_add_f32_e32 v0, v3, v0
	s_nop 1
	v_add_f32_dpp v0, v0, v0 quad_perm:[1,0,3,2] row_mask:0xf bank_mask:0xf bound_ctrl:1
	s_nop 1
	v_add_f32_dpp v0, v0, v0 quad_perm:[2,3,0,1] row_mask:0xf bank_mask:0xf bound_ctrl:1
	s_nop 1
	v_add_f32_dpp v235, v0, v0 row_half_mirror row_mask:0xf bank_mask:0xf bound_ctrl:1
	s_nop 1
	v_mov_b32_dpp v236, v235 row_mirror row_mask:0xf bank_mask:0xf bound_ctrl:1
	global_load_dwordx4 v[130:133], v[146:147], off offset:704
	v_add_u32_e32 v0, 0x58000, v198
	v_lshlrev_b32_e32 v30, 2, v0
	v_lshlrev_b32_e32 v166, 1, v0
	global_load_dwordx4 v[0:3], v30, s[78:79]
	v_add_u32_e32 v10, 0x58800, v198
	v_add_u32_e32 v11, 0x59000, v198
	v_add_u32_e32 v16, 0x59800, v198
	v_lshlrev_b32_e32 v17, 2, v10
	global_load_dwordx2 v[8:9], v166, s[8:9]
	v_lshlrev_b32_e32 v10, 1, v10
	v_lshlrev_b32_e32 v18, 2, v11
	v_lshlrev_b32_e32 v11, 1, v11
	v_lshlrev_b32_e32 v19, 2, v16
	v_lshlrev_b32_e32 v16, 1, v16
	global_load_dwordx4 v[142:145], v17, s[78:79]
	global_load_dwordx2 v[150:151], v10, s[8:9]
	global_load_dwordx4 v[138:141], v18, s[78:79]
	global_load_dwordx2 v[148:149], v11, s[8:9]
	global_load_dwordx4 v[134:137], v19, s[78:79]
	global_load_dwordx2 v[146:147], v16, s[8:9]
	s_waitcnt vmcnt(8)
	v_fmamk_f32 v10, v130, 0x3a000000, v175
	s_waitcnt vmcnt(7)
	v_mov_b32_e32 v17, v2
	v_rsq_f32_e32 v18, v10
	v_mov_b32_e32 v16, v0
	s_waitcnt vmcnt(6)
	v_lshlrev_b32_e32 v11, 16, v9
	v_mov_b32_e32 v0, v18
	v_mul_f32_e32 v2, v204, v0
	v_mul_f32_e32 v18, v182, v0
	v_mul_f32_e32 v19, v12, v0
	v_mul_f32_e32 v0, v4, v0
	v_mul_f32_e32 v2, 0xbfb8aa3b, v2
	v_mul_f32_e32 v18, 0xbfb8aa3b, v18
	v_mul_f32_e32 v19, 0xbfb8aa3b, v19
	v_mul_f32_e32 v0, 0xbfb8aa3b, v0
	v_exp_f32_e32 v2, v2
	v_exp_f32_e32 v18, v18
	v_exp_f32_e32 v19, v19
	v_exp_f32_e32 v0, v0
	v_add_f32_e32 v2, 1.0, v2
	v_add_f32_e32 v28, 1.0, v18
	v_add_f32_e32 v19, 1.0, v19
	v_add_f32_e32 v0, 1.0, v0
	v_rcp_f32_e32 v18, v2
	v_rcp_f32_e32 v28, v28
	v_rcp_f32_e32 v19, v19
	v_rcp_f32_e32 v29, v0
	v_lshlrev_b32_e32 v10, 16, v8
	v_and_b32_e32 v9, 0xffff0000, v9
	v_and_b32_e32 v8, 0xffff0000, v8
	v_mov_b32_e32 v2, v1
	v_pk_fma_f32 v[152:153], v[18:19], v[10:11], v[16:17]
	v_pk_fma_f32 v[154:155], v[28:29], v[8:9], v[2:3]
	v_mov_b32_e32 v0, v152
	v_mov_b32_e32 v1, v154
	v_mov_b32_e32 v2, v153
	v_mov_b32_e32 v3, v155
	s_and_b64 vcc, exec, s[6:7]
	global_store_dwordx4 v30, v[0:3], s[2:3]
	s_cbranch_vccnz .LBB0_1189
	s_nop 0
	v_pk_mul_f32 v[0:1], v[128:129], v[152:153]
	v_pk_mul_f32 v[2:3], v[170:171], v[154:155]
	v_and_b32_sdwa v10, v1, v177 dst_sel:DWORD dst_unused:UNUSED_PAD src0_sel:WORD_1 src1_sel:DWORD
	v_and_b32_sdwa v11, v0, v177 dst_sel:DWORD dst_unused:UNUSED_PAD src0_sel:WORD_1 src1_sel:DWORD
	v_add3_u32 v0, v0, v11, s48
	v_add3_u32 v1, v1, v10, s48
	v_and_b32_sdwa v10, v3, v177 dst_sel:DWORD dst_unused:UNUSED_PAD src0_sel:WORD_1 src1_sel:DWORD
	v_and_b32_sdwa v11, v2, v177 dst_sel:DWORD dst_unused:UNUSED_PAD src0_sel:WORD_1 src1_sel:DWORD
	v_add3_u32 v3, v3, v10, s48
	v_add3_u32 v2, v2, v11, s48
	v_and_b32_e32 v3, 0xffff0000, v3
	v_and_b32_e32 v2, 0xffff0000, v2
	v_lshl_add_u64 v[8:9], s[90:91], 0, v[166:167]
	v_or_b32_sdwa v1, v3, v1 dst_sel:DWORD dst_unused:UNUSED_PAD src0_sel:DWORD src1_sel:WORD_1
	v_or_b32_sdwa v0, v2, v0 dst_sel:DWORD dst_unused:UNUSED_PAD src0_sel:DWORD src1_sel:WORD_1
	global_store_dwordx2 v[8:9], v[0:1], off

; __device__ __forceinline__ u32 pack2(float a, float b) { return (u32)f2bf(a) | ((u32)f2bf(b) << 16); }
; __device__ __forceinline__ float sigmoidf_(float x) { return __builtin_amdgcn_rcpf(1.f + __expf(-x)); }
; __device__ __forceinline__ void gemm_tile(const GemmArgs& ga, int wgid, int next_wgid, bool prefetched, u16* shm, unsigned char* ws, int wv_) {
;     ...
;   if (epi == EPI_SWIGLU) {
;     const int oc = pn * HALF + (wc * 16 + fr) * 2;
;     float sc[2][4][4];
;     _Pragma("unroll") for (int ai = 0; ai < 2; ++ai)
;       _Pragma("unroll") for (int m = 0; m < 4; ++m)
;         _Pragma("unroll") for (int j = 0; j < 4; ++j) sc[ai][m][j] = e_ss[rbase + ai * HALF + m * 16 + j];
;     _Pragma("unroll") for (int ai = 0; ai < 2; ++ai)
;       _Pragma("unroll") for (int m = 0; m < 4; ++m)
;         _Pragma("unroll") for (int j = 0; j < 4; ++j) {
;           int row = rbase + ai * HALF + m * 16 + j;
;           float s = rsqrtf(sc[ai][m][j] * (1.f / D_) + 1e-6f);
;           float h2[2];
;           _Pragma("unroll") for (int n = 0; n < 2; ++n) {
;             float a1 = acc[ai][0][m][n][j] * s, a3 = acc[ai][1][m][n][j] * s;
;             h2[n] = a1 * sigmoidf_(a1) * a3;
;           }
;           *(u32*)(e_outb + (size_t)row * F_ + oc) = pack2(h2[0], h2[1]);
;         }
.LBB0_1263:
	s_lshl_b32 s2, s87, 7
	v_ashrrev_i32_e32 v169, 31, v168
	v_lshl_or_b32 v0, v187, 1, s2
	v_lshl_add_u64 v[132:133], v[168:169], 2, s[68:69]
	v_ashrrev_i32_e32 v1, 31, v0
	v_lshl_add_u64 v[128:129], v[0:1], 1, s[90:91]
	global_load_dwordx4 v[0:3], v[132:133], off
	s_movk_i32 s8, 0x2c00
	v_mad_i64_i32 v[134:135], s[2:3], v168, s8, v[128:129]
	s_mov_b32 s2, 0x358637bd
	s_nop 0
	v_mov_b64_e32 v[130:131], s[2:3]
	s_mov_b32 s12, 0x3a000000
	v_or_b32_e32 v8, 1, v168
	v_or_b32_e32 v9, 2, v168
	v_or_b32_e32 v10, 3, v168
	v_or_b32_e32 v11, 16, v168
	v_or_b32_e32 v162, 17, v168
	v_or_b32_e32 v161, 18, v168
	v_or_b32_e32 v160, 19, v168
	v_or_b32_e32 v159, 32, v168
	v_or_b32_e32 v158, 33, v168
	v_or_b32_e32 v157, 34, v168
	v_or_b32_e32 v156, 35, v168
	v_or_b32_e32 v155, 48, v168
	v_or_b32_e32 v154, 49, v168
	v_or_b32_e32 v153, 50, v168
	v_or_b32_e32 v152, 51, v168
	v_add_u32_e32 v151, 0x80, v168
	v_add_u32_e32 v150, 0x81, v168
	v_add_u32_e32 v149, 0x82, v168
	v_add_u32_e32 v148, 0x83, v168
	v_add_u32_e32 v147, 0x90, v168
	v_add_u32_e32 v146, 0x91, v168
	v_add_u32_e32 v145, 0x92, v168
	v_add_u32_e32 v144, 0x93, v168
	v_add_u32_e32 v143, 0xa0, v168
	v_add_u32_e32 v142, 0xa1, v168
	v_add_u32_e32 v141, 0xa2, v168
	v_add_u32_e32 v140, 0xa3, v168
	v_add_u32_e32 v139, 0xb0, v168
	v_add_u32_e32 v138, 0xb1, v168
	v_add_u32_e32 v137, 0xb2, v168
	v_add_u32_e32 v136, 0xb3, v168
	s_waitcnt vmcnt(0)
	v_pk_fma_f32 v[0:1], v[0:1], s[12:13], v[130:131] op_sel_hi:[1,0,0]
	s_nop 0
	v_pk_fma_f32 v[2:3], v[2:3], s[12:13], v[130:131] op_sel_hi:[1,0,0]
	v_rsq_f32_e32 v0, v0
	s_nop 0
	v_mul_f32_e32 v16, v116, v0
	v_mul_f32_e32 v18, 0xbfb8aa3b, v16
	v_exp_f32_e32 v18, v18
	v_mul_f32_e32 v17, v124, v0
	v_add_f32_e32 v18, 1.0, v18
	v_rcp_f32_e32 v18, v18
	s_nop 0
	v_mul_f32_e32 v16, v16, v18
	v_mul_f32_e32 v16, v17, v16
	v_mul_f32_e32 v17, v112, v0
	v_mul_f32_e32 v18, 0xbfb8aa3b, v17
	v_exp_f32_e32 v18, v18
	v_mul_f32_e32 v0, v120, v0
	v_add_f32_e32 v18, 1.0, v18
	v_rcp_f32_e32 v18, v18
	s_nop 0
	v_mul_f32_e32 v17, v17, v18
	v_mul_f32_e32 v0, v0, v17
	v_bfe_u32 v17, v16, 16, 1
	v_add3_u32 v16, v16, v17, s48
	v_bfe_u32 v17, v0, 16, 1
	v_lshrrev_b32_e32 v16, 16, v16
	v_add3_u32 v0, v0, v17, s48
	v_and_or_b32 v0, v0, s97, v16
	global_store_dword v[134:135], v0, off
	v_rsq_f32_e32 v0, v1
	s_nop 0
	v_mul_f32_e32 v1, v117, v0
	v_mul_f32_e32 v17, 0xbfb8aa3b, v1
	v_exp_f32_e32 v17, v17
	v_mul_f32_e32 v16, v125, v0
	v_mad_i64_i32 v[116:117], s[2:3], v11, s8, v[128:129]
	v_add_f32_e32 v17, 1.0, v17
	v_rcp_f32_e32 v17, v17
	s_nop 0
	v_mul_f32_e32 v1, v1, v17
	v_mul_f32_e32 v1, v16, v1
	v_mul_f32_e32 v16, v113, v0
	v_mul_f32_e32 v17, 0xbfb8aa3b, v16
	v_exp_f32_e32 v17, v17
	v_mul_f32_e32 v0, v121, v0
	v_add_f32_e32 v17, 1.0, v17
	v_rcp_f32_e32 v17, v17
	s_nop 0
	v_mul_f32_e32 v16, v16, v17
	v_mul_f32_e32 v0, v0, v16
	v_bfe_u32 v16, v1, 16, 1
	v_add3_u32 v1, v1, v16, s48
	v_bfe_u32 v16, v0, 16, 1
	v_lshrrev_b32_e32 v1, 16, v1
	v_add3_u32 v0, v0, v16, s48
	v_and_or_b32 v16, v0, s97, v1
	v_mad_i64_i32 v[0:1], s[2:3], v8, s8, v[128:129]
	v_rsq_f32_e32 v2, v2
	global_store_dword v[0:1], v16, off
	v_mad_i64_i32 v[0:1], s[2:3], v9, s8, v[128:129]
	v_mul_f32_e32 v8, v118, v2
	v_mul_f32_e32 v16, 0xbfb8aa3b, v8
	v_exp_f32_e32 v16, v16
	v_mul_f32_e32 v9, v126, v2
	v_add_f32_e32 v16, 1.0, v16
	v_rcp_f32_e32 v16, v16
	s_nop 0
	v_mul_f32_e32 v8, v8, v16
	v_mul_f32_e32 v8, v9, v8
	v_mul_f32_e32 v9, v114, v2
	v_mul_f32_e32 v16, 0xbfb8aa3b, v9
	v_exp_f32_e32 v16, v16
	v_mul_f32_e32 v2, v122, v2
	v_add_f32_e32 v16, 1.0, v16
	v_rcp_f32_e32 v16, v16
	s_nop 0
	v_mul_f32_e32 v9, v9, v16
	v_mul_f32_e32 v2, v2, v9
	v_bfe_u32 v9, v8, 16, 1
	v_add3_u32 v8, v8, v9, s48
	v_bfe_u32 v9, v2, 16, 1
	v_lshrrev_b32_e32 v8, 16, v8
	v_add3_u32 v2, v2, v9, s48
	v_and_or_b32 v2, v2, s97, v8
	global_store_dword v[0:1], v2, off
	v_rsq_f32_e32 v0, v3
	global_load_dwordx4 v[16:19], v[132:133], off offset:704
	v_mul_f32_e32 v1, v119, v0
	v_mul_f32_e32 v3, 0xbfb8aa3b, v1
	v_exp_f32_e32 v3, v3
	v_mul_f32_e32 v2, v127, v0
	v_add_f32_e32 v3, 1.0, v3
	v_rcp_f32_e32 v3, v3
	s_nop 0
	v_mul_f32_e32 v1, v1, v3
	v_mul_f32_e32 v1, v2, v1
	v_mul_f32_e32 v2, v115, v0
	global_load_dwordx4 v[112:115], v[132:133], off offset:64
	v_mul_f32_e32 v3, 0xbfb8aa3b, v2
	v_exp_f32_e32 v3, v3
	v_mul_f32_e32 v0, v123, v0
	v_add_f32_e32 v3, 1.0, v3
	v_rcp_f32_e32 v3, v3
	s_nop 0
	v_mul_f32_e32 v2, v2, v3
	v_mul_f32_e32 v0, v0, v2
	v_bfe_u32 v2, v1, 16, 1
	v_add3_u32 v1, v1, v2, s48
	v_bfe_u32 v2, v0, 16, 1
	v_lshrrev_b32_e32 v1, 16, v1
	v_add3_u32 v0, v0, v2, s48
	v_and_or_b32 v2, v0, s97, v1
	v_mad_i64_i32 v[0:1], s[2:3], v10, s8, v[128:129]
	global_store_dword v[0:1], v2, off
	s_waitcnt vmcnt(0)
; __device__ __forceinline__ u32 pack2(float a, float b) { return (u32)f2bf(a) | ((u32)f2bf(b) << 16); }
; __device__ __forceinline__ float sigmoidf_(float x) { return __builtin_amdgcn_rcpf(1.f + __expf(-x)); }
; __device__ __forceinline__ void gemm_tile(const GemmArgs& ga, int wgid, int next_wgid, bool prefetched, u16* shm, unsigned char* ws, int wv_) {
;     ...
;   if (epi == EPI_SWIGLU) {
;     const int oc = pn * HALF + (wc * 16 + fr) * 2;
;     float sc[2][4][4];
;     _Pragma("unroll") for (int ai = 0; ai < 2; ++ai)
;       _Pragma("unroll") for (int m = 0; m < 4; ++m)
;         _Pragma("unroll") for (int j = 0; j < 4; ++j) sc[ai][m][j] = e_ss[rbase + ai * HALF + m * 16 + j];
;     _Pragma("unroll") for (int ai = 0; ai < 2; ++ai)
;       _Pragma("unroll") for (int m = 0; m < 4; ++m)
;         _Pragma("unroll") for (int j = 0; j < 4; ++j) {
;           int row = rbase + ai * HALF + m * 16 + j;
;           float s = rsqrtf(sc[ai][m][j] * (1.f / D_) + 1e-6f);
;           float h2[2];
;           _Pragma("unroll") for (int n = 0; n < 2; ++n) {
;             float a1 = acc[ai][0][m][n][j] * s, a3 = acc[ai][1][m][n][j] * s;
;             h2[n] = a1 * sigmoidf_(a1) * a3;
;           }
;           *(u32*)(e_outb + (size_t)row * F_ + oc) = pack2(h2[0], h2[1]);
;         }
	v_pk_fma_f32 v[0:1], v[112:113], s[12:13], v[130:131] op_sel_hi:[1,0,0]
	s_nop 0
	s_nop 0
	v_rsq_f32_e32 v0, v0
	s_nop 0
	v_mul_f32_e32 v2, v100, v0
	v_mul_f32_e32 v8, 0xbfb8aa3b, v2
	v_exp_f32_e32 v8, v8
	v_mul_f32_e32 v3, v108, v0
	v_add_f32_e32 v8, 1.0, v8
	v_rcp_f32_e32 v8, v8
	s_nop 0
	v_mul_f32_e32 v2, v2, v8
	v_mul_f32_e32 v2, v3, v2
	v_mul_f32_e32 v3, v96, v0
	v_mul_f32_e32 v8, 0xbfb8aa3b, v3
	v_exp_f32_e32 v8, v8
	v_mul_f32_e32 v0, v104, v0
	v_add_f32_e32 v8, 1.0, v8
	v_rcp_f32_e32 v8, v8
	s_nop 0
	v_mul_f32_e32 v3, v3, v8
	v_mul_f32_e32 v0, v0, v3
	v_bfe_u32 v3, v2, 16, 1
	v_add3_u32 v2, v2, v3, s48
	v_bfe_u32 v3, v0, 16, 1
	v_lshrrev_b32_e32 v2, 16, v2
	v_add3_u32 v0, v0, v3, s48
	v_and_or_b32 v0, v0, s97, v2
	global_store_dword v[116:117], v0, off
	v_rsq_f32_e32 v0, v1
	s_nop 0
	v_mul_f32_e32 v1, v101, v0
	v_mul_f32_e32 v3, 0xbfb8aa3b, v1
	v_exp_f32_e32 v3, v3
	v_mul_f32_e32 v2, v109, v0
	v_add_f32_e32 v3, 1.0, v3
	v_rcp_f32_e32 v3, v3
	s_nop 0
	v_mul_f32_e32 v1, v1, v3
	v_mul_f32_e32 v1, v2, v1
	v_mul_f32_e32 v2, v97, v0
	v_mul_f32_e32 v3, 0xbfb8aa3b, v2
	v_exp_f32_e32 v3, v3
	v_mul_f32_e32 v0, v105, v0
	v_mad_i64_i32 v[96:97], s[2:3], v159, s8, v[128:129]
	v_add_f32_e32 v3, 1.0, v3
	v_rcp_f32_e32 v3, v3
	s_nop 0
	v_mul_f32_e32 v2, v2, v3
	v_mul_f32_e32 v0, v0, v2
	v_bfe_u32 v2, v1, 16, 1
	v_add3_u32 v1, v1, v2, s48
	v_bfe_u32 v2, v0, 16, 1
	v_lshrrev_b32_e32 v1, 16, v1
	v_add3_u32 v0, v0, v2, s48
	v_and_or_b32 v2, v0, s97, v1
	v_mad_i64_i32 v[0:1], s[2:3], v162, s8, v[128:129]
	global_store_dword v[0:1], v2, off
	v_pk_fma_f32 v[2:3], v[114:115], s[12:13], v[130:131] op_sel_hi:[1,0,0]
	v_mad_i64_i32 v[0:1], s[2:3], v161, s8, v[128:129]
	s_nop 0
	v_rsq_f32_e32 v2, v2
	s_nop 0
	v_mul_f32_e32 v8, v102, v2
	v_mul_f32_e32 v10, 0xbfb8aa3b, v8
	v_exp_f32_e32 v10, v10
	v_mul_f32_e32 v9, v110, v2
	v_add_f32_e32 v10, 1.0, v10
	v_rcp_f32_e32 v10, v10
	s_nop 0
	v_mul_f32_e32 v8, v8, v10
	v_mul_f32_e32 v8, v9, v8
	v_mul_f32_e32 v9, v98, v2
	v_mul_f32_e32 v10, 0xbfb8aa3b, v9
	v_exp_f32_e32 v10, v10
	v_mul_f32_e32 v2, v106, v2
	v_add_f32_e32 v10, 1.0, v10
	v_rcp_f32_e32 v10, v10
	s_nop 0
	v_mul_f32_e32 v9, v9, v10
	v_mul_f32_e32 v2, v2, v9
	v_bfe_u32 v9, v8, 16, 1
	v_add3_u32 v8, v8, v9, s48
	v_bfe_u32 v9, v2, 16, 1
	v_lshrrev_b32_e32 v8, 16, v8
	v_add3_u32 v2, v2, v9, s48
	v_and_or_b32 v2, v2, s97, v8
	global_store_dword v[0:1], v2, off
	v_rsq_f32_e32 v0, v3
	s_nop 0
	v_mul_f32_e32 v1, v103, v0
	v_mul_f32_e32 v3, 0xbfb8aa3b, v1
	v_exp_f32_e32 v3, v3
	v_mul_f32_e32 v2, v111, v0
	v_add_f32_e32 v3, 1.0, v3
	v_rcp_f32_e32 v3, v3
	s_nop 0
	v_mul_f32_e32 v1, v1, v3
	v_mul_f32_e32 v1, v2, v1
	v_mul_f32_e32 v2, v99, v0
	v_mul_f32_e32 v3, 0xbfb8aa3b, v2
	v_exp_f32_e32 v3, v3
	v_mul_f32_e32 v0, v107, v0
	v_add_f32_e32 v3, 1.0, v3
	v_rcp_f32_e32 v3, v3
	s_nop 0
	v_mul_f32_e32 v2, v2, v3
	v_mul_f32_e32 v0, v0, v2
	v_bfe_u32 v2, v1, 16, 1
	v_add3_u32 v1, v1, v2, s48
	v_bfe_u32 v2, v0, 16, 1
	v_lshrrev_b32_e32 v1, 16, v1
	v_add3_u32 v0, v0, v2, s48
	v_and_or_b32 v2, v0, s97, v1
	v_mad_i64_i32 v[0:1], s[2:3], v160, s8, v[128:129]
	global_store_dword v[0:1], v2, off
	global_load_dwordx4 v[0:3], v[132:133], off offset:128
	s_waitcnt vmcnt(0)
	v_pk_fma_f32 v[0:1], v[0:1], s[12:13], v[130:131] op_sel_hi:[1,0,0]
	s_nop 0
	v_pk_fma_f32 v[2:3], v[2:3], s[12:13], v[130:131] op_sel_hi:[1,0,0]
	v_rsq_f32_e32 v0, v0
	s_nop 0
	v_mul_f32_e32 v8, v84, v0
	v_mul_f32_e32 v10, 0xbfb8aa3b, v8
	v_exp_f32_e32 v10, v10
	v_mul_f32_e32 v9, v92, v0
	v_add_f32_e32 v10, 1.0, v10
	v_rcp_f32_e32 v10, v10
	s_nop 0
	v_mul_f32_e32 v8, v8, v10
	v_mul_f32_e32 v8, v9, v8
	v_mul_f32_e32 v9, v80, v0
	v_mul_f32_e32 v10, 0xbfb8aa3b, v9
	v_exp_f32_e32 v10, v10
	v_mul_f32_e32 v0, v88, v0
	v_add_f32_e32 v10, 1.0, v10
	v_rcp_f32_e32 v10, v10
	s_nop 0
	v_mul_f32_e32 v9, v9, v10
	v_mul_f32_e32 v0, v0, v9
	v_bfe_u32 v9, v8, 16, 1
	v_add3_u32 v8, v8, v9, s48
	v_bfe_u32 v9, v0, 16, 1
	v_lshrrev_b32_e32 v8, 16, v8
	v_add3_u32 v0, v0, v9, s48
	v_and_or_b32 v0, v0, s97, v8
	global_store_dword v[96:97], v0, off
	v_rsq_f32_e32 v0, v1
	s_nop 0
	v_mul_f32_e32 v1, v85, v0
	v_mul_f32_e32 v9, 0xbfb8aa3b, v1
	v_exp_f32_e32 v9, v9
	v_mul_f32_e32 v8, v93, v0
	v_mad_i64_i32 v[84:85], s[2:3], v155, s8, v[128:129]
	v_add_f32_e32 v9, 1.0, v9
	v_rcp_f32_e32 v9, v9
	s_nop 0
	v_mul_f32_e32 v1, v1, v9
	v_mul_f32_e32 v1, v8, v1
	v_mul_f32_e32 v8, v81, v0
	v_mul_f32_e32 v9, 0xbfb8aa3b, v8
	v_exp_f32_e32 v9, v9
	v_mul_f32_e32 v0, v89, v0
	v_add_f32_e32 v9, 1.0, v9
	v_rcp_f32_e32 v9, v9
	s_nop 0
	v_mul_f32_e32 v8, v8, v9
	v_mul_f32_e32 v0, v0, v8
	v_bfe_u32 v8, v1, 16, 1
	v_add3_u32 v1, v1, v8, s48
	v_bfe_u32 v8, v0, 16, 1
	v_lshrrev_b32_e32 v1, 16, v1
	v_add3_u32 v0, v0, v8, s48
	v_and_or_b32 v8, v0, s97, v1
	v_mad_i64_i32 v[0:1], s[2:3], v158, s8, v[128:129]
	global_store_dword v[0:1], v8, off
	v_rsq_f32_e32 v2, v2
	v_mad_i64_i32 v[0:1], s[2:3], v157, s8, v[128:129]
	v_mul_f32_e32 v8, v86, v2
	v_mul_f32_e32 v10, 0xbfb8aa3b, v8
	v_exp_f32_e32 v10, v10
	v_mul_f32_e32 v9, v94, v2
	v_add_f32_e32 v10, 1.0, v10
	v_rcp_f32_e32 v10, v10
	s_nop 0
	v_mul_f32_e32 v8, v8, v10
	v_mul_f32_e32 v8, v9, v8
	v_mul_f32_e32 v9, v82, v2
	v_mul_f32_e32 v10, 0xbfb8aa3b, v9
	v_exp_f32_e32 v10, v10
	v_mul_f32_e32 v2, v90, v2
	v_add_f32_e32 v10, 1.0, v10
	v_rcp_f32_e32 v10, v10
	s_nop 0
	v_mul_f32_e32 v9, v9, v10
	v_mul_f32_e32 v2, v2, v9
	v_bfe_u32 v9, v8, 16, 1
	v_add3_u32 v8, v8, v9, s48
	v_bfe_u32 v9, v2, 16, 1
	v_lshrrev_b32_e32 v8, 16, v8
	v_add3_u32 v2, v2, v9, s48
	v_and_or_b32 v2, v2, s97, v8
	global_store_dword v[0:1], v2, off
	v_rsq_f32_e32 v0, v3
	s_nop 0
	v_mul_f32_e32 v1, v87, v0
	v_mul_f32_e32 v3, 0xbfb8aa3b, v1
	v_exp_f32_e32 v3, v3
	v_mul_f32_e32 v2, v95, v0
	v_add_f32_e32 v3, 1.0, v3
	v_rcp_f32_e32 v3, v3
	s_nop 0
	v_mul_f32_e32 v1, v1, v3
	v_mul_f32_e32 v1, v2, v1
	v_mul_f32_e32 v2, v83, v0
	global_load_dwordx4 v[80:83], v[132:133], off offset:192
	v_mul_f32_e32 v3, 0xbfb8aa3b, v2
	v_exp_f32_e32 v3, v3
	v_mul_f32_e32 v0, v91, v0
	v_add_f32_e32 v3, 1.0, v3
	v_rcp_f32_e32 v3, v3
	s_nop 0
	v_mul_f32_e32 v2, v2, v3
	v_mul_f32_e32 v0, v0, v2
	v_bfe_u32 v2, v1, 16, 1
	v_add3_u32 v1, v1, v2, s48
	v_bfe_u32 v2, v0, 16, 1
	v_lshrrev_b32_e32 v1, 16, v1
	v_add3_u32 v0, v0, v2, s48
	v_and_or_b32 v2, v0, s97, v1
	v_mad_i64_i32 v[0:1], s[2:3], v156, s8, v[128:129]
	global_store_dword v[0:1], v2, off
	s_waitcnt vmcnt(0)
; __device__ __forceinline__ u32 pack2(float a, float b) { return (u32)f2bf(a) | ((u32)f2bf(b) << 16); }
; __device__ __forceinline__ float sigmoidf_(float x) { return __builtin_amdgcn_rcpf(1.f + __expf(-x)); }
; __device__ __forceinline__ void gemm_tile(const GemmArgs& ga, int wgid, int next_wgid, bool prefetched, u16* shm, unsigned char* ws, int wv_) {
;     ...
;   if (epi == EPI_SWIGLU) {
;     const int oc = pn * HALF + (wc * 16 + fr) * 2;
;     float sc[2][4][4];
;     _Pragma("unroll") for (int ai = 0; ai < 2; ++ai)
;       _Pragma("unroll") for (int m = 0; m < 4; ++m)
;         _Pragma("unroll") for (int j = 0; j < 4; ++j) sc[ai][m][j] = e_ss[rbase + ai * HALF + m * 16 + j];
;     _Pragma("unroll") for (int ai = 0; ai < 2; ++ai)
;       _Pragma("unroll") for (int m = 0; m < 4; ++m)
;         _Pragma("unroll") for (int j = 0; j < 4; ++j) {
;           int row = rbase + ai * HALF + m * 16 + j;
;           float s = rsqrtf(sc[ai][m][j] * (1.f / D_) + 1e-6f);
;           float h2[2];
;           _Pragma("unroll") for (int n = 0; n < 2; ++n) {
;             float a1 = acc[ai][0][m][n][j] * s, a3 = acc[ai][1][m][n][j] * s;
;             h2[n] = a1 * sigmoidf_(a1) * a3;
;           }
;           *(u32*)(e_outb + (size_t)row * F_ + oc) = pack2(h2[0], h2[1]);
;         }
	v_pk_fma_f32 v[0:1], v[80:81], s[12:13], v[130:131] op_sel_hi:[1,0,0]
	s_nop 0
	s_nop 0
	v_rsq_f32_e32 v0, v0
	s_nop 0
	v_mul_f32_e32 v2, v68, v0
	v_mul_f32_e32 v8, 0xbfb8aa3b, v2
	v_exp_f32_e32 v8, v8
	v_mul_f32_e32 v3, v76, v0
	v_add_f32_e32 v8, 1.0, v8
	v_rcp_f32_e32 v8, v8
	s_nop 0
	v_mul_f32_e32 v2, v2, v8
	v_mul_f32_e32 v2, v3, v2
	v_mul_f32_e32 v3, v64, v0
	v_mul_f32_e32 v8, 0xbfb8aa3b, v3
	v_exp_f32_e32 v8, v8
	v_mul_f32_e32 v0, v72, v0
	v_add_f32_e32 v8, 1.0, v8
	v_rcp_f32_e32 v8, v8
	s_nop 0
	v_mul_f32_e32 v3, v3, v8
	v_mul_f32_e32 v0, v0, v3
	v_bfe_u32 v3, v2, 16, 1
	v_add3_u32 v2, v2, v3, s48
	v_bfe_u32 v3, v0, 16, 1
	v_lshrrev_b32_e32 v2, 16, v2
	v_add3_u32 v0, v0, v3, s48
	v_and_or_b32 v0, v0, s97, v2
	global_store_dword v[84:85], v0, off
	v_rsq_f32_e32 v0, v1
	s_nop 0
	v_mul_f32_e32 v1, v69, v0
	v_mul_f32_e32 v3, 0xbfb8aa3b, v1
	v_exp_f32_e32 v3, v3
	v_mul_f32_e32 v2, v77, v0
	v_add_f32_e32 v3, 1.0, v3
	v_rcp_f32_e32 v3, v3
	s_nop 0
	v_mul_f32_e32 v1, v1, v3
	v_mul_f32_e32 v1, v2, v1
	v_mul_f32_e32 v2, v65, v0
	v_mul_f32_e32 v3, 0xbfb8aa3b, v2
	v_exp_f32_e32 v3, v3
	v_mul_f32_e32 v0, v73, v0
	v_mad_i64_i32 v[64:65], s[2:3], v151, s8, v[128:129]
	v_add_f32_e32 v3, 1.0, v3
	v_rcp_f32_e32 v3, v3
	s_nop 0
	v_mul_f32_e32 v2, v2, v3
	v_mul_f32_e32 v0, v0, v2
	v_bfe_u32 v2, v1, 16, 1
	v_add3_u32 v1, v1, v2, s48
	v_bfe_u32 v2, v0, 16, 1
	v_lshrrev_b32_e32 v1, 16, v1
	v_add3_u32 v0, v0, v2, s48
	v_and_or_b32 v2, v0, s97, v1
	v_mad_i64_i32 v[0:1], s[2:3], v154, s8, v[128:129]
	global_store_dword v[0:1], v2, off
	v_pk_fma_f32 v[2:3], v[82:83], s[12:13], v[130:131] op_sel_hi:[1,0,0]
	v_mad_i64_i32 v[0:1], s[2:3], v153, s8, v[128:129]
	s_nop 0
	v_rsq_f32_e32 v2, v2
	s_nop 0
	v_mul_f32_e32 v8, v70, v2
	v_mul_f32_e32 v10, 0xbfb8aa3b, v8
	v_exp_f32_e32 v10, v10
	v_mul_f32_e32 v9, v78, v2
	v_add_f32_e32 v10, 1.0, v10
	v_rcp_f32_e32 v10, v10
	s_nop 0
	v_mul_f32_e32 v8, v8, v10
	v_mul_f32_e32 v8, v9, v8
	v_mul_f32_e32 v9, v66, v2
	v_mul_f32_e32 v10, 0xbfb8aa3b, v9
	v_exp_f32_e32 v10, v10
	v_mul_f32_e32 v2, v74, v2
	v_add_f32_e32 v10, 1.0, v10
	v_rcp_f32_e32 v10, v10
	s_nop 0
	v_mul_f32_e32 v9, v9, v10
	v_mul_f32_e32 v2, v2, v9
	v_bfe_u32 v9, v8, 16, 1
	v_add3_u32 v8, v8, v9, s48
	v_bfe_u32 v9, v2, 16, 1
	v_lshrrev_b32_e32 v8, 16, v8
	v_add3_u32 v2, v2, v9, s48
	v_and_or_b32 v2, v2, s97, v8
	global_store_dword v[0:1], v2, off
	v_rsq_f32_e32 v0, v3
	s_nop 0
	v_mul_f32_e32 v1, v71, v0
	v_mul_f32_e32 v3, 0xbfb8aa3b, v1
	v_exp_f32_e32 v3, v3
	v_mul_f32_e32 v2, v79, v0
	v_add_f32_e32 v3, 1.0, v3
	v_rcp_f32_e32 v3, v3
	s_nop 0
	v_mul_f32_e32 v1, v1, v3
	v_mul_f32_e32 v1, v2, v1
	v_mul_f32_e32 v2, v67, v0
	v_mul_f32_e32 v3, 0xbfb8aa3b, v2
	v_exp_f32_e32 v3, v3
	v_mul_f32_e32 v0, v75, v0
	v_add_f32_e32 v3, 1.0, v3
	v_rcp_f32_e32 v3, v3
	s_nop 0
	v_mul_f32_e32 v2, v2, v3
	v_mul_f32_e32 v0, v0, v2
	v_bfe_u32 v2, v1, 16, 1
	v_add3_u32 v1, v1, v2, s48
	v_bfe_u32 v2, v0, 16, 1
	v_lshrrev_b32_e32 v1, 16, v1
	v_add3_u32 v0, v0, v2, s48
	v_and_or_b32 v2, v0, s97, v1
	v_mad_i64_i32 v[0:1], s[2:3], v152, s8, v[128:129]
	global_store_dword v[0:1], v2, off
	global_load_dwordx4 v[0:3], v[132:133], off offset:512
	s_waitcnt vmcnt(0)
	v_pk_fma_f32 v[0:1], v[0:1], s[12:13], v[130:131] op_sel_hi:[1,0,0]
	s_nop 0
	v_pk_fma_f32 v[2:3], v[2:3], s[12:13], v[130:131] op_sel_hi:[1,0,0]
	v_rsq_f32_e32 v0, v0
	s_nop 0
	v_mul_f32_e32 v8, v52, v0
	v_mul_f32_e32 v10, 0xbfb8aa3b, v8
	v_exp_f32_e32 v10, v10
	v_mul_f32_e32 v9, v60, v0
	v_add_f32_e32 v10, 1.0, v10
	v_rcp_f32_e32 v10, v10
	s_nop 0
	v_mul_f32_e32 v8, v8, v10
	v_mul_f32_e32 v8, v9, v8
	v_mul_f32_e32 v9, v48, v0
	v_mul_f32_e32 v10, 0xbfb8aa3b, v9
	v_exp_f32_e32 v10, v10
	v_mul_f32_e32 v0, v56, v0
	v_add_f32_e32 v10, 1.0, v10
	v_rcp_f32_e32 v10, v10
	s_nop 0
	v_mul_f32_e32 v9, v9, v10
	v_mul_f32_e32 v0, v0, v9
	v_bfe_u32 v9, v8, 16, 1
	v_add3_u32 v8, v8, v9, s48
	v_bfe_u32 v9, v0, 16, 1
	v_lshrrev_b32_e32 v8, 16, v8
	v_add3_u32 v0, v0, v9, s48
	v_and_or_b32 v0, v0, s97, v8
	global_store_dword v[64:65], v0, off
	v_rsq_f32_e32 v0, v1
	s_nop 0
	v_mul_f32_e32 v1, v53, v0
	v_mul_f32_e32 v9, 0xbfb8aa3b, v1
	v_exp_f32_e32 v9, v9
	v_mul_f32_e32 v8, v61, v0
	v_mad_i64_i32 v[52:53], s[2:3], v147, s8, v[128:129]
	v_add_f32_e32 v9, 1.0, v9
	v_rcp_f32_e32 v9, v9
	s_nop 0
	v_mul_f32_e32 v1, v1, v9
	v_mul_f32_e32 v1, v8, v1
	v_mul_f32_e32 v8, v49, v0
	v_mul_f32_e32 v9, 0xbfb8aa3b, v8
	v_exp_f32_e32 v9, v9
	v_mul_f32_e32 v0, v57, v0
	v_add_f32_e32 v9, 1.0, v9
	v_rcp_f32_e32 v9, v9
	s_nop 0
	v_mul_f32_e32 v8, v8, v9
	v_mul_f32_e32 v0, v0, v8
	v_bfe_u32 v8, v1, 16, 1
	v_add3_u32 v1, v1, v8, s48
	v_bfe_u32 v8, v0, 16, 1
	v_lshrrev_b32_e32 v1, 16, v1
	v_add3_u32 v0, v0, v8, s48
	v_and_or_b32 v8, v0, s97, v1
	v_mad_i64_i32 v[0:1], s[2:3], v150, s8, v[128:129]
	global_store_dword v[0:1], v8, off
	v_rsq_f32_e32 v2, v2
	v_mad_i64_i32 v[0:1], s[2:3], v149, s8, v[128:129]
	v_mul_f32_e32 v8, v54, v2
	v_mul_f32_e32 v10, 0xbfb8aa3b, v8
	v_exp_f32_e32 v10, v10
	v_mul_f32_e32 v9, v62, v2
	v_add_f32_e32 v10, 1.0, v10
	v_rcp_f32_e32 v10, v10
	s_nop 0
	v_mul_f32_e32 v8, v8, v10
	v_mul_f32_e32 v8, v9, v8
	v_mul_f32_e32 v9, v50, v2
	v_mul_f32_e32 v10, 0xbfb8aa3b, v9
	v_exp_f32_e32 v10, v10
	v_mul_f32_e32 v2, v58, v2
	v_add_f32_e32 v10, 1.0, v10
	v_rcp_f32_e32 v10, v10
	s_nop 0
	v_mul_f32_e32 v9, v9, v10
	v_mul_f32_e32 v2, v2, v9
	v_bfe_u32 v9, v8, 16, 1
	v_add3_u32 v8, v8, v9, s48
	v_bfe_u32 v9, v2, 16, 1
	v_lshrrev_b32_e32 v8, 16, v8
	v_add3_u32 v2, v2, v9, s48
	v_and_or_b32 v2, v2, s97, v8
	global_store_dword v[0:1], v2, off
	v_rsq_f32_e32 v0, v3
	s_nop 0
	v_mul_f32_e32 v1, v55, v0
	v_mul_f32_e32 v3, 0xbfb8aa3b, v1
	v_exp_f32_e32 v3, v3
	v_mul_f32_e32 v2, v63, v0
	v_add_f32_e32 v3, 1.0, v3
	v_rcp_f32_e32 v3, v3
	s_nop 0
	v_mul_f32_e32 v1, v1, v3
	v_mul_f32_e32 v1, v2, v1
	v_mul_f32_e32 v2, v51, v0
	global_load_dwordx4 v[48:51], v[132:133], off offset:576
	v_mul_f32_e32 v3, 0xbfb8aa3b, v2
	v_exp_f32_e32 v3, v3
	v_mul_f32_e32 v0, v59, v0
	v_add_f32_e32 v3, 1.0, v3
	v_rcp_f32_e32 v3, v3
	s_nop 0
	v_mul_f32_e32 v2, v2, v3
	v_mul_f32_e32 v0, v0, v2
	v_bfe_u32 v2, v1, 16, 1
	v_add3_u32 v1, v1, v2, s48
	v_bfe_u32 v2, v0, 16, 1
	v_lshrrev_b32_e32 v1, 16, v1
	v_add3_u32 v0, v0, v2, s48
	v_and_or_b32 v2, v0, s97, v1
	v_mad_i64_i32 v[0:1], s[2:3], v148, s8, v[128:129]
	global_store_dword v[0:1], v2, off
	s_waitcnt vmcnt(0)
; __device__ __forceinline__ u32 pack2(float a, float b) { return (u32)f2bf(a) | ((u32)f2bf(b) << 16); }
; __device__ __forceinline__ float sigmoidf_(float x) { return __builtin_amdgcn_rcpf(1.f + __expf(-x)); }
; __device__ __forceinline__ void gemm_tile(const GemmArgs& ga, int wgid, int next_wgid, bool prefetched, u16* shm, unsigned char* ws, int wv_) {
;     ...
;   if (epi == EPI_SWIGLU) {
;     const int oc = pn * HALF + (wc * 16 + fr) * 2;
;     float sc[2][4][4];
;     _Pragma("unroll") for (int ai = 0; ai < 2; ++ai)
;       _Pragma("unroll") for (int m = 0; m < 4; ++m)
;         _Pragma("unroll") for (int j = 0; j < 4; ++j) sc[ai][m][j] = e_ss[rbase + ai * HALF + m * 16 + j];
;     _Pragma("unroll") for (int ai = 0; ai < 2; ++ai)
;       _Pragma("unroll") for (int m = 0; m < 4; ++m)
;         _Pragma("unroll") for (int j = 0; j < 4; ++j) {
;           int row = rbase + ai * HALF + m * 16 + j;
;           float s = rsqrtf(sc[ai][m][j] * (1.f / D_) + 1e-6f);
;           float h2[2];
;           _Pragma("unroll") for (int n = 0; n < 2; ++n) {
;             float a1 = acc[ai][0][m][n][j] * s, a3 = acc[ai][1][m][n][j] * s;
;             h2[n] = a1 * sigmoidf_(a1) * a3;
;           }
;           *(u32*)(e_outb + (size_t)row * F_ + oc) = pack2(h2[0], h2[1]);
;         }
	v_pk_fma_f32 v[0:1], v[48:49], s[12:13], v[130:131] op_sel_hi:[1,0,0]
	s_nop 0
	s_nop 0
	v_rsq_f32_e32 v0, v0
	s_nop 0
	v_mul_f32_e32 v2, v36, v0
	v_mul_f32_e32 v8, 0xbfb8aa3b, v2
	v_exp_f32_e32 v8, v8
	v_mul_f32_e32 v3, v44, v0
	v_add_f32_e32 v8, 1.0, v8
	v_rcp_f32_e32 v8, v8
	s_nop 0
	v_mul_f32_e32 v2, v2, v8
	v_mul_f32_e32 v2, v3, v2
	v_mul_f32_e32 v3, v32, v0
	v_mul_f32_e32 v8, 0xbfb8aa3b, v3
	v_exp_f32_e32 v8, v8
	v_mul_f32_e32 v0, v40, v0
	v_add_f32_e32 v8, 1.0, v8
	v_rcp_f32_e32 v8, v8
	s_nop 0
	v_mul_f32_e32 v3, v3, v8
	v_mul_f32_e32 v0, v0, v3
	v_bfe_u32 v3, v2, 16, 1
	v_add3_u32 v2, v2, v3, s48
	v_bfe_u32 v3, v0, 16, 1
	v_lshrrev_b32_e32 v2, 16, v2
	v_add3_u32 v0, v0, v3, s48
	v_and_or_b32 v0, v0, s97, v2
	global_store_dword v[52:53], v0, off
	v_rsq_f32_e32 v0, v1
	s_nop 0
	v_mul_f32_e32 v1, v37, v0
	v_mul_f32_e32 v3, 0xbfb8aa3b, v1
	v_exp_f32_e32 v3, v3
	v_mul_f32_e32 v2, v45, v0
	v_add_f32_e32 v3, 1.0, v3
	v_rcp_f32_e32 v3, v3
	s_nop 0
	v_mul_f32_e32 v1, v1, v3
	v_mul_f32_e32 v1, v2, v1
	v_mul_f32_e32 v2, v33, v0
	v_mul_f32_e32 v3, 0xbfb8aa3b, v2
	v_exp_f32_e32 v3, v3
	v_mul_f32_e32 v0, v41, v0
	v_mad_i64_i32 v[32:33], s[2:3], v143, s8, v[128:129]
	v_add_f32_e32 v3, 1.0, v3
	v_rcp_f32_e32 v3, v3
	s_nop 0
	v_mul_f32_e32 v2, v2, v3
	v_mul_f32_e32 v0, v0, v2
	v_bfe_u32 v2, v1, 16, 1
	v_add3_u32 v1, v1, v2, s48
	v_bfe_u32 v2, v0, 16, 1
	v_lshrrev_b32_e32 v1, 16, v1
	v_add3_u32 v0, v0, v2, s48
	v_and_or_b32 v2, v0, s97, v1
	v_mad_i64_i32 v[0:1], s[2:3], v146, s8, v[128:129]
	global_store_dword v[0:1], v2, off
	v_pk_fma_f32 v[2:3], v[50:51], s[12:13], v[130:131] op_sel_hi:[1,0,0]
	v_mad_i64_i32 v[0:1], s[2:3], v145, s8, v[128:129]
	s_nop 0
	v_rsq_f32_e32 v2, v2
	s_nop 0
	v_mul_f32_e32 v8, v38, v2
	v_mul_f32_e32 v10, 0xbfb8aa3b, v8
	v_exp_f32_e32 v10, v10
	v_mul_f32_e32 v9, v46, v2
	v_add_f32_e32 v10, 1.0, v10
	v_rcp_f32_e32 v10, v10
	s_nop 0
	v_mul_f32_e32 v8, v8, v10
	v_mul_f32_e32 v8, v9, v8
	v_mul_f32_e32 v9, v34, v2
	v_mul_f32_e32 v10, 0xbfb8aa3b, v9
	v_exp_f32_e32 v10, v10
	v_mul_f32_e32 v2, v42, v2
	v_add_f32_e32 v10, 1.0, v10
	v_rcp_f32_e32 v10, v10
	s_nop 0
	v_mul_f32_e32 v9, v9, v10
	v_mul_f32_e32 v2, v2, v9
	v_bfe_u32 v9, v8, 16, 1
	v_add3_u32 v8, v8, v9, s48
	v_bfe_u32 v9, v2, 16, 1
	v_lshrrev_b32_e32 v8, 16, v8
	v_add3_u32 v2, v2, v9, s48
	v_and_or_b32 v2, v2, s97, v8
	global_store_dword v[0:1], v2, off
	v_rsq_f32_e32 v0, v3
	s_nop 0
	v_mul_f32_e32 v1, v39, v0
	v_mul_f32_e32 v3, 0xbfb8aa3b, v1
	v_exp_f32_e32 v3, v3
	v_mul_f32_e32 v2, v47, v0
	v_add_f32_e32 v3, 1.0, v3
	v_rcp_f32_e32 v3, v3
	s_nop 0
	v_mul_f32_e32 v1, v1, v3
	v_mul_f32_e32 v1, v2, v1
	v_mul_f32_e32 v2, v35, v0
	v_mul_f32_e32 v3, 0xbfb8aa3b, v2
	v_exp_f32_e32 v3, v3
	v_mul_f32_e32 v0, v43, v0
	v_add_f32_e32 v3, 1.0, v3
	v_rcp_f32_e32 v3, v3
	s_nop 0
	v_mul_f32_e32 v2, v2, v3
	v_mul_f32_e32 v0, v0, v2
	v_bfe_u32 v2, v1, 16, 1
	v_add3_u32 v1, v1, v2, s48
	v_bfe_u32 v2, v0, 16, 1
	v_lshrrev_b32_e32 v1, 16, v1
	v_add3_u32 v0, v0, v2, s48
	v_and_or_b32 v2, v0, s97, v1
	v_mad_i64_i32 v[0:1], s[2:3], v144, s8, v[128:129]
	global_store_dword v[0:1], v2, off
	global_load_dwordx4 v[0:3], v[132:133], off offset:640
	s_waitcnt vmcnt(0)
; __device__ __forceinline__ u32 pack2(float a, float b) { return (u32)f2bf(a) | ((u32)f2bf(b) << 16); }
; __device__ __forceinline__ float sigmoidf_(float x) { return __builtin_amdgcn_rcpf(1.f + __expf(-x)); }
; __device__ __forceinline__ void gemm_tile(const GemmArgs& ga, int wgid, int next_wgid, bool prefetched, u16* shm, unsigned char* ws, int wv_) {
;     ...
;   if (epi == EPI_SWIGLU) {
;     const int oc = pn * HALF + (wc * 16 + fr) * 2;
;     float sc[2][4][4];
;     _Pragma("unroll") for (int ai = 0; ai < 2; ++ai)
;       _Pragma("unroll") for (int m = 0; m < 4; ++m)
;         _Pragma("unroll") for (int j = 0; j < 4; ++j) sc[ai][m][j] = e_ss[rbase + ai * HALF + m * 16 + j];
;     _Pragma("unroll") for (int ai = 0; ai < 2; ++ai)
;       _Pragma("unroll") for (int m = 0; m < 4; ++m)
;         _Pragma("unroll") for (int j = 0; j < 4; ++j) {
;           int row = rbase + ai * HALF + m * 16 + j;
;           float s = rsqrtf(sc[ai][m][j] * (1.f / D_) + 1e-6f);
;           float h2[2];
;           _Pragma("unroll") for (int n = 0; n < 2; ++n) {
;             float a1 = acc[ai][0][m][n][j] * s, a3 = acc[ai][1][m][n][j] * s;
;             h2[n] = a1 * sigmoidf_(a1) * a3;
;           }
;           *(u32*)(e_outb + (size_t)row * F_ + oc) = pack2(h2[0], h2[1]);
;         }
	v_pk_fma_f32 v[0:1], v[0:1], s[12:13], v[130:131] op_sel_hi:[1,0,0]
	s_nop 0
	v_pk_fma_f32 v[2:3], v[2:3], s[12:13], v[130:131] op_sel_hi:[1,0,0]
	v_rsq_f32_e32 v0, v0
	s_nop 0
	v_mul_f32_e32 v8, v20, v0
	v_mul_f32_e32 v10, 0xbfb8aa3b, v8
	v_exp_f32_e32 v10, v10
	v_mul_f32_e32 v9, v244, v0
	v_add_f32_e32 v10, 1.0, v10
	v_rcp_f32_e32 v10, v10
	s_nop 0
	v_mul_f32_e32 v8, v8, v10
	v_mul_f32_e32 v8, v9, v8
	v_mul_f32_e32 v9, v240, v0
	v_mul_f32_e32 v10, 0xbfb8aa3b, v9
	v_exp_f32_e32 v10, v10
	v_mul_f32_e32 v0, v24, v0
	v_add_f32_e32 v10, 1.0, v10
	v_rcp_f32_e32 v10, v10
	s_nop 0
	v_mul_f32_e32 v9, v9, v10
	v_mul_f32_e32 v0, v0, v9
	v_bfe_u32 v9, v8, 16, 1
	v_add3_u32 v8, v8, v9, s48
	v_bfe_u32 v9, v0, 16, 1
	v_lshrrev_b32_e32 v8, 16, v8
	v_add3_u32 v0, v0, v9, s48
	v_and_or_b32 v0, v0, s97, v8
	global_store_dword v[32:33], v0, off
	v_rsq_f32_e32 v0, v1
	s_nop 0
	v_mul_f32_e32 v1, v21, v0
	v_mul_f32_e32 v9, 0xbfb8aa3b, v1
	v_exp_f32_e32 v9, v9
	v_mul_f32_e32 v8, v245, v0
	v_mad_i64_i32 v[20:21], s[2:3], v139, s8, v[128:129]
	v_add_f32_e32 v9, 1.0, v9
	v_rcp_f32_e32 v9, v9
	s_nop 0
	v_mul_f32_e32 v1, v1, v9
	v_mul_f32_e32 v1, v8, v1
	v_mul_f32_e32 v8, v241, v0
	v_mul_f32_e32 v9, 0xbfb8aa3b, v8
	v_exp_f32_e32 v9, v9
	v_mul_f32_e32 v0, v25, v0
	v_add_f32_e32 v9, 1.0, v9
	v_rcp_f32_e32 v9, v9
	s_nop 0
	v_mul_f32_e32 v8, v8, v9
	v_mul_f32_e32 v0, v0, v8
	v_bfe_u32 v8, v1, 16, 1
	v_add3_u32 v1, v1, v8, s48
	v_bfe_u32 v8, v0, 16, 1
	v_lshrrev_b32_e32 v1, 16, v1
	v_add3_u32 v0, v0, v8, s48
	v_and_or_b32 v8, v0, s97, v1
	v_mad_i64_i32 v[0:1], s[2:3], v142, s8, v[128:129]
	global_store_dword v[0:1], v8, off
	v_rsq_f32_e32 v2, v2
	v_mad_i64_i32 v[0:1], s[2:3], v141, s8, v[128:129]
	v_mul_f32_e32 v8, v22, v2
	v_mul_f32_e32 v10, 0xbfb8aa3b, v8
	v_exp_f32_e32 v10, v10
	v_mul_f32_e32 v9, v246, v2
	v_add_f32_e32 v10, 1.0, v10
	v_rcp_f32_e32 v10, v10
	s_nop 0
	v_mul_f32_e32 v8, v8, v10
	v_mul_f32_e32 v8, v9, v8
	v_mul_f32_e32 v9, v242, v2
	v_mul_f32_e32 v10, 0xbfb8aa3b, v9
	v_exp_f32_e32 v10, v10
	v_mul_f32_e32 v2, v26, v2
	v_add_f32_e32 v10, 1.0, v10
	v_rcp_f32_e32 v10, v10
	s_nop 0
	v_mul_f32_e32 v9, v9, v10
	v_mul_f32_e32 v2, v2, v9
	v_bfe_u32 v9, v8, 16, 1
	v_add3_u32 v8, v8, v9, s48
	v_bfe_u32 v9, v2, 16, 1
	v_lshrrev_b32_e32 v8, 16, v8
	v_add3_u32 v2, v2, v9, s48
	v_and_or_b32 v2, v2, s97, v8
	global_store_dword v[0:1], v2, off
	v_rsq_f32_e32 v0, v3
	s_nop 0
	v_mul_f32_e32 v1, v23, v0
	v_mul_f32_e32 v3, 0xbfb8aa3b, v1
	v_exp_f32_e32 v3, v3
	v_mul_f32_e32 v2, v247, v0
	v_add_f32_e32 v3, 1.0, v3
	v_rcp_f32_e32 v3, v3
	s_nop 0
	v_mul_f32_e32 v1, v1, v3
	v_mul_f32_e32 v1, v2, v1
	v_mul_f32_e32 v2, v243, v0
	v_mul_f32_e32 v3, 0xbfb8aa3b, v2
	v_exp_f32_e32 v3, v3
	v_mul_f32_e32 v0, v27, v0
	v_add_f32_e32 v3, 1.0, v3
	v_rcp_f32_e32 v3, v3
	s_nop 0
	v_mul_f32_e32 v2, v2, v3
	v_mul_f32_e32 v0, v0, v2
	v_bfe_u32 v2, v1, 16, 1
	v_add3_u32 v1, v1, v2, s48
	v_bfe_u32 v2, v0, 16, 1
	v_lshrrev_b32_e32 v1, 16, v1
	v_add3_u32 v0, v0, v2, s48
	v_and_or_b32 v2, v0, s97, v1
	v_mad_i64_i32 v[0:1], s[2:3], v140, s8, v[128:129]
	global_store_dword v[0:1], v2, off
	v_pk_fma_f32 v[0:1], v[16:17], s[12:13], v[130:131] op_sel_hi:[1,0,0]
	s_nop 0
	s_nop 0
	v_rsq_f32_e32 v0, v0
	s_nop 0
	v_mul_f32_e32 v2, v204, v0
	v_mul_f32_e32 v8, 0xbfb8aa3b, v2
	v_exp_f32_e32 v8, v8
	v_mul_f32_e32 v3, v12, v0
	v_add_f32_e32 v8, 1.0, v8
	v_rcp_f32_e32 v8, v8
	s_nop 0
	v_mul_f32_e32 v2, v2, v8
	v_mul_f32_e32 v2, v3, v2
	v_mul_f32_e32 v3, v182, v0
	v_mul_f32_e32 v0, v4, v0
	v_mul_f32_e32 v4, 0xbfb8aa3b, v3
	v_exp_f32_e32 v4, v4
	s_nop 0
	v_add_f32_e32 v4, 1.0, v4
	v_rcp_f32_e32 v4, v4
	s_nop 0
	v_mul_f32_e32 v3, v3, v4
	v_mul_f32_e32 v0, v0, v3
	v_bfe_u32 v3, v2, 16, 1
	v_add3_u32 v2, v2, v3, s48
	v_bfe_u32 v3, v0, 16, 1
	v_lshrrev_b32_e32 v2, 16, v2
	v_add3_u32 v0, v0, v3, s48
	v_and_or_b32 v0, v0, s97, v2
	global_store_dword v[20:21], v0, off
	v_rsq_f32_e32 v0, v1
	s_nop 0
	v_mul_f32_e32 v1, v205, v0
	v_mul_f32_e32 v3, 0xbfb8aa3b, v1
	v_exp_f32_e32 v3, v3
	v_mul_f32_e32 v2, v13, v0
	v_add_f32_e32 v3, 1.0, v3
	v_rcp_f32_e32 v3, v3
	s_nop 0
	v_mul_f32_e32 v1, v1, v3
	v_mul_f32_e32 v1, v2, v1
	v_mul_f32_e32 v2, v183, v0
	v_mul_f32_e32 v3, 0xbfb8aa3b, v2
	v_exp_f32_e32 v3, v3
	v_mul_f32_e32 v0, v5, v0
	v_add_f32_e32 v3, 1.0, v3
	v_rcp_f32_e32 v3, v3
	s_nop 0
	v_mul_f32_e32 v2, v2, v3
	v_mul_f32_e32 v0, v0, v2
	v_bfe_u32 v2, v1, 16, 1
	v_add3_u32 v1, v1, v2, s48
	v_bfe_u32 v2, v0, 16, 1
	v_lshrrev_b32_e32 v1, 16, v1
	v_add3_u32 v0, v0, v2, s48
	v_and_or_b32 v2, v0, s97, v1
	v_mad_i64_i32 v[0:1], s[2:3], v138, s8, v[128:129]
	global_store_dword v[0:1], v2, off
	v_pk_fma_f32 v[2:3], v[18:19], s[12:13], v[130:131] op_sel_hi:[1,0,0]
	v_mad_i64_i32 v[0:1], s[2:3], v137, s8, v[128:129]
	s_nop 0
	v_rsq_f32_e32 v2, v2
	s_nop 0
	v_mul_f32_e32 v4, v206, v2
	v_mul_f32_e32 v8, 0xbfb8aa3b, v4
	v_exp_f32_e32 v8, v8
	v_mul_f32_e32 v5, v14, v2
	v_add_f32_e32 v8, 1.0, v8
	v_rcp_f32_e32 v8, v8
	s_nop 0
	v_mul_f32_e32 v4, v4, v8
	v_mul_f32_e32 v4, v5, v4
	v_mul_f32_e32 v5, v184, v2
	v_mul_f32_e32 v2, v6, v2
	v_mul_f32_e32 v6, 0xbfb8aa3b, v5
	v_exp_f32_e32 v6, v6
	s_nop 0
	v_add_f32_e32 v6, 1.0, v6
	v_rcp_f32_e32 v6, v6
	s_nop 0
	v_mul_f32_e32 v5, v5, v6
	v_mul_f32_e32 v2, v2, v5
	v_bfe_u32 v5, v4, 16, 1
	v_add3_u32 v4, v4, v5, s48
	v_bfe_u32 v5, v2, 16, 1
	v_lshrrev_b32_e32 v4, 16, v4
	v_add3_u32 v2, v2, v5, s48
	v_and_or_b32 v2, v2, s97, v4
	global_store_dword v[0:1], v2, off
	v_rsq_f32_e32 v0, v3
	s_nop 0
	v_mul_f32_e32 v1, v207, v0
	v_mul_f32_e32 v3, 0xbfb8aa3b, v1
	v_exp_f32_e32 v3, v3
	v_mul_f32_e32 v2, v15, v0
	v_add_f32_e32 v3, 1.0, v3
	v_rcp_f32_e32 v3, v3
	s_nop 0
	v_mul_f32_e32 v1, v1, v3
	v_mul_f32_e32 v1, v2, v1
	v_mul_f32_e32 v2, v185, v0
	v_mul_f32_e32 v3, 0xbfb8aa3b, v2
	v_exp_f32_e32 v3, v3
	v_mul_f32_e32 v0, v7, v0
	v_add_f32_e32 v3, 1.0, v3
	v_rcp_f32_e32 v3, v3
	s_nop 0
	v_mul_f32_e32 v2, v2, v3
	v_mul_f32_e32 v0, v0, v2
	v_bfe_u32 v2, v1, 16, 1
	v_add3_u32 v1, v1, v2, s48
	v_bfe_u32 v2, v0, 16, 1
	v_lshrrev_b32_e32 v1, 16, v1
	v_add3_u32 v0, v0, v2, s48
	v_and_or_b32 v2, v0, s97, v1
	v_mad_i64_i32 v[0:1], s[2:3], v136, s8, v[128:129]
	global_store_dword v[0:1], v2, off
	s_branch .LBB0_501
